# rec_in and att_in phases rewritten by hand on the pipelined GEMM core: rope applied in row-per-lane registers with pipelined table loads, LDS-staged full-line nt stores
# speedup vs baseline: 1.1057x; 1.0244x over previous
; DI f32x16 zero16() { f32x16 z; for (int i = 0; i < 16; ++i) z[i] = 0.f; return z; }
; DI int opqv(int x) { asm volatile("" : "+v"(x)); return x; }
; DI char* opq(char* p) { asm volatile("" : "+s"(p)); return p; }
; #define RAWBAR() { asm volatile("s_waitcnt vmcnt(0) lgkmcnt(0)" ::: "memory"); __builtin_amdgcn_s_barrier(); }
;   const int tid = opqv(threadIdx.x), lane = tid & 63, w = tid >> 6, wm = w >> 2, wn = w & 3, l32 = lane & 31, hf = lane >> 5;
;   f32x16 acc[2][2][2];
; #pragma unroll
;   for (int h = 0; h < 2; ++h)
; #pragma unroll
;     for (int i = 0; i < 2; ++i)
; #pragma unroll
;       for (int j = 0; j < 2; ++j) acc[h][i][j] = zero16();
;   const int nk = nk1 + nk2;
;   const int drow = lane >> 3, dslot = lane & 7, x7 = (l32 >> 1) & 7;
;     ...
;   if (V != 1) GLDS(0, 0);
;   RAWBAR();
; DI void att_in_phase(const Params& p, int j, char* smem) {
;   const int tid = opqv(threadIdx.x), lane = tid & 63, w = tid >> 6, wm = w >> 2, wn = w & 3, l32 = lane & 31, hf = lane >> 5;
;   char* ws = opq(p.ws);
;   const u16* A = (const u16*)(ws + OFF_HY);
;   const u16* Wt = (const u16*)(ws + OFF_W_ATTIN) + (size_t)j * 1536 * LDW1;
;   u16* zc = (u16*)(ws + OFF_ZC); u16* SQ = (u16*)(ws + OFF_SQ); u16* SK = (u16*)(ws + OFF_SK); u16* SV = (u16*)(ws + OFF_SV);
;   u16* Kb = (u16*)(ws + OFF_KB);
;   const float2* rt64 = (const float2*)(ws + OFF_RT64); const float2* rt32 = (const float2*)(ws + OFF_RT32);
;   const int nN = 6;
;   for (int lt = blockIdx.x >> 3; lt < 16 * nN; lt += gridDim.x >> 3) {
;     int mt, nt; tile_map(lt, 16, nN, 16, 2, mt, nt);
;     const int m0 = mt * 256, n0 = nt * 256;
;     gemm_tile(A + (size_t)m0 * LDH, LDH, 16, nullptr, 0, 0, Wt + (size_t)n0 * LDW1, LDW1, smem, [&](f32x16(&acc)[2][2], int moff) {
.LBB0_649:
	v_readlane_b32 s4, v251, 54
	v_readlane_b32 s0, v251, 13
	v_readlane_b32 s5, v251, 55
	v_mov_b32_e32 v0, v182
	v_readlane_b32 s1, v251, 14
	s_andn2_b64 vcc, exec, s[4:5]
	s_cbranch_vccnz .LBB0_709
	s_mov_b64 s[70:71], s[62:63]
	v_readlane_b32 s28, v253, 48
	v_readlane_b32 s30, v253, 50
	s_cmp_ge_u32 s28, 0x60
	s_cbranch_scc1 .LBB0_708
	s_add_u32 s4, s0, 0x8c04100
	s_addc_u32 s5, s1, 0
	v_readlane_b32 s6, v254, 25
	v_readlane_b32 s31, v251, 0
	s_mul_i32 s6, s6, 0x330000
	s_add_u32 s6, s0, s6
	s_addc_u32 s7, s1, 0
	s_add_u32 s6, s6, 0x10c4100
	s_addc_u32 s7, s7, 0
	s_and_b32 s31, s31, 7
	s_lshl_b32 s31, s31, 4
	s_lshr_b32 s8, s28, 1
	s_add_u32 s31, s31, s8
	s_mul_i32 s8, s31, 0x88000
	s_add_u32 s34, s4, s8
	s_addc_u32 s35, s5, 0
	v_lshrrev_b32_e32 v228, 6, v182
	v_and_b32_e32 v229, 63, v182
	v_readfirstlane_b32 s15, v228
	v_and_b32_e32 v230, 31, v229
	v_lshrrev_b32_e32 v231, 5, v229
	v_lshrrev_b32_e32 v232, 3, v229
	v_and_b32_e32 v233, 7, v229
	s_lshl_b32 s14, s15, 12
	s_add_u32 s14, s14, 32
	v_lshrrev_b32_e32 v234, 1, v232
	v_xor_b32_e32 v234, v233, v234
	v_lshlrev_b32_e32 v234, 4, v234
	s_lshl_b32 s8, s15, 2
	s_add_u32 s8, s8, 0
	s_lshl_b32 s8, s8, 3
	v_add_u32_e32 v235, s8, v232
	s_movk_i32 s9, 0x880
	v_mad_u32_u24 v220, v235, s9, v234
	v_lshrrev_b32_e32 v234, 1, v232
	v_add_u32_e32 v234, 4, v234
	v_xor_b32_e32 v234, v233, v234
	v_lshlrev_b32_e32 v234, 4, v234
	s_lshl_b32 s8, s15, 2
	s_add_u32 s8, s8, 1
	s_lshl_b32 s8, s8, 3
	v_add_u32_e32 v235, s8, v232
	s_movk_i32 s9, 0x880
	v_mad_u32_u24 v221, v235, s9, v234
	v_lshrrev_b32_e32 v234, 1, v232
	v_xor_b32_e32 v234, v233, v234
	v_lshlrev_b32_e32 v234, 4, v234
	s_lshl_b32 s8, s15, 2
	s_add_u32 s8, s8, 2
	s_lshl_b32 s8, s8, 3
	v_add_u32_e32 v235, s8, v232
	s_movk_i32 s9, 0x880
	v_mad_u32_u24 v222, v235, s9, v234
	v_lshrrev_b32_e32 v234, 1, v232
	v_add_u32_e32 v234, 4, v234
	v_xor_b32_e32 v234, v233, v234
	v_lshlrev_b32_e32 v234, 4, v234
	s_lshl_b32 s8, s15, 2
	s_add_u32 s8, s8, 3
	s_lshl_b32 s8, s8, 3
	v_add_u32_e32 v235, s8, v232
	s_movk_i32 s9, 0x880
	v_mad_u32_u24 v223, v235, s9, v234
	v_lshrrev_b32_e32 v236, 1, v230
	v_and_b32_e32 v236, 7, v236
	s_lshr_b32 s8, s15, 2
	s_and_b32 s9, s15, 3
	s_lshl_b32 s10, s8, 14
	s_add_u32 s10, s10, 32
	s_lshl_b32 s11, s9, 13
	s_add_u32 s11, s11, 0x8020
	v_lshlrev_b32_e32 v237, 7, v230
	v_add_u32_e32 v238, s11, v237
	v_add_u32_e32 v237, s10, v237
	v_add_u32_e32 v239, 0, v231
	v_xor_b32_e32 v239, v239, v236
	v_lshlrev_b32_e32 v239, 4, v239
	v_add_u32_e32 v204, v237, v239
	v_add_u32_e32 v212, v238, v239
	v_add_u32_e32 v208, 0x10000, v204
	v_add_u32_e32 v216, 0x10000, v212
	v_add_u32_e32 v239, 2, v231
	v_xor_b32_e32 v239, v239, v236
	v_lshlrev_b32_e32 v239, 4, v239
	v_add_u32_e32 v205, v237, v239
	v_add_u32_e32 v213, v238, v239
	v_add_u32_e32 v209, 0x10000, v205
	v_add_u32_e32 v217, 0x10000, v213
	v_add_u32_e32 v239, 4, v231
	v_xor_b32_e32 v239, v239, v236
	v_lshlrev_b32_e32 v239, 4, v239
	v_add_u32_e32 v206, v237, v239
	v_add_u32_e32 v214, v238, v239
	v_add_u32_e32 v210, 0x10000, v206
	v_add_u32_e32 v218, 0x10000, v214
	v_add_u32_e32 v239, 6, v231
	v_xor_b32_e32 v239, v239, v236
	v_lshlrev_b32_e32 v239, 4, v239
	v_add_u32_e32 v207, v237, v239
	v_add_u32_e32 v215, v238, v239
	v_add_u32_e32 v211, 0x10000, v207
	v_add_u32_e32 v219, 0x10000, v215
	s_add_u32 s10, s14, 0x18000
	v_lshlrev_b32_e32 v234, 7, v230
	v_lshlrev_b32_e32 v235, 3, v231
	v_add3_u32 v234, v234, v235, s10
	v_and_b32_e32 v235, 7, v230
	v_mov_b32_e32 v178, v235
	v_xor_b32_e32 v179, 1, v235
	v_xor_b32_e32 v180, 2, v235
	v_xor_b32_e32 v181, 3, v235
	v_xor_b32_e32 v188, 4, v235
	v_xor_b32_e32 v189, 5, v235
	v_xor_b32_e32 v190, 6, v235
	v_xor_b32_e32 v191, 7, v235
	v_lshl_add_u32 v178, v178, 4, v234
	v_lshl_add_u32 v179, v179, 4, v234
	v_lshl_add_u32 v180, v180, 4, v234
	v_lshl_add_u32 v181, v181, 4, v234
	v_lshl_add_u32 v188, v188, 4, v234
	v_lshl_add_u32 v189, v189, 4, v234
	v_lshl_add_u32 v190, v190, 4, v234
	v_lshl_add_u32 v191, v191, 4, v234
	v_xor_b32_e32 v194, v232, v233
	v_lshlrev_b32_e32 v194, 4, v194
	v_lshl_add_u32 v194, v232, 7, v194
	v_add_u32_e32 v194, s10, v194
	s_lshl_b32 s12, s8, 7
	s_mov_b32 s13, s9
	v_lshlrev_b32_e32 v195, 4, v233
	s_movk_i32 s10, 0x500
	v_mad_u32_u24 v195, v232, s10, v195
	v_lshlrev_b32_e32 v196, 4, v233
	s_movk_i32 s10, 0x400
	v_mad_u32_u24 v196, v232, s10, v196
	v_lshlrev_b32_e32 v197, 4, v233
	s_movk_i32 s10, 0x100
	v_mad_u32_u24 v197, v232, s10, v197
	v_lshlrev_b32_e32 v160, 8, v230
	v_lshl_add_u32 v160, v231, 5, v160
	s_lshl_b32 s10, s31, 8
	s_add_u32 s10, s10, s12
	s_mov_b32 s52, s10
	s_and_b32 s10, s10, 0x3fff
	s_mov_b32 s53, s10
	s_lshl_b32 s10, s10, 8
	s_add_u32 s36, s0, s10
	s_addc_u32 s37, s1, 0
	s_add_u32 s36, s36, 0x234100
	s_addc_u32 s37, s37, 0
	s_mov_b32 s27, s28
	s_mov_b32 s26, 0
	s_lshr_b32 s8, s27, 5
	s_lshl_b32 s8, s8, 1
	s_and_b32 s9, s27, 1
	s_add_u32 s8, s8, s9
	s_mul_i32 s8, s8, 0x88000
	s_add_u32 s24, s6, s8
	s_addc_u32 s25, s7, 0
	s_mov_b64 s[22:23], s[34:35]
	s_add_u32 m0, s14, 0x0
	s_nop 0
	global_load_lds_dwordx4 v220, s[22:23]
	s_add_u32 m0, s14, 0x8000
	s_nop 0
	global_load_lds_dwordx4 v220, s[24:25]
	s_add_u32 m0, s14, 0x400
	s_nop 0
	global_load_lds_dwordx4 v221, s[22:23]
	s_add_u32 m0, s14, 0x8400
	s_nop 0
	global_load_lds_dwordx4 v221, s[24:25]
	s_add_u32 m0, s14, 0x800
	s_nop 0
	global_load_lds_dwordx4 v222, s[22:23]
	s_add_u32 m0, s14, 0x8800
	s_nop 0
	global_load_lds_dwordx4 v222, s[24:25]
	s_add_u32 m0, s14, 0xc00
	s_nop 0
	global_load_lds_dwordx4 v223, s[22:23]
	s_add_u32 m0, s14, 0x8c00
	s_nop 0
	global_load_lds_dwordx4 v223, s[24:25]
	s_add_u32 s22, s22, 0x80
	s_addc_u32 s23, s23, 0
	s_add_u32 s24, s24, 0x80
	s_addc_u32 s25, s25, 0
	s_add_u32 s26, s26, 1
	s_cmp_eq_u32 s26, 16
	s_cbranch_scc0 .Lai1_cadv_done
	s_mov_b32 s26, 0
	s_add_u32 s27, s27, s30
	s_cmp_lt_u32 s27, 0x60
	s_cbranch_scc1 .Lai1_cadv_new
	s_sub_u32 s22, s22, 0x800
	s_subb_u32 s23, s23, 0
	s_sub_u32 s24, s24, 0x800
	s_subb_u32 s25, s25, 0
	s_branch .Lai1_cadv_done
.Lai1_cadv_new:
	s_lshr_b32 s8, s27, 5
	s_lshl_b32 s8, s8, 1
	s_and_b32 s9, s27, 1
	s_add_u32 s8, s8, s9
	s_mul_i32 s8, s8, 0x88000
	s_add_u32 s24, s6, s8
	s_addc_u32 s25, s7, 0
	s_mov_b64 s[22:23], s[34:35]
.Lai1_cadv_done:
	s_add_u32 m0, s14, 0x10000
	s_nop 0
	global_load_lds_dwordx4 v220, s[22:23]
	s_add_u32 m0, s14, 0x18000
	s_nop 0
	global_load_lds_dwordx4 v220, s[24:25]
	s_add_u32 m0, s14, 0x10400
	s_nop 0
	global_load_lds_dwordx4 v221, s[22:23]
	s_add_u32 m0, s14, 0x18400
	s_nop 0
	global_load_lds_dwordx4 v221, s[24:25]
	s_add_u32 m0, s14, 0x10800
	s_nop 0
	global_load_lds_dwordx4 v222, s[22:23]
	s_add_u32 m0, s14, 0x18800
	s_nop 0
	global_load_lds_dwordx4 v222, s[24:25]
	s_add_u32 m0, s14, 0x10c00
	s_nop 0
	global_load_lds_dwordx4 v223, s[22:23]
	s_add_u32 m0, s14, 0x18c00
	s_nop 0
	global_load_lds_dwordx4 v223, s[24:25]
	s_add_u32 s22, s22, 0x80
	s_addc_u32 s23, s23, 0
	s_add_u32 s24, s24, 0x80
	s_addc_u32 s25, s25, 0
	s_add_u32 s26, s26, 1
	s_cmp_eq_u32 s26, 16
	s_cbranch_scc0 .Lai2_cadv_done
	s_mov_b32 s26, 0
	s_add_u32 s27, s27, s30
	s_cmp_lt_u32 s27, 0x60
	s_cbranch_scc1 .Lai2_cadv_new
	s_sub_u32 s22, s22, 0x800
	s_subb_u32 s23, s23, 0
	s_sub_u32 s24, s24, 0x800
	s_subb_u32 s25, s25, 0
	s_branch .Lai2_cadv_done

; #define RAWBAR() { asm volatile("s_waitcnt vmcnt(0) lgkmcnt(0)" ::: "memory"); __builtin_amdgcn_s_barrier(); }
;     ...
;   if (V != 1) GLDS(0, 0);
;   RAWBAR();
;   for (int kt = 0; kt < nk; kt += 2) {
;     if (V != 1) GLDS(kt + 1, 1);
;     if (V != 2) COMPUTE(0);
;     RAWBAR();
.Lai_tile:
	s_waitcnt lgkmcnt(6)
	v_mfma_f32_32x32x16_bf16 v[0:15], v[162:165], v[128:131], 0
	v_mfma_f32_32x32x16_bf16 v[16:31], v[166:169], v[128:131], 0
	ds_read_b128 v[128:131], v206
	v_mfma_f32_32x32x16_bf16 v[32:47], v[162:165], v[132:135], 0
	v_mfma_f32_32x32x16_bf16 v[48:63], v[166:169], v[132:135], 0
	ds_read_b128 v[132:135], v206 offset:4096
	v_mfma_f32_32x32x16_bf16 v[64:79], v[162:165], v[136:139], 0
	v_mfma_f32_32x32x16_bf16 v[80:95], v[166:169], v[136:139], 0
	ds_read_b128 v[136:139], v206 offset:8192
	v_mfma_f32_32x32x16_bf16 v[96:111], v[162:165], v[140:143], 0
	v_mfma_f32_32x32x16_bf16 v[112:127], v[166:169], v[140:143], 0
	ds_read_b128 v[140:143], v206 offset:12288
	ds_read_b128 v[162:165], v214
	ds_read_b128 v[166:169], v214 offset:4096
	s_waitcnt lgkmcnt(6)
	v_mfma_f32_32x32x16_bf16 v[0:15], v[170:173], v[144:147], v[0:15]
	v_mfma_f32_32x32x16_bf16 v[16:31], v[174:177], v[144:147], v[16:31]
	ds_read_b128 v[144:147], v207
	v_mfma_f32_32x32x16_bf16 v[32:47], v[170:173], v[148:151], v[32:47]
	v_mfma_f32_32x32x16_bf16 v[48:63], v[174:177], v[148:151], v[48:63]
	ds_read_b128 v[148:151], v207 offset:4096
	v_mfma_f32_32x32x16_bf16 v[64:79], v[170:173], v[152:155], v[64:79]
	v_mfma_f32_32x32x16_bf16 v[80:95], v[174:177], v[152:155], v[80:95]
	ds_read_b128 v[152:155], v207 offset:8192
	v_mfma_f32_32x32x16_bf16 v[96:111], v[170:173], v[156:159], v[96:111]
	v_mfma_f32_32x32x16_bf16 v[112:127], v[174:177], v[156:159], v[112:127]
	ds_read_b128 v[156:159], v207 offset:12288
	ds_read_b128 v[170:173], v215
	ds_read_b128 v[174:177], v215 offset:4096
	s_waitcnt vmcnt(0) lgkmcnt(0)
	s_barrier
	s_add_u32 m0, s14, 0x0
	v_mfma_f32_32x32x16_bf16 v[0:15], v[162:165], v[128:131], v[0:15]
	global_load_lds_dwordx4 v220, s[22:23]
	s_add_u32 m0, s14, 0x8000
	v_mfma_f32_32x32x16_bf16 v[16:31], v[166:169], v[128:131], v[16:31]
	global_load_lds_dwordx4 v220, s[24:25]
	ds_read_b128 v[128:131], v208
	s_add_u32 m0, s14, 0x400
	v_mfma_f32_32x32x16_bf16 v[32:47], v[162:165], v[132:135], v[32:47]
	global_load_lds_dwordx4 v221, s[22:23]
	s_add_u32 m0, s14, 0x8400
	v_mfma_f32_32x32x16_bf16 v[48:63], v[166:169], v[132:135], v[48:63]
	global_load_lds_dwordx4 v221, s[24:25]
	ds_read_b128 v[132:135], v208 offset:4096
	s_add_u32 m0, s14, 0x800
	v_mfma_f32_32x32x16_bf16 v[64:79], v[162:165], v[136:139], v[64:79]
	global_load_lds_dwordx4 v222, s[22:23]
	s_add_u32 m0, s14, 0x8800
	v_mfma_f32_32x32x16_bf16 v[80:95], v[166:169], v[136:139], v[80:95]
	global_load_lds_dwordx4 v222, s[24:25]
	ds_read_b128 v[136:139], v208 offset:8192
	s_add_u32 m0, s14, 0xc00
	v_mfma_f32_32x32x16_bf16 v[96:111], v[162:165], v[140:143], v[96:111]
	global_load_lds_dwordx4 v223, s[22:23]
	s_add_u32 m0, s14, 0x8c00
	v_mfma_f32_32x32x16_bf16 v[112:127], v[166:169], v[140:143], v[112:127]
	global_load_lds_dwordx4 v223, s[24:25]
	ds_read_b128 v[140:143], v208 offset:12288
	ds_read_b128 v[162:165], v216
	ds_read_b128 v[166:169], v216 offset:4096
	v_mfma_f32_32x32x16_bf16 v[0:15], v[170:173], v[144:147], v[0:15]
	v_mfma_f32_32x32x16_bf16 v[16:31], v[174:177], v[144:147], v[16:31]
	ds_read_b128 v[144:147], v209
	v_mfma_f32_32x32x16_bf16 v[32:47], v[170:173], v[148:151], v[32:47]
	v_mfma_f32_32x32x16_bf16 v[48:63], v[174:177], v[148:151], v[48:63]
	ds_read_b128 v[148:151], v209 offset:4096
	v_mfma_f32_32x32x16_bf16 v[64:79], v[170:173], v[152:155], v[64:79]
	v_mfma_f32_32x32x16_bf16 v[80:95], v[174:177], v[152:155], v[80:95]
	ds_read_b128 v[152:155], v209 offset:8192
	v_mfma_f32_32x32x16_bf16 v[96:111], v[170:173], v[156:159], v[96:111]
	v_mfma_f32_32x32x16_bf16 v[112:127], v[174:177], v[156:159], v[112:127]
	ds_read_b128 v[156:159], v209 offset:12288
	ds_read_b128 v[170:173], v217
	ds_read_b128 v[174:177], v217 offset:4096
	s_add_u32 s22, s22, 0x80
	s_addc_u32 s23, s23, 0
	s_add_u32 s24, s24, 0x80
	s_addc_u32 s25, s25, 0
	s_add_u32 s26, s26, 1
	s_cmp_eq_u32 s26, 16
	s_cbranch_scc0 .Lai3_cadv_done
	s_mov_b32 s26, 0
	s_add_u32 s27, s27, s30
	s_cmp_lt_u32 s27, 0x60
	s_cbranch_scc1 .Lai3_cadv_new
	s_sub_u32 s22, s22, 0x800
	s_subb_u32 s23, s23, 0
	s_sub_u32 s24, s24, 0x800
	s_subb_u32 s25, s25, 0
	s_branch .Lai3_cadv_done

; #define RAWBAR() { asm volatile("s_waitcnt vmcnt(0) lgkmcnt(0)" ::: "memory"); __builtin_amdgcn_s_barrier(); }
;     ...
;   if (V != 1) GLDS(0, 0);
;   RAWBAR();
;   for (int kt = 0; kt < nk; kt += 2) {
;     if (V != 1) GLDS(kt + 1, 1);
;     if (V != 2) COMPUTE(0);
;     RAWBAR();
;     if (V != 1) if (kt + 2 < nk) GLDS(kt + 2, 0);
;     if (V != 2) COMPUTE(1);
;     RAWBAR();
.Lai3_cadv_done:
	s_waitcnt lgkmcnt(6)
	v_mfma_f32_32x32x16_bf16 v[0:15], v[162:165], v[128:131], v[0:15]
	v_mfma_f32_32x32x16_bf16 v[16:31], v[166:169], v[128:131], v[16:31]
	ds_read_b128 v[128:131], v210
	v_mfma_f32_32x32x16_bf16 v[32:47], v[162:165], v[132:135], v[32:47]
	v_mfma_f32_32x32x16_bf16 v[48:63], v[166:169], v[132:135], v[48:63]
	ds_read_b128 v[132:135], v210 offset:4096
	v_mfma_f32_32x32x16_bf16 v[64:79], v[162:165], v[136:139], v[64:79]
	v_mfma_f32_32x32x16_bf16 v[80:95], v[166:169], v[136:139], v[80:95]
	ds_read_b128 v[136:139], v210 offset:8192
	v_mfma_f32_32x32x16_bf16 v[96:111], v[162:165], v[140:143], v[96:111]
	v_mfma_f32_32x32x16_bf16 v[112:127], v[166:169], v[140:143], v[112:127]
	ds_read_b128 v[140:143], v210 offset:12288
	ds_read_b128 v[162:165], v218
	ds_read_b128 v[166:169], v218 offset:4096
	s_waitcnt lgkmcnt(6)
	v_mfma_f32_32x32x16_bf16 v[0:15], v[170:173], v[144:147], v[0:15]
	v_mfma_f32_32x32x16_bf16 v[16:31], v[174:177], v[144:147], v[16:31]
	ds_read_b128 v[144:147], v211
	v_mfma_f32_32x32x16_bf16 v[32:47], v[170:173], v[148:151], v[32:47]
	v_mfma_f32_32x32x16_bf16 v[48:63], v[174:177], v[148:151], v[48:63]
	ds_read_b128 v[148:151], v211 offset:4096
	v_mfma_f32_32x32x16_bf16 v[64:79], v[170:173], v[152:155], v[64:79]
	v_mfma_f32_32x32x16_bf16 v[80:95], v[174:177], v[152:155], v[80:95]
	ds_read_b128 v[152:155], v211 offset:8192
	v_mfma_f32_32x32x16_bf16 v[96:111], v[170:173], v[156:159], v[96:111]
	v_mfma_f32_32x32x16_bf16 v[112:127], v[174:177], v[156:159], v[112:127]
	ds_read_b128 v[156:159], v211 offset:12288
	ds_read_b128 v[170:173], v219
	ds_read_b128 v[174:177], v219 offset:4096
	s_waitcnt vmcnt(0) lgkmcnt(0)
	s_barrier
	s_add_u32 m0, s14, 0x10000
	v_mfma_f32_32x32x16_bf16 v[0:15], v[162:165], v[128:131], v[0:15]
	global_load_lds_dwordx4 v220, s[22:23]
	s_add_u32 m0, s14, 0x18000
	v_mfma_f32_32x32x16_bf16 v[16:31], v[166:169], v[128:131], v[16:31]
	global_load_lds_dwordx4 v220, s[24:25]
	ds_read_b128 v[128:131], v204
	s_add_u32 m0, s14, 0x10400
	v_mfma_f32_32x32x16_bf16 v[32:47], v[162:165], v[132:135], v[32:47]
	global_load_lds_dwordx4 v221, s[22:23]
	s_add_u32 m0, s14, 0x18400
	v_mfma_f32_32x32x16_bf16 v[48:63], v[166:169], v[132:135], v[48:63]
	global_load_lds_dwordx4 v221, s[24:25]
	ds_read_b128 v[132:135], v204 offset:4096
	s_add_u32 m0, s14, 0x10800
	v_mfma_f32_32x32x16_bf16 v[64:79], v[162:165], v[136:139], v[64:79]
	global_load_lds_dwordx4 v222, s[22:23]
	s_add_u32 m0, s14, 0x18800
	v_mfma_f32_32x32x16_bf16 v[80:95], v[166:169], v[136:139], v[80:95]
	global_load_lds_dwordx4 v222, s[24:25]
	ds_read_b128 v[136:139], v204 offset:8192
	s_add_u32 m0, s14, 0x10c00
	v_mfma_f32_32x32x16_bf16 v[96:111], v[162:165], v[140:143], v[96:111]
	global_load_lds_dwordx4 v223, s[22:23]
	s_add_u32 m0, s14, 0x18c00
	v_mfma_f32_32x32x16_bf16 v[112:127], v[166:169], v[140:143], v[112:127]
	global_load_lds_dwordx4 v223, s[24:25]
	ds_read_b128 v[140:143], v204 offset:12288
	ds_read_b128 v[162:165], v212
	ds_read_b128 v[166:169], v212 offset:4096
	v_mfma_f32_32x32x16_bf16 v[0:15], v[170:173], v[144:147], v[0:15]
	v_mfma_f32_32x32x16_bf16 v[16:31], v[174:177], v[144:147], v[16:31]
	ds_read_b128 v[144:147], v205
	v_mfma_f32_32x32x16_bf16 v[32:47], v[170:173], v[148:151], v[32:47]
	v_mfma_f32_32x32x16_bf16 v[48:63], v[174:177], v[148:151], v[48:63]
	ds_read_b128 v[148:151], v205 offset:4096
	v_mfma_f32_32x32x16_bf16 v[64:79], v[170:173], v[152:155], v[64:79]
	v_mfma_f32_32x32x16_bf16 v[80:95], v[174:177], v[152:155], v[80:95]
	ds_read_b128 v[152:155], v205 offset:8192
	v_mfma_f32_32x32x16_bf16 v[96:111], v[170:173], v[156:159], v[96:111]
	v_mfma_f32_32x32x16_bf16 v[112:127], v[174:177], v[156:159], v[112:127]
	ds_read_b128 v[156:159], v205 offset:12288
	ds_read_b128 v[170:173], v213
	ds_read_b128 v[174:177], v213 offset:4096
	s_add_u32 s22, s22, 0x80
	s_addc_u32 s23, s23, 0
	s_add_u32 s24, s24, 0x80
	s_addc_u32 s25, s25, 0
	s_add_u32 s26, s26, 1
	s_cmp_eq_u32 s26, 16
	s_cbranch_scc0 .Lai4_cadv_done
	s_mov_b32 s26, 0
	s_add_u32 s27, s27, s30
	s_cmp_lt_u32 s27, 0x60
	s_cbranch_scc1 .Lai4_cadv_new
	s_sub_u32 s22, s22, 0x800
	s_subb_u32 s23, s23, 0
	s_sub_u32 s24, s24, 0x800
	s_subb_u32 s25, s25, 0
	s_branch .Lai4_cadv_done

; #define RAWBAR() { asm volatile("s_waitcnt vmcnt(0) lgkmcnt(0)" ::: "memory"); __builtin_amdgcn_s_barrier(); }
;     ...
;   for (int kt = 0; kt < nk; kt += 2) {
;     if (V != 1) GLDS(kt + 1, 1);
;     if (V != 2) COMPUTE(0);
;     RAWBAR();
;     if (V != 1) if (kt + 2 < nk) GLDS(kt + 2, 0);
;     if (V != 2) COMPUTE(1);
;     RAWBAR();
.Lai4_cadv_done:
	s_mov_b32 s29, 6
	s_cmp_eq_u32 s29, 0
	s_cbranch_scc1 .Lai_pairs_done
.Lai_pair:
	s_waitcnt lgkmcnt(6)
	v_mfma_f32_32x32x16_bf16 v[0:15], v[162:165], v[128:131], v[0:15]
	v_mfma_f32_32x32x16_bf16 v[16:31], v[166:169], v[128:131], v[16:31]
	ds_read_b128 v[128:131], v206
	v_mfma_f32_32x32x16_bf16 v[32:47], v[162:165], v[132:135], v[32:47]
	v_mfma_f32_32x32x16_bf16 v[48:63], v[166:169], v[132:135], v[48:63]
	ds_read_b128 v[132:135], v206 offset:4096
	v_mfma_f32_32x32x16_bf16 v[64:79], v[162:165], v[136:139], v[64:79]
	v_mfma_f32_32x32x16_bf16 v[80:95], v[166:169], v[136:139], v[80:95]
	ds_read_b128 v[136:139], v206 offset:8192
	v_mfma_f32_32x32x16_bf16 v[96:111], v[162:165], v[140:143], v[96:111]
	v_mfma_f32_32x32x16_bf16 v[112:127], v[166:169], v[140:143], v[112:127]
	ds_read_b128 v[140:143], v206 offset:12288
	ds_read_b128 v[162:165], v214
	ds_read_b128 v[166:169], v214 offset:4096
	s_waitcnt lgkmcnt(6)
	v_mfma_f32_32x32x16_bf16 v[0:15], v[170:173], v[144:147], v[0:15]
	v_mfma_f32_32x32x16_bf16 v[16:31], v[174:177], v[144:147], v[16:31]
	ds_read_b128 v[144:147], v207
	v_mfma_f32_32x32x16_bf16 v[32:47], v[170:173], v[148:151], v[32:47]
	v_mfma_f32_32x32x16_bf16 v[48:63], v[174:177], v[148:151], v[48:63]
	ds_read_b128 v[148:151], v207 offset:4096
	v_mfma_f32_32x32x16_bf16 v[64:79], v[170:173], v[152:155], v[64:79]
	v_mfma_f32_32x32x16_bf16 v[80:95], v[174:177], v[152:155], v[80:95]
	ds_read_b128 v[152:155], v207 offset:8192
	v_mfma_f32_32x32x16_bf16 v[96:111], v[170:173], v[156:159], v[96:111]
	v_mfma_f32_32x32x16_bf16 v[112:127], v[174:177], v[156:159], v[112:127]
	ds_read_b128 v[156:159], v207 offset:12288
	ds_read_b128 v[170:173], v215
	ds_read_b128 v[174:177], v215 offset:4096
	s_waitcnt vmcnt(0) lgkmcnt(0)
	s_barrier
	s_add_u32 m0, s14, 0x0
	v_mfma_f32_32x32x16_bf16 v[0:15], v[162:165], v[128:131], v[0:15]
	global_load_lds_dwordx4 v220, s[22:23]
	s_add_u32 m0, s14, 0x8000
	v_mfma_f32_32x32x16_bf16 v[16:31], v[166:169], v[128:131], v[16:31]
	global_load_lds_dwordx4 v220, s[24:25]
	ds_read_b128 v[128:131], v208
	s_add_u32 m0, s14, 0x400
	v_mfma_f32_32x32x16_bf16 v[32:47], v[162:165], v[132:135], v[32:47]
	global_load_lds_dwordx4 v221, s[22:23]
	s_add_u32 m0, s14, 0x8400
	v_mfma_f32_32x32x16_bf16 v[48:63], v[166:169], v[132:135], v[48:63]
	global_load_lds_dwordx4 v221, s[24:25]
	ds_read_b128 v[132:135], v208 offset:4096
	s_add_u32 m0, s14, 0x800
	v_mfma_f32_32x32x16_bf16 v[64:79], v[162:165], v[136:139], v[64:79]
	global_load_lds_dwordx4 v222, s[22:23]
	s_add_u32 m0, s14, 0x8800
	v_mfma_f32_32x32x16_bf16 v[80:95], v[166:169], v[136:139], v[80:95]
	global_load_lds_dwordx4 v222, s[24:25]
	ds_read_b128 v[136:139], v208 offset:8192
	s_add_u32 m0, s14, 0xc00
	v_mfma_f32_32x32x16_bf16 v[96:111], v[162:165], v[140:143], v[96:111]
	global_load_lds_dwordx4 v223, s[22:23]
	s_add_u32 m0, s14, 0x8c00
	v_mfma_f32_32x32x16_bf16 v[112:127], v[166:169], v[140:143], v[112:127]
	global_load_lds_dwordx4 v223, s[24:25]
	ds_read_b128 v[140:143], v208 offset:12288
	ds_read_b128 v[162:165], v216
	ds_read_b128 v[166:169], v216 offset:4096
	v_mfma_f32_32x32x16_bf16 v[0:15], v[170:173], v[144:147], v[0:15]
	v_mfma_f32_32x32x16_bf16 v[16:31], v[174:177], v[144:147], v[16:31]
	ds_read_b128 v[144:147], v209
	v_mfma_f32_32x32x16_bf16 v[32:47], v[170:173], v[148:151], v[32:47]
	v_mfma_f32_32x32x16_bf16 v[48:63], v[174:177], v[148:151], v[48:63]
	ds_read_b128 v[148:151], v209 offset:4096
	v_mfma_f32_32x32x16_bf16 v[64:79], v[170:173], v[152:155], v[64:79]
	v_mfma_f32_32x32x16_bf16 v[80:95], v[174:177], v[152:155], v[80:95]
	ds_read_b128 v[152:155], v209 offset:8192
	v_mfma_f32_32x32x16_bf16 v[96:111], v[170:173], v[156:159], v[96:111]
	v_mfma_f32_32x32x16_bf16 v[112:127], v[174:177], v[156:159], v[112:127]
	ds_read_b128 v[156:159], v209 offset:12288
	ds_read_b128 v[170:173], v217
	ds_read_b128 v[174:177], v217 offset:4096
	s_add_u32 s22, s22, 0x80
	s_addc_u32 s23, s23, 0
	s_add_u32 s24, s24, 0x80
	s_addc_u32 s25, s25, 0
	s_add_u32 s26, s26, 1
	s_cmp_eq_u32 s26, 16
	s_cbranch_scc0 .Lai5_cadv_done
	s_mov_b32 s26, 0
	s_add_u32 s27, s27, s30
	s_cmp_lt_u32 s27, 0x60
	s_cbranch_scc1 .Lai5_cadv_new
	s_sub_u32 s22, s22, 0x800
	s_subb_u32 s23, s23, 0
	s_sub_u32 s24, s24, 0x800
	s_subb_u32 s25, s25, 0
	s_branch .Lai5_cadv_done

; #define RAWBAR() { asm volatile("s_waitcnt vmcnt(0) lgkmcnt(0)" ::: "memory"); __builtin_amdgcn_s_barrier(); }
;     ...
;   for (int kt = 0; kt < nk; kt += 2) {
;     if (V != 1) GLDS(kt + 1, 1);
;     if (V != 2) COMPUTE(0);
;     RAWBAR();
;     if (V != 1) if (kt + 2 < nk) GLDS(kt + 2, 0);
;     if (V != 2) COMPUTE(1);
;     RAWBAR();
;   }
.Lai6_cadv_done:
	s_sub_u32 s29, s29, 1
	s_cmp_lg_u32 s29, 0
	s_cbranch_scc1 .Lai_pair

; DI int crow(int r, int hf) { return (r & 3) + 8 * (r >> 2) + 4 * hf; }
; DI void att_in_phase(const Params& p, int j, char* smem) {
;     ...
;     gemm_tile(A + (size_t)m0 * LDH, LDH, 16, nullptr, 0, 0, Wt + (size_t)n0 * LDW1, LDW1, smem, [&](f32x16(&acc)[2][2], int moff) {
;       const int m0_ = m0 + moff;
;       int l32_ = l32, hf_ = hf; asm volatile("" : "+v"(l32_), "+v"(hf_));
;       const int C64 = n0 + wn * 64;
; #pragma unroll
;       for (int i = 0; i < 2; ++i) {
;         const int rb = m0_ + wm * 64 + i * 32;
;         if (C64 < 640) {
; #pragma unroll
;           for (int jn = 0; jn < 2; ++jn)
; #pragma unroll
;             for (int r = 0; r < 16; ++r) zc[(size_t)(rb + crow(r, hf_)) * 640 + C64 + jn * 32 + l32_] = f2bf(acc[i][jn][r]);
.Lai7_cadv_done:
	s_waitcnt lgkmcnt(6)
	v_mfma_f32_32x32x16_bf16 v[0:15], v[162:165], v[128:131], v[0:15]
	v_mfma_f32_32x32x16_bf16 v[16:31], v[166:169], v[128:131], v[16:31]
	ds_read_b128 v[128:131], v210
	v_mfma_f32_32x32x16_bf16 v[32:47], v[162:165], v[132:135], v[32:47]
	v_mfma_f32_32x32x16_bf16 v[48:63], v[166:169], v[132:135], v[48:63]
	ds_read_b128 v[132:135], v210 offset:4096
	v_mfma_f32_32x32x16_bf16 v[64:79], v[162:165], v[136:139], v[64:79]
	v_mfma_f32_32x32x16_bf16 v[80:95], v[166:169], v[136:139], v[80:95]
	ds_read_b128 v[136:139], v210 offset:8192
	v_mfma_f32_32x32x16_bf16 v[96:111], v[162:165], v[140:143], v[96:111]
	v_mfma_f32_32x32x16_bf16 v[112:127], v[166:169], v[140:143], v[112:127]
	ds_read_b128 v[140:143], v210 offset:12288
	ds_read_b128 v[162:165], v218
	ds_read_b128 v[166:169], v218 offset:4096
	s_waitcnt lgkmcnt(6)
	v_mfma_f32_32x32x16_bf16 v[0:15], v[170:173], v[144:147], v[0:15]
	v_mfma_f32_32x32x16_bf16 v[16:31], v[174:177], v[144:147], v[16:31]
	ds_read_b128 v[144:147], v211
	v_mfma_f32_32x32x16_bf16 v[32:47], v[170:173], v[148:151], v[32:47]
	v_mfma_f32_32x32x16_bf16 v[48:63], v[174:177], v[148:151], v[48:63]
	ds_read_b128 v[148:151], v211 offset:4096
	v_mfma_f32_32x32x16_bf16 v[64:79], v[170:173], v[152:155], v[64:79]
	v_mfma_f32_32x32x16_bf16 v[80:95], v[174:177], v[152:155], v[80:95]
	ds_read_b128 v[152:155], v211 offset:8192
	v_mfma_f32_32x32x16_bf16 v[96:111], v[170:173], v[156:159], v[96:111]
	v_mfma_f32_32x32x16_bf16 v[112:127], v[174:177], v[156:159], v[112:127]
	ds_read_b128 v[156:159], v211 offset:12288
	ds_read_b128 v[170:173], v219
	ds_read_b128 v[174:177], v219 offset:4096
	s_waitcnt vmcnt(0) lgkmcnt(0)
	s_barrier
	s_add_u32 m0, s14, 0x10000
	v_mfma_f32_32x32x16_bf16 v[0:15], v[162:165], v[128:131], v[0:15]
	global_load_lds_dwordx4 v220, s[22:23]
	s_add_u32 m0, s14, 0x10400
	v_mfma_f32_32x32x16_bf16 v[16:31], v[166:169], v[128:131], v[16:31]
	global_load_lds_dwordx4 v221, s[22:23]
	s_add_u32 m0, s14, 0x10800
	v_mfma_f32_32x32x16_bf16 v[32:47], v[162:165], v[132:135], v[32:47]
	global_load_lds_dwordx4 v222, s[22:23]
	s_add_u32 m0, s14, 0x10c00
	v_mfma_f32_32x32x16_bf16 v[48:63], v[166:169], v[132:135], v[48:63]
	global_load_lds_dwordx4 v223, s[22:23]
	v_mfma_f32_32x32x16_bf16 v[64:79], v[162:165], v[136:139], v[64:79]
	v_mfma_f32_32x32x16_bf16 v[80:95], v[166:169], v[136:139], v[80:95]
	v_mfma_f32_32x32x16_bf16 v[96:111], v[162:165], v[140:143], v[96:111]
	v_mfma_f32_32x32x16_bf16 v[112:127], v[166:169], v[140:143], v[112:127]
	v_mfma_f32_32x32x16_bf16 v[0:15], v[170:173], v[144:147], v[0:15]
	v_mfma_f32_32x32x16_bf16 v[16:31], v[174:177], v[144:147], v[16:31]
	v_mfma_f32_32x32x16_bf16 v[32:47], v[170:173], v[148:151], v[32:47]
	v_mfma_f32_32x32x16_bf16 v[48:63], v[174:177], v[148:151], v[48:63]
	v_mfma_f32_32x32x16_bf16 v[64:79], v[170:173], v[152:155], v[64:79]
	v_mfma_f32_32x32x16_bf16 v[80:95], v[174:177], v[152:155], v[80:95]
	v_mfma_f32_32x32x16_bf16 v[96:111], v[170:173], v[156:159], v[96:111]
	v_mfma_f32_32x32x16_bf16 v[112:127], v[174:177], v[156:159], v[112:127]
	s_lshr_b32 s20, s28, 5
	s_lshl_b32 s20, s20, 1
	s_and_b32 s8, s28, 1
	s_add_u32 s20, s20, s8
	s_lshl_b32 s20, s20, 2
	s_add_u32 s20, s20, s13
	s_cmp_lt_u32 s20, 10
	s_cbranch_scc1 .Lai_epi_zc
	s_cmp_lt_u32 s20, 18
	s_cbranch_scc1 .Lai_epi_sq
	s_cmp_lt_u32 s20, 20
	s_cbranch_scc1 .Lai_epi_sk
	s_cmp_lt_u32 s20, 22
	s_cbranch_scc1 .Lai_epi_sv
	s_cmp_eq_u32 s20, 22
	s_cbranch_scc1 .Lai_epi_kr
	s_branch .Lai_epi_done
.Lai_epi_zc:
	s_lshl_b32 s9, s20, 7
	s_mul_i32 s8, s52, 0x500
	s_add_u32 s8, s8, s9
	s_add_u32 s38, s0, s8
	s_addc_u32 s39, s1, 0
	s_add_u32 s38, s38, 0xd004100
	s_addc_u32 s39, s39, 0
	v_cvt_pk_bf16_f32 v240, v0, v1
	v_cvt_pk_bf16_f32 v241, v2, v3
	ds_write_b64 v178, v[240:241]
	v_cvt_pk_bf16_f32 v242, v4, v5
	v_cvt_pk_bf16_f32 v243, v6, v7
	ds_write_b64 v179, v[242:243]
	v_cvt_pk_bf16_f32 v244, v8, v9
	v_cvt_pk_bf16_f32 v245, v10, v11
	ds_write_b64 v180, v[244:245]
	v_cvt_pk_bf16_f32 v246, v12, v13
	v_cvt_pk_bf16_f32 v247, v14, v15
	ds_write_b64 v181, v[246:247]
	v_cvt_pk_bf16_f32 v240, v16, v17
	v_cvt_pk_bf16_f32 v241, v18, v19
	ds_write_b64 v188, v[240:241]
	v_cvt_pk_bf16_f32 v242, v20, v21
	v_cvt_pk_bf16_f32 v243, v22, v23
	ds_write_b64 v189, v[242:243]
	v_cvt_pk_bf16_f32 v244, v24, v25
	v_cvt_pk_bf16_f32 v245, v26, v27
	ds_write_b64 v190, v[244:245]
	v_cvt_pk_bf16_f32 v246, v28, v29
	v_cvt_pk_bf16_f32 v247, v30, v31
	ds_write_b64 v191, v[246:247]
	ds_read_b128 v[0:3], v194
	ds_read_b128 v[4:7], v194 offset:1024
	ds_read_b128 v[8:11], v194 offset:2048
	ds_read_b128 v[12:15], v194 offset:3072
	v_cvt_pk_bf16_f32 v240, v32, v33
	v_cvt_pk_bf16_f32 v241, v34, v35
	ds_write_b64 v178, v[240:241]
	v_cvt_pk_bf16_f32 v242, v36, v37
	v_cvt_pk_bf16_f32 v243, v38, v39
	ds_write_b64 v179, v[242:243]
	v_cvt_pk_bf16_f32 v244, v40, v41
	v_cvt_pk_bf16_f32 v245, v42, v43
	ds_write_b64 v180, v[244:245]
	v_cvt_pk_bf16_f32 v246, v44, v45
	v_cvt_pk_bf16_f32 v247, v46, v47
	ds_write_b64 v181, v[246:247]
	v_cvt_pk_bf16_f32 v240, v48, v49
	v_cvt_pk_bf16_f32 v241, v50, v51
	ds_write_b64 v188, v[240:241]
	v_cvt_pk_bf16_f32 v242, v52, v53
	v_cvt_pk_bf16_f32 v243, v54, v55
	ds_write_b64 v189, v[242:243]
	v_cvt_pk_bf16_f32 v244, v56, v57
	v_cvt_pk_bf16_f32 v245, v58, v59
	ds_write_b64 v190, v[244:245]
	v_cvt_pk_bf16_f32 v246, v60, v61
	v_cvt_pk_bf16_f32 v247, v62, v63
	ds_write_b64 v191, v[246:247]
	ds_read_b128 v[32:35], v194
	ds_read_b128 v[36:39], v194 offset:1024
	ds_read_b128 v[40:43], v194 offset:2048
	ds_read_b128 v[44:47], v194 offset:3072
	s_waitcnt lgkmcnt(12)
; DI int crow(int r, int hf) { return (r & 3) + 8 * (r >> 2) + 4 * hf; }
; DI void att_in_phase(const Params& p, int j, char* smem) {
;     ...
;         if (C64 < 640) {
; #pragma unroll
;           for (int jn = 0; jn < 2; ++jn)
; #pragma unroll
;             for (int r = 0; r < 16; ++r) zc[(size_t)(rb + crow(r, hf_)) * 640 + C64 + jn * 32 + l32_] = f2bf(acc[i][jn][r]);
;         } else if (C64 < 1280) {
;           const bool isq = C64 < 1152;
;           u16* dst = isq ? SQ : SK; const int pitch = isq ? 512 : 128; const int cb = isq ? (C64 - 640) : (C64 - 1152);
;           const float sc = isq ? SWA_QSCALE : 1.f;
; #pragma unroll
;           for (int r = 0; r < 16; ++r) {
;             const int t = rb + crow(r, hf_), pos = t & (S_ - 1);
;             const float2 cs = rt64[pos * 32 + l32_];
;             const float x1 = acc[i][0][r], x2 = acc[i][1][r];
;             dst[(size_t)t * pitch + cb + l32_] = f2bf((x1 * cs.x - x2 * cs.y) * sc);
;             dst[(size_t)t * pitch + cb + 32 + l32_] = f2bf((x2 * cs.x + x1 * cs.y) * sc);
	global_store_dwordx4 v195, v[0:3], s[38:39] nt
	s_add_u32 s38, s38, 0x2800
	s_addc_u32 s39, s39, 0
	global_store_dwordx4 v195, v[4:7], s[38:39] nt
	s_add_u32 s38, s38, 0x2800
	s_addc_u32 s39, s39, 0
	global_store_dwordx4 v195, v[8:11], s[38:39] nt
	s_add_u32 s38, s38, 0x2800
	s_addc_u32 s39, s39, 0
	global_store_dwordx4 v195, v[12:15], s[38:39] nt
	s_add_u32 s38, s38, 0x2800
	s_addc_u32 s39, s39, 0
	v_cvt_pk_bf16_f32 v240, v64, v65
	v_cvt_pk_bf16_f32 v241, v66, v67
	ds_write_b64 v178, v[240:241]
	v_cvt_pk_bf16_f32 v242, v68, v69
	v_cvt_pk_bf16_f32 v243, v70, v71
	ds_write_b64 v179, v[242:243]
	v_cvt_pk_bf16_f32 v244, v72, v73
	v_cvt_pk_bf16_f32 v245, v74, v75
	ds_write_b64 v180, v[244:245]
	v_cvt_pk_bf16_f32 v246, v76, v77
	v_cvt_pk_bf16_f32 v247, v78, v79
	ds_write_b64 v181, v[246:247]
	v_cvt_pk_bf16_f32 v240, v80, v81
	v_cvt_pk_bf16_f32 v241, v82, v83
	ds_write_b64 v188, v[240:241]
	v_cvt_pk_bf16_f32 v242, v84, v85
	v_cvt_pk_bf16_f32 v243, v86, v87
	ds_write_b64 v189, v[242:243]
	v_cvt_pk_bf16_f32 v244, v88, v89
	v_cvt_pk_bf16_f32 v245, v90, v91
	ds_write_b64 v190, v[244:245]
	v_cvt_pk_bf16_f32 v246, v92, v93
	v_cvt_pk_bf16_f32 v247, v94, v95
	ds_write_b64 v191, v[246:247]
	ds_read_b128 v[64:67], v194
	ds_read_b128 v[68:71], v194 offset:1024
	ds_read_b128 v[72:75], v194 offset:2048
	ds_read_b128 v[76:79], v194 offset:3072
	s_waitcnt lgkmcnt(12)
	global_store_dwordx4 v195, v[32:35], s[38:39] nt
	s_add_u32 s38, s38, 0x2800
	s_addc_u32 s39, s39, 0
	global_store_dwordx4 v195, v[36:39], s[38:39] nt
	s_add_u32 s38, s38, 0x2800
	s_addc_u32 s39, s39, 0
	global_store_dwordx4 v195, v[40:43], s[38:39] nt
	s_add_u32 s38, s38, 0x2800
	s_addc_u32 s39, s39, 0
	global_store_dwordx4 v195, v[44:47], s[38:39] nt
	s_add_u32 s38, s38, 0x2800
	s_addc_u32 s39, s39, 0
	v_cvt_pk_bf16_f32 v240, v96, v97
	v_cvt_pk_bf16_f32 v241, v98, v99
	ds_write_b64 v178, v[240:241]
	v_cvt_pk_bf16_f32 v242, v100, v101
	v_cvt_pk_bf16_f32 v243, v102, v103
	ds_write_b64 v179, v[242:243]
	v_cvt_pk_bf16_f32 v244, v104, v105
	v_cvt_pk_bf16_f32 v245, v106, v107
	ds_write_b64 v180, v[244:245]
	v_cvt_pk_bf16_f32 v246, v108, v109
	v_cvt_pk_bf16_f32 v247, v110, v111
	ds_write_b64 v181, v[246:247]
	v_cvt_pk_bf16_f32 v240, v112, v113
	v_cvt_pk_bf16_f32 v241, v114, v115
	ds_write_b64 v188, v[240:241]
	v_cvt_pk_bf16_f32 v242, v116, v117
	v_cvt_pk_bf16_f32 v243, v118, v119
	ds_write_b64 v189, v[242:243]
	v_cvt_pk_bf16_f32 v244, v120, v121
	v_cvt_pk_bf16_f32 v245, v122, v123
	ds_write_b64 v190, v[244:245]
	v_cvt_pk_bf16_f32 v246, v124, v125
	v_cvt_pk_bf16_f32 v247, v126, v127
	ds_write_b64 v191, v[246:247]
	ds_read_b128 v[96:99], v194
	ds_read_b128 v[100:103], v194 offset:1024
	ds_read_b128 v[104:107], v194 offset:2048
	ds_read_b128 v[108:111], v194 offset:3072
	s_waitcnt lgkmcnt(12)
	global_store_dwordx4 v195, v[64:67], s[38:39] nt
	s_add_u32 s38, s38, 0x2800
	s_addc_u32 s39, s39, 0
	global_store_dwordx4 v195, v[68:71], s[38:39] nt
	s_add_u32 s38, s38, 0x2800
	s_addc_u32 s39, s39, 0
	global_store_dwordx4 v195, v[72:75], s[38:39] nt
	s_add_u32 s38, s38, 0x2800
	s_addc_u32 s39, s39, 0
	global_store_dwordx4 v195, v[76:79], s[38:39] nt
	s_add_u32 s38, s38, 0x2800
	s_addc_u32 s39, s39, 0
	s_waitcnt lgkmcnt(0)
	global_store_dwordx4 v195, v[96:99], s[38:39] nt
	s_add_u32 s38, s38, 0x2800
	s_addc_u32 s39, s39, 0
	global_store_dwordx4 v195, v[100:103], s[38:39] nt
	s_add_u32 s38, s38, 0x2800
	s_addc_u32 s39, s39, 0
	global_store_dwordx4 v195, v[104:107], s[38:39] nt
	s_add_u32 s38, s38, 0x2800
	s_addc_u32 s39, s39, 0
	global_store_dwordx4 v195, v[108:111], s[38:39] nt
	s_branch .Lai_epi_done
.Lai_epi_sq:
	s_sub_u32 s9, s20, 10
	s_lshl_b32 s9, s9, 7
	s_mul_i32 s8, s52, 0x400
	s_add_u32 s8, s8, s9
	s_add_u32 s38, s0, s8
	s_addc_u32 s39, s1, 0
	s_add_u32 s38, s38, 0x17c24100
	s_addc_u32 s39, s39, 0
	s_mov_b32 s51, 0x3e38aa3b
	s_add_u32 s8, s36, 0x0
	s_addc_u32 s9, s37, 0
	global_load_dwordx4 v[128:131], v160, s[8:9]
	global_load_dwordx4 v[132:135], v160, s[8:9] offset:16
	s_add_u32 s8, s36, 0x0
	s_addc_u32 s9, s37, 0
	global_load_dwordx4 v[136:139], v160, s[8:9] offset:64
	global_load_dwordx4 v[140:143], v160, s[8:9] offset:80
	s_add_u32 s8, s36, 0x0
	s_addc_u32 s9, s37, 0
	global_load_dwordx4 v[144:147], v160, s[8:9] offset:128
	global_load_dwordx4 v[148:151], v160, s[8:9] offset:144
	s_add_u32 s8, s36, 0x0
	s_addc_u32 s9, s37, 0
	global_load_dwordx4 v[152:155], v160, s[8:9] offset:192
	global_load_dwordx4 v[156:159], v160, s[8:9] offset:208
	s_add_u32 s8, s36, 0x2000
	s_addc_u32 s9, s37, 0
	global_load_dwordx4 v[162:165], v160, s[8:9]
	global_load_dwordx4 v[166:169], v160, s[8:9] offset:16
	s_add_u32 s8, s36, 0x2000
	s_addc_u32 s9, s37, 0
	global_load_dwordx4 v[170:173], v160, s[8:9] offset:64
	global_load_dwordx4 v[174:177], v160, s[8:9] offset:80
	s_add_u32 s8, s36, 0x2000
	s_addc_u32 s9, s37, 0
	global_load_dwordx4 v[224:227], v160, s[8:9] offset:128
	global_load_dwordx4 v[228:231], v160, s[8:9] offset:144
	s_add_u32 s8, s36, 0x2000
	s_addc_u32 s9, s37, 0
	global_load_dwordx4 v[232:235], v160, s[8:9] offset:192
	global_load_dwordx4 v[236:239], v160, s[8:9] offset:208
	s_waitcnt vmcnt(14)
	v_mul_f32_e32 v246, v16, v129
	v_mul_f32_e32 v247, v0, v129
	v_fma_f32 v0, v0, v128, -v246
	v_fma_f32 v16, v16, v128, v247
	v_mul_f32_e32 v0, s51, v0
	v_mul_f32_e32 v16, s51, v16
	v_mul_f32_e32 v246, v17, v131
	v_mul_f32_e32 v247, v1, v131
	v_fma_f32 v1, v1, v130, -v246
	v_fma_f32 v17, v17, v130, v247
	v_mul_f32_e32 v1, s51, v1
	v_mul_f32_e32 v17, s51, v17
	v_mul_f32_e32 v246, v18, v133
	v_mul_f32_e32 v247, v2, v133
	v_fma_f32 v2, v2, v132, -v246
	v_fma_f32 v18, v18, v132, v247
	v_mul_f32_e32 v2, s51, v2
	v_mul_f32_e32 v18, s51, v18
	v_mul_f32_e32 v246, v19, v135
	v_mul_f32_e32 v247, v3, v135
	v_fma_f32 v3, v3, v134, -v246
	v_fma_f32 v19, v19, v134, v247
	v_mul_f32_e32 v3, s51, v3
	v_mul_f32_e32 v19, s51, v19
	s_add_u32 s8, s36, 0x4000
	s_addc_u32 s9, s37, 0
	global_load_dwordx4 v[128:131], v160, s[8:9]
	global_load_dwordx4 v[132:135], v160, s[8:9] offset:16
	s_waitcnt vmcnt(14)
; DI int crow(int r, int hf) { return (r & 3) + 8 * (r >> 2) + 4 * hf; }
; DI void att_in_phase(const Params& p, int j, char* smem) {
;     ...
;         } else if (C64 < 1280) {
;           const bool isq = C64 < 1152;
;           u16* dst = isq ? SQ : SK; const int pitch = isq ? 512 : 128; const int cb = isq ? (C64 - 640) : (C64 - 1152);
;           const float sc = isq ? SWA_QSCALE : 1.f;
; #pragma unroll
;           for (int r = 0; r < 16; ++r) {
;             const int t = rb + crow(r, hf_), pos = t & (S_ - 1);
;             const float2 cs = rt64[pos * 32 + l32_];
;             const float x1 = acc[i][0][r], x2 = acc[i][1][r];
;             dst[(size_t)t * pitch + cb + l32_] = f2bf((x1 * cs.x - x2 * cs.y) * sc);
;             dst[(size_t)t * pitch + cb + 32 + l32_] = f2bf((x2 * cs.x + x1 * cs.y) * sc);
	v_mul_f32_e32 v246, v20, v137
	v_mul_f32_e32 v247, v4, v137
	v_fma_f32 v4, v4, v136, -v246
	v_fma_f32 v20, v20, v136, v247
	v_mul_f32_e32 v4, s51, v4
	v_mul_f32_e32 v20, s51, v20
	v_mul_f32_e32 v246, v21, v139
	v_mul_f32_e32 v247, v5, v139
	v_fma_f32 v5, v5, v138, -v246
	v_fma_f32 v21, v21, v138, v247
	v_mul_f32_e32 v5, s51, v5
	v_mul_f32_e32 v21, s51, v21
	v_mul_f32_e32 v246, v22, v141
	v_mul_f32_e32 v247, v6, v141
	v_fma_f32 v6, v6, v140, -v246
	v_fma_f32 v22, v22, v140, v247
	v_mul_f32_e32 v6, s51, v6
	v_mul_f32_e32 v22, s51, v22
	v_mul_f32_e32 v246, v23, v143
	v_mul_f32_e32 v247, v7, v143
	v_fma_f32 v7, v7, v142, -v246
	v_fma_f32 v23, v23, v142, v247
	v_mul_f32_e32 v7, s51, v7
	v_mul_f32_e32 v23, s51, v23
	s_add_u32 s8, s36, 0x4000
	s_addc_u32 s9, s37, 0
	global_load_dwordx4 v[136:139], v160, s[8:9] offset:64
	global_load_dwordx4 v[140:143], v160, s[8:9] offset:80
	s_waitcnt vmcnt(14)
	v_mul_f32_e32 v246, v24, v145
	v_mul_f32_e32 v247, v8, v145
	v_fma_f32 v8, v8, v144, -v246
	v_fma_f32 v24, v24, v144, v247
	v_mul_f32_e32 v8, s51, v8
	v_mul_f32_e32 v24, s51, v24
	v_mul_f32_e32 v246, v25, v147
	v_mul_f32_e32 v247, v9, v147
	v_fma_f32 v9, v9, v146, -v246
	v_fma_f32 v25, v25, v146, v247
	v_mul_f32_e32 v9, s51, v9
	v_mul_f32_e32 v25, s51, v25
	v_mul_f32_e32 v246, v26, v149
	v_mul_f32_e32 v247, v10, v149
	v_fma_f32 v10, v10, v148, -v246
	v_fma_f32 v26, v26, v148, v247
	v_mul_f32_e32 v10, s51, v10
	v_mul_f32_e32 v26, s51, v26
	v_mul_f32_e32 v246, v27, v151
	v_mul_f32_e32 v247, v11, v151
	v_fma_f32 v11, v11, v150, -v246
	v_fma_f32 v27, v27, v150, v247
	v_mul_f32_e32 v11, s51, v11
	v_mul_f32_e32 v27, s51, v27
	s_add_u32 s8, s36, 0x4000
	s_addc_u32 s9, s37, 0
	global_load_dwordx4 v[144:147], v160, s[8:9] offset:128
	global_load_dwordx4 v[148:151], v160, s[8:9] offset:144
	s_waitcnt vmcnt(14)
	v_mul_f32_e32 v246, v28, v153
	v_mul_f32_e32 v247, v12, v153
	v_fma_f32 v12, v12, v152, -v246
	v_fma_f32 v28, v28, v152, v247
	v_mul_f32_e32 v12, s51, v12
	v_mul_f32_e32 v28, s51, v28
	v_mul_f32_e32 v246, v29, v155
	v_mul_f32_e32 v247, v13, v155
	v_fma_f32 v13, v13, v154, -v246
	v_fma_f32 v29, v29, v154, v247
	v_mul_f32_e32 v13, s51, v13
	v_mul_f32_e32 v29, s51, v29
	v_mul_f32_e32 v246, v30, v157
	v_mul_f32_e32 v247, v14, v157
	v_fma_f32 v14, v14, v156, -v246
	v_fma_f32 v30, v30, v156, v247
	v_mul_f32_e32 v14, s51, v14
	v_mul_f32_e32 v30, s51, v30
	v_mul_f32_e32 v246, v31, v159
	v_mul_f32_e32 v247, v15, v159
	v_fma_f32 v15, v15, v158, -v246
	v_fma_f32 v31, v31, v158, v247
	v_mul_f32_e32 v15, s51, v15
	v_mul_f32_e32 v31, s51, v31
	s_add_u32 s8, s36, 0x4000
	s_addc_u32 s9, s37, 0
	global_load_dwordx4 v[152:155], v160, s[8:9] offset:192
	global_load_dwordx4 v[156:159], v160, s[8:9] offset:208
	v_cvt_pk_bf16_f32 v240, v0, v1
	v_cvt_pk_bf16_f32 v241, v2, v3
	ds_write_b64 v178, v[240:241]
	v_cvt_pk_bf16_f32 v242, v4, v5
	v_cvt_pk_bf16_f32 v243, v6, v7
	ds_write_b64 v179, v[242:243]
	v_cvt_pk_bf16_f32 v244, v8, v9
	v_cvt_pk_bf16_f32 v245, v10, v11
	ds_write_b64 v180, v[244:245]
	v_cvt_pk_bf16_f32 v240, v12, v13
	v_cvt_pk_bf16_f32 v241, v14, v15
	ds_write_b64 v181, v[240:241]
	v_cvt_pk_bf16_f32 v242, v16, v17
	v_cvt_pk_bf16_f32 v243, v18, v19
	ds_write_b64 v188, v[242:243]
	v_cvt_pk_bf16_f32 v244, v20, v21
	v_cvt_pk_bf16_f32 v245, v22, v23
	ds_write_b64 v189, v[244:245]
	v_cvt_pk_bf16_f32 v240, v24, v25
	v_cvt_pk_bf16_f32 v241, v26, v27
	ds_write_b64 v190, v[240:241]
	v_cvt_pk_bf16_f32 v242, v28, v29
	v_cvt_pk_bf16_f32 v243, v30, v31
	ds_write_b64 v191, v[242:243]
	ds_read_b128 v[0:3], v194
	ds_read_b128 v[4:7], v194 offset:1024
	ds_read_b128 v[8:11], v194 offset:2048
	ds_read_b128 v[12:15], v194 offset:3072
	s_waitcnt vmcnt(14)
	v_mul_f32_e32 v246, v48, v163
	v_mul_f32_e32 v247, v32, v163
	v_fma_f32 v32, v32, v162, -v246
	v_fma_f32 v48, v48, v162, v247
	v_mul_f32_e32 v32, s51, v32
	v_mul_f32_e32 v48, s51, v48
	v_mul_f32_e32 v246, v49, v165
	v_mul_f32_e32 v247, v33, v165
	v_fma_f32 v33, v33, v164, -v246
	v_fma_f32 v49, v49, v164, v247
	v_mul_f32_e32 v33, s51, v33
	v_mul_f32_e32 v49, s51, v49
	v_mul_f32_e32 v246, v50, v167
	v_mul_f32_e32 v247, v34, v167
	v_fma_f32 v34, v34, v166, -v246
	v_fma_f32 v50, v50, v166, v247
	v_mul_f32_e32 v34, s51, v34
	v_mul_f32_e32 v50, s51, v50
	v_mul_f32_e32 v246, v51, v169
	v_mul_f32_e32 v247, v35, v169
	v_fma_f32 v35, v35, v168, -v246
	v_fma_f32 v51, v51, v168, v247
	v_mul_f32_e32 v35, s51, v35
	v_mul_f32_e32 v51, s51, v51
	s_add_u32 s8, s36, 0x6000
	s_addc_u32 s9, s37, 0
	global_load_dwordx4 v[162:165], v160, s[8:9]
	global_load_dwordx4 v[166:169], v160, s[8:9] offset:16
	s_waitcnt vmcnt(14)
	v_mul_f32_e32 v246, v52, v171
	v_mul_f32_e32 v247, v36, v171
	v_fma_f32 v36, v36, v170, -v246
	v_fma_f32 v52, v52, v170, v247
	v_mul_f32_e32 v36, s51, v36
	v_mul_f32_e32 v52, s51, v52
	v_mul_f32_e32 v246, v53, v173
	v_mul_f32_e32 v247, v37, v173
	v_fma_f32 v37, v37, v172, -v246
	v_fma_f32 v53, v53, v172, v247
	v_mul_f32_e32 v37, s51, v37
	v_mul_f32_e32 v53, s51, v53
	v_mul_f32_e32 v246, v54, v175
	v_mul_f32_e32 v247, v38, v175
	v_fma_f32 v38, v38, v174, -v246
	v_fma_f32 v54, v54, v174, v247
	v_mul_f32_e32 v38, s51, v38
	v_mul_f32_e32 v54, s51, v54
	v_mul_f32_e32 v246, v55, v177
	v_mul_f32_e32 v247, v39, v177
	v_fma_f32 v39, v39, v176, -v246
	v_fma_f32 v55, v55, v176, v247
	v_mul_f32_e32 v39, s51, v39
	v_mul_f32_e32 v55, s51, v55
	s_add_u32 s8, s36, 0x6000
	s_addc_u32 s9, s37, 0
	global_load_dwordx4 v[170:173], v160, s[8:9] offset:64
	global_load_dwordx4 v[174:177], v160, s[8:9] offset:80
	s_waitcnt vmcnt(14)
; DI int crow(int r, int hf) { return (r & 3) + 8 * (r >> 2) + 4 * hf; }
; DI void att_in_phase(const Params& p, int j, char* smem) {
;     ...
;         } else if (C64 < 1280) {
;           const bool isq = C64 < 1152;
;           u16* dst = isq ? SQ : SK; const int pitch = isq ? 512 : 128; const int cb = isq ? (C64 - 640) : (C64 - 1152);
;           const float sc = isq ? SWA_QSCALE : 1.f;
; #pragma unroll
;           for (int r = 0; r < 16; ++r) {
;             const int t = rb + crow(r, hf_), pos = t & (S_ - 1);
;             const float2 cs = rt64[pos * 32 + l32_];
;             const float x1 = acc[i][0][r], x2 = acc[i][1][r];
;             dst[(size_t)t * pitch + cb + l32_] = f2bf((x1 * cs.x - x2 * cs.y) * sc);
;             dst[(size_t)t * pitch + cb + 32 + l32_] = f2bf((x2 * cs.x + x1 * cs.y) * sc);
	v_mul_f32_e32 v246, v56, v225
	v_mul_f32_e32 v247, v40, v225
	v_fma_f32 v40, v40, v224, -v246
	v_fma_f32 v56, v56, v224, v247
	v_mul_f32_e32 v40, s51, v40
	v_mul_f32_e32 v56, s51, v56
	v_mul_f32_e32 v246, v57, v227
	v_mul_f32_e32 v247, v41, v227
	v_fma_f32 v41, v41, v226, -v246
	v_fma_f32 v57, v57, v226, v247
	v_mul_f32_e32 v41, s51, v41
	v_mul_f32_e32 v57, s51, v57
	v_mul_f32_e32 v246, v58, v229
	v_mul_f32_e32 v247, v42, v229
	v_fma_f32 v42, v42, v228, -v246
	v_fma_f32 v58, v58, v228, v247
	v_mul_f32_e32 v42, s51, v42
	v_mul_f32_e32 v58, s51, v58
	v_mul_f32_e32 v246, v59, v231
	v_mul_f32_e32 v247, v43, v231
	v_fma_f32 v43, v43, v230, -v246
	v_fma_f32 v59, v59, v230, v247
	v_mul_f32_e32 v43, s51, v43
	v_mul_f32_e32 v59, s51, v59
	s_add_u32 s8, s36, 0x6000
	s_addc_u32 s9, s37, 0
	global_load_dwordx4 v[224:227], v160, s[8:9] offset:128
	global_load_dwordx4 v[228:231], v160, s[8:9] offset:144
	s_waitcnt vmcnt(14)
	v_mul_f32_e32 v246, v60, v233
	v_mul_f32_e32 v247, v44, v233
	v_fma_f32 v44, v44, v232, -v246
	v_fma_f32 v60, v60, v232, v247
	v_mul_f32_e32 v44, s51, v44
	v_mul_f32_e32 v60, s51, v60
	v_mul_f32_e32 v246, v61, v235
	v_mul_f32_e32 v247, v45, v235
	v_fma_f32 v45, v45, v234, -v246
	v_fma_f32 v61, v61, v234, v247
	v_mul_f32_e32 v45, s51, v45
	v_mul_f32_e32 v61, s51, v61
	v_mul_f32_e32 v246, v62, v237
	v_mul_f32_e32 v247, v46, v237
	v_fma_f32 v46, v46, v236, -v246
	v_fma_f32 v62, v62, v236, v247
	v_mul_f32_e32 v46, s51, v46
	v_mul_f32_e32 v62, s51, v62
	v_mul_f32_e32 v246, v63, v239
	v_mul_f32_e32 v247, v47, v239
	v_fma_f32 v47, v47, v238, -v246
	v_fma_f32 v63, v63, v238, v247
	v_mul_f32_e32 v47, s51, v47
	v_mul_f32_e32 v63, s51, v63
	s_add_u32 s8, s36, 0x6000
	s_addc_u32 s9, s37, 0
	global_load_dwordx4 v[232:235], v160, s[8:9] offset:192
	global_load_dwordx4 v[236:239], v160, s[8:9] offset:208
	v_cvt_pk_bf16_f32 v244, v32, v33
	v_cvt_pk_bf16_f32 v245, v34, v35
	ds_write_b64 v178, v[244:245]
	v_cvt_pk_bf16_f32 v240, v36, v37
	v_cvt_pk_bf16_f32 v241, v38, v39
	ds_write_b64 v179, v[240:241]
	v_cvt_pk_bf16_f32 v242, v40, v41
	v_cvt_pk_bf16_f32 v243, v42, v43
	ds_write_b64 v180, v[242:243]
	v_cvt_pk_bf16_f32 v244, v44, v45
	v_cvt_pk_bf16_f32 v245, v46, v47
	ds_write_b64 v181, v[244:245]
	v_cvt_pk_bf16_f32 v240, v48, v49
	v_cvt_pk_bf16_f32 v241, v50, v51
	ds_write_b64 v188, v[240:241]
	v_cvt_pk_bf16_f32 v242, v52, v53
	v_cvt_pk_bf16_f32 v243, v54, v55
	ds_write_b64 v189, v[242:243]
	v_cvt_pk_bf16_f32 v244, v56, v57
	v_cvt_pk_bf16_f32 v245, v58, v59
	ds_write_b64 v190, v[244:245]
	v_cvt_pk_bf16_f32 v240, v60, v61
	v_cvt_pk_bf16_f32 v241, v62, v63
	ds_write_b64 v191, v[240:241]
	ds_read_b128 v[32:35], v194
	ds_read_b128 v[36:39], v194 offset:1024
	ds_read_b128 v[40:43], v194 offset:2048
	ds_read_b128 v[44:47], v194 offset:3072
	s_waitcnt lgkmcnt(12)
	global_store_dwordx4 v196, v[0:3], s[38:39] nt
	s_add_u32 s38, s38, 0x2000
	s_addc_u32 s39, s39, 0
	global_store_dwordx4 v196, v[4:7], s[38:39] nt
	s_add_u32 s38, s38, 0x2000
	s_addc_u32 s39, s39, 0
	global_store_dwordx4 v196, v[8:11], s[38:39] nt
	s_add_u32 s38, s38, 0x2000
	s_addc_u32 s39, s39, 0
	global_store_dwordx4 v196, v[12:15], s[38:39] nt
	s_add_u32 s38, s38, 0x2000
	s_addc_u32 s39, s39, 0
	s_waitcnt vmcnt(18)
	v_mul_f32_e32 v246, v80, v129
	v_mul_f32_e32 v247, v64, v129
	v_fma_f32 v64, v64, v128, -v246
	v_fma_f32 v80, v80, v128, v247
	v_mul_f32_e32 v64, s51, v64
	v_mul_f32_e32 v80, s51, v80
	v_mul_f32_e32 v246, v81, v131
	v_mul_f32_e32 v247, v65, v131
	v_fma_f32 v65, v65, v130, -v246
	v_fma_f32 v81, v81, v130, v247
	v_mul_f32_e32 v65, s51, v65
	v_mul_f32_e32 v81, s51, v81
	v_mul_f32_e32 v246, v82, v133
	v_mul_f32_e32 v247, v66, v133
	v_fma_f32 v66, v66, v132, -v246
	v_fma_f32 v82, v82, v132, v247
	v_mul_f32_e32 v66, s51, v66
	v_mul_f32_e32 v82, s51, v82
	v_mul_f32_e32 v246, v83, v135
	v_mul_f32_e32 v247, v67, v135
	v_fma_f32 v67, v67, v134, -v246
	v_fma_f32 v83, v83, v134, v247
	v_mul_f32_e32 v67, s51, v67
	v_mul_f32_e32 v83, s51, v83
	s_waitcnt vmcnt(16)
	v_mul_f32_e32 v246, v84, v137
	v_mul_f32_e32 v247, v68, v137
	v_fma_f32 v68, v68, v136, -v246
	v_fma_f32 v84, v84, v136, v247
	v_mul_f32_e32 v68, s51, v68
	v_mul_f32_e32 v84, s51, v84
	v_mul_f32_e32 v246, v85, v139
	v_mul_f32_e32 v247, v69, v139
	v_fma_f32 v69, v69, v138, -v246
	v_fma_f32 v85, v85, v138, v247
	v_mul_f32_e32 v69, s51, v69
	v_mul_f32_e32 v85, s51, v85
	v_mul_f32_e32 v246, v86, v141
	v_mul_f32_e32 v247, v70, v141
	v_fma_f32 v70, v70, v140, -v246
	v_fma_f32 v86, v86, v140, v247
	v_mul_f32_e32 v70, s51, v70
	v_mul_f32_e32 v86, s51, v86
	v_mul_f32_e32 v246, v87, v143
	v_mul_f32_e32 v247, v71, v143
	v_fma_f32 v71, v71, v142, -v246
	v_fma_f32 v87, v87, v142, v247
	v_mul_f32_e32 v71, s51, v71
	v_mul_f32_e32 v87, s51, v87
	s_waitcnt vmcnt(14)
	v_mul_f32_e32 v246, v88, v145
	v_mul_f32_e32 v247, v72, v145
	v_fma_f32 v72, v72, v144, -v246
	v_fma_f32 v88, v88, v144, v247
	v_mul_f32_e32 v72, s51, v72
	v_mul_f32_e32 v88, s51, v88
	v_mul_f32_e32 v246, v89, v147
	v_mul_f32_e32 v247, v73, v147
	v_fma_f32 v73, v73, v146, -v246
	v_fma_f32 v89, v89, v146, v247
	v_mul_f32_e32 v73, s51, v73
	v_mul_f32_e32 v89, s51, v89
	v_mul_f32_e32 v246, v90, v149
	v_mul_f32_e32 v247, v74, v149
	v_fma_f32 v74, v74, v148, -v246
	v_fma_f32 v90, v90, v148, v247
	v_mul_f32_e32 v74, s51, v74
	v_mul_f32_e32 v90, s51, v90
	v_mul_f32_e32 v246, v91, v151
	v_mul_f32_e32 v247, v75, v151
	v_fma_f32 v75, v75, v150, -v246
	v_fma_f32 v91, v91, v150, v247
	v_mul_f32_e32 v75, s51, v75
	v_mul_f32_e32 v91, s51, v91
	s_waitcnt vmcnt(12)
; DI int crow(int r, int hf) { return (r & 3) + 8 * (r >> 2) + 4 * hf; }
; DI void att_in_phase(const Params& p, int j, char* smem) {
;     ...
;         } else if (C64 < 1280) {
;           const bool isq = C64 < 1152;
;           u16* dst = isq ? SQ : SK; const int pitch = isq ? 512 : 128; const int cb = isq ? (C64 - 640) : (C64 - 1152);
;           const float sc = isq ? SWA_QSCALE : 1.f;
; #pragma unroll
;           for (int r = 0; r < 16; ++r) {
;             const int t = rb + crow(r, hf_), pos = t & (S_ - 1);
;             const float2 cs = rt64[pos * 32 + l32_];
;             const float x1 = acc[i][0][r], x2 = acc[i][1][r];
;             dst[(size_t)t * pitch + cb + l32_] = f2bf((x1 * cs.x - x2 * cs.y) * sc);
;             dst[(size_t)t * pitch + cb + 32 + l32_] = f2bf((x2 * cs.x + x1 * cs.y) * sc);
	v_mul_f32_e32 v246, v92, v153
	v_mul_f32_e32 v247, v76, v153
	v_fma_f32 v76, v76, v152, -v246
	v_fma_f32 v92, v92, v152, v247
	v_mul_f32_e32 v76, s51, v76
	v_mul_f32_e32 v92, s51, v92
	v_mul_f32_e32 v246, v93, v155
	v_mul_f32_e32 v247, v77, v155
	v_fma_f32 v77, v77, v154, -v246
	v_fma_f32 v93, v93, v154, v247
	v_mul_f32_e32 v77, s51, v77
	v_mul_f32_e32 v93, s51, v93
	v_mul_f32_e32 v246, v94, v157
	v_mul_f32_e32 v247, v78, v157
	v_fma_f32 v78, v78, v156, -v246
	v_fma_f32 v94, v94, v156, v247
	v_mul_f32_e32 v78, s51, v78
	v_mul_f32_e32 v94, s51, v94
	v_mul_f32_e32 v246, v95, v159
	v_mul_f32_e32 v247, v79, v159
	v_fma_f32 v79, v79, v158, -v246
	v_fma_f32 v95, v95, v158, v247
	v_mul_f32_e32 v79, s51, v79
	v_mul_f32_e32 v95, s51, v95
	v_cvt_pk_bf16_f32 v242, v64, v65
	v_cvt_pk_bf16_f32 v243, v66, v67
	ds_write_b64 v178, v[242:243]
	v_cvt_pk_bf16_f32 v244, v68, v69
	v_cvt_pk_bf16_f32 v245, v70, v71
	ds_write_b64 v179, v[244:245]
	v_cvt_pk_bf16_f32 v240, v72, v73
	v_cvt_pk_bf16_f32 v241, v74, v75
	ds_write_b64 v180, v[240:241]
	v_cvt_pk_bf16_f32 v242, v76, v77
	v_cvt_pk_bf16_f32 v243, v78, v79
	ds_write_b64 v181, v[242:243]
	v_cvt_pk_bf16_f32 v244, v80, v81
	v_cvt_pk_bf16_f32 v245, v82, v83
	ds_write_b64 v188, v[244:245]
	v_cvt_pk_bf16_f32 v240, v84, v85
	v_cvt_pk_bf16_f32 v241, v86, v87
	ds_write_b64 v189, v[240:241]
	v_cvt_pk_bf16_f32 v242, v88, v89
	v_cvt_pk_bf16_f32 v243, v90, v91
	ds_write_b64 v190, v[242:243]
	v_cvt_pk_bf16_f32 v244, v92, v93
	v_cvt_pk_bf16_f32 v245, v94, v95
	ds_write_b64 v191, v[244:245]
	ds_read_b128 v[64:67], v194
	ds_read_b128 v[68:71], v194 offset:1024
	ds_read_b128 v[72:75], v194 offset:2048
	ds_read_b128 v[76:79], v194 offset:3072
	s_waitcnt lgkmcnt(12)
	global_store_dwordx4 v196, v[32:35], s[38:39] nt
	s_add_u32 s38, s38, 0x2000
	s_addc_u32 s39, s39, 0
	global_store_dwordx4 v196, v[36:39], s[38:39] nt
	s_add_u32 s38, s38, 0x2000
	s_addc_u32 s39, s39, 0
	global_store_dwordx4 v196, v[40:43], s[38:39] nt
	s_add_u32 s38, s38, 0x2000
	s_addc_u32 s39, s39, 0
	global_store_dwordx4 v196, v[44:47], s[38:39] nt
	s_add_u32 s38, s38, 0x2000
	s_addc_u32 s39, s39, 0
	s_waitcnt vmcnt(14)
	v_mul_f32_e32 v246, v112, v163
	v_mul_f32_e32 v247, v96, v163
	v_fma_f32 v96, v96, v162, -v246
	v_fma_f32 v112, v112, v162, v247
	v_mul_f32_e32 v96, s51, v96
	v_mul_f32_e32 v112, s51, v112
	v_mul_f32_e32 v246, v113, v165
	v_mul_f32_e32 v247, v97, v165
	v_fma_f32 v97, v97, v164, -v246
	v_fma_f32 v113, v113, v164, v247
	v_mul_f32_e32 v97, s51, v97
	v_mul_f32_e32 v113, s51, v113
	v_mul_f32_e32 v246, v114, v167
	v_mul_f32_e32 v247, v98, v167
	v_fma_f32 v98, v98, v166, -v246
	v_fma_f32 v114, v114, v166, v247
	v_mul_f32_e32 v98, s51, v98
	v_mul_f32_e32 v114, s51, v114
	v_mul_f32_e32 v246, v115, v169
	v_mul_f32_e32 v247, v99, v169
	v_fma_f32 v99, v99, v168, -v246
	v_fma_f32 v115, v115, v168, v247
	v_mul_f32_e32 v99, s51, v99
	v_mul_f32_e32 v115, s51, v115
	s_waitcnt vmcnt(12)
	v_mul_f32_e32 v246, v116, v171
	v_mul_f32_e32 v247, v100, v171
	v_fma_f32 v100, v100, v170, -v246
	v_fma_f32 v116, v116, v170, v247
	v_mul_f32_e32 v100, s51, v100
	v_mul_f32_e32 v116, s51, v116
	v_mul_f32_e32 v246, v117, v173
	v_mul_f32_e32 v247, v101, v173
	v_fma_f32 v101, v101, v172, -v246
	v_fma_f32 v117, v117, v172, v247
	v_mul_f32_e32 v101, s51, v101
	v_mul_f32_e32 v117, s51, v117
	v_mul_f32_e32 v246, v118, v175
	v_mul_f32_e32 v247, v102, v175
	v_fma_f32 v102, v102, v174, -v246
	v_fma_f32 v118, v118, v174, v247
	v_mul_f32_e32 v102, s51, v102
	v_mul_f32_e32 v118, s51, v118
	v_mul_f32_e32 v246, v119, v177
	v_mul_f32_e32 v247, v103, v177
	v_fma_f32 v103, v103, v176, -v246
	v_fma_f32 v119, v119, v176, v247
	v_mul_f32_e32 v103, s51, v103
	v_mul_f32_e32 v119, s51, v119
	s_waitcnt vmcnt(10)
	v_mul_f32_e32 v246, v120, v225
	v_mul_f32_e32 v247, v104, v225
	v_fma_f32 v104, v104, v224, -v246
	v_fma_f32 v120, v120, v224, v247
	v_mul_f32_e32 v104, s51, v104
	v_mul_f32_e32 v120, s51, v120
	v_mul_f32_e32 v246, v121, v227
	v_mul_f32_e32 v247, v105, v227
	v_fma_f32 v105, v105, v226, -v246
	v_fma_f32 v121, v121, v226, v247
	v_mul_f32_e32 v105, s51, v105
	v_mul_f32_e32 v121, s51, v121
	v_mul_f32_e32 v246, v122, v229
	v_mul_f32_e32 v247, v106, v229
	v_fma_f32 v106, v106, v228, -v246
	v_fma_f32 v122, v122, v228, v247
	v_mul_f32_e32 v106, s51, v106
	v_mul_f32_e32 v122, s51, v122
	v_mul_f32_e32 v246, v123, v231
	v_mul_f32_e32 v247, v107, v231
	v_fma_f32 v107, v107, v230, -v246
	v_fma_f32 v123, v123, v230, v247
	v_mul_f32_e32 v107, s51, v107
	v_mul_f32_e32 v123, s51, v123
	s_waitcnt vmcnt(8)
	v_mul_f32_e32 v246, v124, v233
	v_mul_f32_e32 v247, v108, v233
	v_fma_f32 v108, v108, v232, -v246
	v_fma_f32 v124, v124, v232, v247
	v_mul_f32_e32 v108, s51, v108
	v_mul_f32_e32 v124, s51, v124
	v_mul_f32_e32 v246, v125, v235
	v_mul_f32_e32 v247, v109, v235
	v_fma_f32 v109, v109, v234, -v246
	v_fma_f32 v125, v125, v234, v247
	v_mul_f32_e32 v109, s51, v109
	v_mul_f32_e32 v125, s51, v125
	v_mul_f32_e32 v246, v126, v237
	v_mul_f32_e32 v247, v110, v237
	v_fma_f32 v110, v110, v236, -v246
	v_fma_f32 v126, v126, v236, v247
	v_mul_f32_e32 v110, s51, v110
	v_mul_f32_e32 v126, s51, v126
	v_mul_f32_e32 v246, v127, v239
	v_mul_f32_e32 v247, v111, v239
	v_fma_f32 v111, v111, v238, -v246
	v_fma_f32 v127, v127, v238, v247
	v_mul_f32_e32 v111, s51, v111
	v_mul_f32_e32 v127, s51, v127
	v_cvt_pk_bf16_f32 v240, v96, v97
	v_cvt_pk_bf16_f32 v241, v98, v99
	ds_write_b64 v178, v[240:241]
	v_cvt_pk_bf16_f32 v242, v100, v101
	v_cvt_pk_bf16_f32 v243, v102, v103
	ds_write_b64 v179, v[242:243]
	v_cvt_pk_bf16_f32 v244, v104, v105
	v_cvt_pk_bf16_f32 v245, v106, v107
	ds_write_b64 v180, v[244:245]
	v_cvt_pk_bf16_f32 v240, v108, v109
	v_cvt_pk_bf16_f32 v241, v110, v111
	ds_write_b64 v181, v[240:241]
	v_cvt_pk_bf16_f32 v242, v112, v113
	v_cvt_pk_bf16_f32 v243, v114, v115
	ds_write_b64 v188, v[242:243]
	v_cvt_pk_bf16_f32 v244, v116, v117
	v_cvt_pk_bf16_f32 v245, v118, v119
	ds_write_b64 v189, v[244:245]
	v_cvt_pk_bf16_f32 v240, v120, v121
	v_cvt_pk_bf16_f32 v241, v122, v123
	ds_write_b64 v190, v[240:241]
	v_cvt_pk_bf16_f32 v242, v124, v125
	v_cvt_pk_bf16_f32 v243, v126, v127
	ds_write_b64 v191, v[242:243]
	ds_read_b128 v[96:99], v194
	ds_read_b128 v[100:103], v194 offset:1024
	ds_read_b128 v[104:107], v194 offset:2048
	ds_read_b128 v[108:111], v194 offset:3072
	s_waitcnt lgkmcnt(12)
; DI int crow(int r, int hf) { return (r & 3) + 8 * (r >> 2) + 4 * hf; }
; DI void att_in_phase(const Params& p, int j, char* smem) {
;     ...
;         } else if (C64 < 1280) {
;           const bool isq = C64 < 1152;
;           u16* dst = isq ? SQ : SK; const int pitch = isq ? 512 : 128; const int cb = isq ? (C64 - 640) : (C64 - 1152);
;           const float sc = isq ? SWA_QSCALE : 1.f;
; #pragma unroll
;           for (int r = 0; r < 16; ++r) {
;             const int t = rb + crow(r, hf_), pos = t & (S_ - 1);
;             const float2 cs = rt64[pos * 32 + l32_];
;             const float x1 = acc[i][0][r], x2 = acc[i][1][r];
;             dst[(size_t)t * pitch + cb + l32_] = f2bf((x1 * cs.x - x2 * cs.y) * sc);
;             dst[(size_t)t * pitch + cb + 32 + l32_] = f2bf((x2 * cs.x + x1 * cs.y) * sc);
	global_store_dwordx4 v196, v[64:67], s[38:39] nt
	s_add_u32 s38, s38, 0x2000
	s_addc_u32 s39, s39, 0
	global_store_dwordx4 v196, v[68:71], s[38:39] nt
	s_add_u32 s38, s38, 0x2000
	s_addc_u32 s39, s39, 0
	global_store_dwordx4 v196, v[72:75], s[38:39] nt
	s_add_u32 s38, s38, 0x2000
	s_addc_u32 s39, s39, 0
	global_store_dwordx4 v196, v[76:79], s[38:39] nt
	s_add_u32 s38, s38, 0x2000
	s_addc_u32 s39, s39, 0
	s_waitcnt lgkmcnt(0)
	global_store_dwordx4 v196, v[96:99], s[38:39] nt
	s_add_u32 s38, s38, 0x2000
	s_addc_u32 s39, s39, 0
	global_store_dwordx4 v196, v[100:103], s[38:39] nt
	s_add_u32 s38, s38, 0x2000
	s_addc_u32 s39, s39, 0
	global_store_dwordx4 v196, v[104:107], s[38:39] nt
	s_add_u32 s38, s38, 0x2000
	s_addc_u32 s39, s39, 0
	global_store_dwordx4 v196, v[108:111], s[38:39] nt
	s_branch .Lai_epi_done
.Lai_epi_sk:
	s_sub_u32 s9, s20, 18
	s_lshl_b32 s9, s9, 7
	s_mul_i32 s8, s52, 0x100
	s_add_u32 s8, s8, s9
	s_add_u32 s38, s0, s8
	s_addc_u32 s39, s1, 0
	s_add_u32 s38, s38, 0x19c24100
	s_addc_u32 s39, s39, 0
	s_mov_b32 s51, 1.0
	s_add_u32 s8, s36, 0x0
	s_addc_u32 s9, s37, 0
	global_load_dwordx4 v[128:131], v160, s[8:9]
	global_load_dwordx4 v[132:135], v160, s[8:9] offset:16
	s_add_u32 s8, s36, 0x0
	s_addc_u32 s9, s37, 0
	global_load_dwordx4 v[136:139], v160, s[8:9] offset:64
	global_load_dwordx4 v[140:143], v160, s[8:9] offset:80
	s_add_u32 s8, s36, 0x0
	s_addc_u32 s9, s37, 0
	global_load_dwordx4 v[144:147], v160, s[8:9] offset:128
	global_load_dwordx4 v[148:151], v160, s[8:9] offset:144
	s_add_u32 s8, s36, 0x0
	s_addc_u32 s9, s37, 0
	global_load_dwordx4 v[152:155], v160, s[8:9] offset:192
	global_load_dwordx4 v[156:159], v160, s[8:9] offset:208
	s_add_u32 s8, s36, 0x2000
	s_addc_u32 s9, s37, 0
	global_load_dwordx4 v[162:165], v160, s[8:9]
	global_load_dwordx4 v[166:169], v160, s[8:9] offset:16
	s_add_u32 s8, s36, 0x2000
	s_addc_u32 s9, s37, 0
	global_load_dwordx4 v[170:173], v160, s[8:9] offset:64
	global_load_dwordx4 v[174:177], v160, s[8:9] offset:80
	s_add_u32 s8, s36, 0x2000
	s_addc_u32 s9, s37, 0
	global_load_dwordx4 v[224:227], v160, s[8:9] offset:128
	global_load_dwordx4 v[228:231], v160, s[8:9] offset:144
	s_add_u32 s8, s36, 0x2000
	s_addc_u32 s9, s37, 0
	global_load_dwordx4 v[232:235], v160, s[8:9] offset:192
	global_load_dwordx4 v[236:239], v160, s[8:9] offset:208
	s_waitcnt vmcnt(14)
	v_mul_f32_e32 v246, v16, v129
	v_mul_f32_e32 v247, v0, v129
	v_fma_f32 v0, v0, v128, -v246
	v_fma_f32 v16, v16, v128, v247
	v_mul_f32_e32 v0, s51, v0
	v_mul_f32_e32 v16, s51, v16
	v_mul_f32_e32 v246, v17, v131
	v_mul_f32_e32 v247, v1, v131
	v_fma_f32 v1, v1, v130, -v246
	v_fma_f32 v17, v17, v130, v247
	v_mul_f32_e32 v1, s51, v1
	v_mul_f32_e32 v17, s51, v17
	v_mul_f32_e32 v246, v18, v133
	v_mul_f32_e32 v247, v2, v133
	v_fma_f32 v2, v2, v132, -v246
	v_fma_f32 v18, v18, v132, v247
	v_mul_f32_e32 v2, s51, v2
	v_mul_f32_e32 v18, s51, v18
	v_mul_f32_e32 v246, v19, v135
	v_mul_f32_e32 v247, v3, v135
	v_fma_f32 v3, v3, v134, -v246
	v_fma_f32 v19, v19, v134, v247
	v_mul_f32_e32 v3, s51, v3
	v_mul_f32_e32 v19, s51, v19
	s_add_u32 s8, s36, 0x4000
	s_addc_u32 s9, s37, 0
	global_load_dwordx4 v[128:131], v160, s[8:9]
	global_load_dwordx4 v[132:135], v160, s[8:9] offset:16
	s_waitcnt vmcnt(14)
	v_mul_f32_e32 v246, v20, v137
	v_mul_f32_e32 v247, v4, v137
	v_fma_f32 v4, v4, v136, -v246
	v_fma_f32 v20, v20, v136, v247
	v_mul_f32_e32 v4, s51, v4
	v_mul_f32_e32 v20, s51, v20
	v_mul_f32_e32 v246, v21, v139
	v_mul_f32_e32 v247, v5, v139
	v_fma_f32 v5, v5, v138, -v246
	v_fma_f32 v21, v21, v138, v247
	v_mul_f32_e32 v5, s51, v5
	v_mul_f32_e32 v21, s51, v21
	v_mul_f32_e32 v246, v22, v141
	v_mul_f32_e32 v247, v6, v141
	v_fma_f32 v6, v6, v140, -v246
	v_fma_f32 v22, v22, v140, v247
	v_mul_f32_e32 v6, s51, v6
	v_mul_f32_e32 v22, s51, v22
	v_mul_f32_e32 v246, v23, v143
	v_mul_f32_e32 v247, v7, v143
	v_fma_f32 v7, v7, v142, -v246
	v_fma_f32 v23, v23, v142, v247
	v_mul_f32_e32 v7, s51, v7
	v_mul_f32_e32 v23, s51, v23
	s_add_u32 s8, s36, 0x4000
	s_addc_u32 s9, s37, 0
	global_load_dwordx4 v[136:139], v160, s[8:9] offset:64
	global_load_dwordx4 v[140:143], v160, s[8:9] offset:80
	s_waitcnt vmcnt(14)
	v_mul_f32_e32 v246, v24, v145
	v_mul_f32_e32 v247, v8, v145
	v_fma_f32 v8, v8, v144, -v246
	v_fma_f32 v24, v24, v144, v247
	v_mul_f32_e32 v8, s51, v8
	v_mul_f32_e32 v24, s51, v24
	v_mul_f32_e32 v246, v25, v147
	v_mul_f32_e32 v247, v9, v147
	v_fma_f32 v9, v9, v146, -v246
	v_fma_f32 v25, v25, v146, v247
	v_mul_f32_e32 v9, s51, v9
	v_mul_f32_e32 v25, s51, v25
	v_mul_f32_e32 v246, v26, v149
	v_mul_f32_e32 v247, v10, v149
	v_fma_f32 v10, v10, v148, -v246
	v_fma_f32 v26, v26, v148, v247
	v_mul_f32_e32 v10, s51, v10
	v_mul_f32_e32 v26, s51, v26
	v_mul_f32_e32 v246, v27, v151
	v_mul_f32_e32 v247, v11, v151
	v_fma_f32 v11, v11, v150, -v246
	v_fma_f32 v27, v27, v150, v247
	v_mul_f32_e32 v11, s51, v11
	v_mul_f32_e32 v27, s51, v27
	s_add_u32 s8, s36, 0x4000
	s_addc_u32 s9, s37, 0
	global_load_dwordx4 v[144:147], v160, s[8:9] offset:128
	global_load_dwordx4 v[148:151], v160, s[8:9] offset:144
	s_waitcnt vmcnt(14)
; DI int crow(int r, int hf) { return (r & 3) + 8 * (r >> 2) + 4 * hf; }
; DI void att_in_phase(const Params& p, int j, char* smem) {
;     ...
;         } else if (C64 < 1280) {
;           const bool isq = C64 < 1152;
;           u16* dst = isq ? SQ : SK; const int pitch = isq ? 512 : 128; const int cb = isq ? (C64 - 640) : (C64 - 1152);
;           const float sc = isq ? SWA_QSCALE : 1.f;
; #pragma unroll
;           for (int r = 0; r < 16; ++r) {
;             const int t = rb + crow(r, hf_), pos = t & (S_ - 1);
;             const float2 cs = rt64[pos * 32 + l32_];
;             const float x1 = acc[i][0][r], x2 = acc[i][1][r];
;             dst[(size_t)t * pitch + cb + l32_] = f2bf((x1 * cs.x - x2 * cs.y) * sc);
;             dst[(size_t)t * pitch + cb + 32 + l32_] = f2bf((x2 * cs.x + x1 * cs.y) * sc);
	v_mul_f32_e32 v246, v28, v153
	v_mul_f32_e32 v247, v12, v153
	v_fma_f32 v12, v12, v152, -v246
	v_fma_f32 v28, v28, v152, v247
	v_mul_f32_e32 v12, s51, v12
	v_mul_f32_e32 v28, s51, v28
	v_mul_f32_e32 v246, v29, v155
	v_mul_f32_e32 v247, v13, v155
	v_fma_f32 v13, v13, v154, -v246
	v_fma_f32 v29, v29, v154, v247
	v_mul_f32_e32 v13, s51, v13
	v_mul_f32_e32 v29, s51, v29
	v_mul_f32_e32 v246, v30, v157
	v_mul_f32_e32 v247, v14, v157
	v_fma_f32 v14, v14, v156, -v246
	v_fma_f32 v30, v30, v156, v247
	v_mul_f32_e32 v14, s51, v14
	v_mul_f32_e32 v30, s51, v30
	v_mul_f32_e32 v246, v31, v159
	v_mul_f32_e32 v247, v15, v159
	v_fma_f32 v15, v15, v158, -v246
	v_fma_f32 v31, v31, v158, v247
	v_mul_f32_e32 v15, s51, v15
	v_mul_f32_e32 v31, s51, v31
	s_add_u32 s8, s36, 0x4000
	s_addc_u32 s9, s37, 0
	global_load_dwordx4 v[152:155], v160, s[8:9] offset:192
	global_load_dwordx4 v[156:159], v160, s[8:9] offset:208
	v_cvt_pk_bf16_f32 v240, v0, v1
	v_cvt_pk_bf16_f32 v241, v2, v3
	ds_write_b64 v178, v[240:241]
	v_cvt_pk_bf16_f32 v242, v4, v5
	v_cvt_pk_bf16_f32 v243, v6, v7
	ds_write_b64 v179, v[242:243]
	v_cvt_pk_bf16_f32 v244, v8, v9
	v_cvt_pk_bf16_f32 v245, v10, v11
	ds_write_b64 v180, v[244:245]
	v_cvt_pk_bf16_f32 v240, v12, v13
	v_cvt_pk_bf16_f32 v241, v14, v15
	ds_write_b64 v181, v[240:241]
	v_cvt_pk_bf16_f32 v242, v16, v17
	v_cvt_pk_bf16_f32 v243, v18, v19
	ds_write_b64 v188, v[242:243]
	v_cvt_pk_bf16_f32 v244, v20, v21
	v_cvt_pk_bf16_f32 v245, v22, v23
	ds_write_b64 v189, v[244:245]
	v_cvt_pk_bf16_f32 v240, v24, v25
	v_cvt_pk_bf16_f32 v241, v26, v27
	ds_write_b64 v190, v[240:241]
	v_cvt_pk_bf16_f32 v242, v28, v29
	v_cvt_pk_bf16_f32 v243, v30, v31
	ds_write_b64 v191, v[242:243]
	ds_read_b128 v[0:3], v194
	ds_read_b128 v[4:7], v194 offset:1024
	ds_read_b128 v[8:11], v194 offset:2048
	ds_read_b128 v[12:15], v194 offset:3072
	s_waitcnt vmcnt(14)
	v_mul_f32_e32 v246, v48, v163
	v_mul_f32_e32 v247, v32, v163
	v_fma_f32 v32, v32, v162, -v246
	v_fma_f32 v48, v48, v162, v247
	v_mul_f32_e32 v32, s51, v32
	v_mul_f32_e32 v48, s51, v48
	v_mul_f32_e32 v246, v49, v165
	v_mul_f32_e32 v247, v33, v165
	v_fma_f32 v33, v33, v164, -v246
	v_fma_f32 v49, v49, v164, v247
	v_mul_f32_e32 v33, s51, v33
	v_mul_f32_e32 v49, s51, v49
	v_mul_f32_e32 v246, v50, v167
	v_mul_f32_e32 v247, v34, v167
	v_fma_f32 v34, v34, v166, -v246
	v_fma_f32 v50, v50, v166, v247
	v_mul_f32_e32 v34, s51, v34
	v_mul_f32_e32 v50, s51, v50
	v_mul_f32_e32 v246, v51, v169
	v_mul_f32_e32 v247, v35, v169
	v_fma_f32 v35, v35, v168, -v246
	v_fma_f32 v51, v51, v168, v247
	v_mul_f32_e32 v35, s51, v35
	v_mul_f32_e32 v51, s51, v51
	s_add_u32 s8, s36, 0x6000
	s_addc_u32 s9, s37, 0
	global_load_dwordx4 v[162:165], v160, s[8:9]
	global_load_dwordx4 v[166:169], v160, s[8:9] offset:16
	s_waitcnt vmcnt(14)
	v_mul_f32_e32 v246, v52, v171
	v_mul_f32_e32 v247, v36, v171
	v_fma_f32 v36, v36, v170, -v246
	v_fma_f32 v52, v52, v170, v247
	v_mul_f32_e32 v36, s51, v36
	v_mul_f32_e32 v52, s51, v52
	v_mul_f32_e32 v246, v53, v173
	v_mul_f32_e32 v247, v37, v173
	v_fma_f32 v37, v37, v172, -v246
	v_fma_f32 v53, v53, v172, v247
	v_mul_f32_e32 v37, s51, v37
	v_mul_f32_e32 v53, s51, v53
	v_mul_f32_e32 v246, v54, v175
	v_mul_f32_e32 v247, v38, v175
	v_fma_f32 v38, v38, v174, -v246
	v_fma_f32 v54, v54, v174, v247
	v_mul_f32_e32 v38, s51, v38
	v_mul_f32_e32 v54, s51, v54
	v_mul_f32_e32 v246, v55, v177
	v_mul_f32_e32 v247, v39, v177
	v_fma_f32 v39, v39, v176, -v246
	v_fma_f32 v55, v55, v176, v247
	v_mul_f32_e32 v39, s51, v39
	v_mul_f32_e32 v55, s51, v55
	s_add_u32 s8, s36, 0x6000
	s_addc_u32 s9, s37, 0
	global_load_dwordx4 v[170:173], v160, s[8:9] offset:64
	global_load_dwordx4 v[174:177], v160, s[8:9] offset:80
	s_waitcnt vmcnt(14)
	v_mul_f32_e32 v246, v56, v225
	v_mul_f32_e32 v247, v40, v225
	v_fma_f32 v40, v40, v224, -v246
	v_fma_f32 v56, v56, v224, v247
	v_mul_f32_e32 v40, s51, v40
	v_mul_f32_e32 v56, s51, v56
	v_mul_f32_e32 v246, v57, v227
	v_mul_f32_e32 v247, v41, v227
	v_fma_f32 v41, v41, v226, -v246
	v_fma_f32 v57, v57, v226, v247
	v_mul_f32_e32 v41, s51, v41
	v_mul_f32_e32 v57, s51, v57
	v_mul_f32_e32 v246, v58, v229
	v_mul_f32_e32 v247, v42, v229
	v_fma_f32 v42, v42, v228, -v246
	v_fma_f32 v58, v58, v228, v247
	v_mul_f32_e32 v42, s51, v42
	v_mul_f32_e32 v58, s51, v58
	v_mul_f32_e32 v246, v59, v231
	v_mul_f32_e32 v247, v43, v231
	v_fma_f32 v43, v43, v230, -v246
	v_fma_f32 v59, v59, v230, v247
	v_mul_f32_e32 v43, s51, v43
	v_mul_f32_e32 v59, s51, v59
	s_add_u32 s8, s36, 0x6000
	s_addc_u32 s9, s37, 0
	global_load_dwordx4 v[224:227], v160, s[8:9] offset:128
	global_load_dwordx4 v[228:231], v160, s[8:9] offset:144
	s_waitcnt vmcnt(14)
	v_mul_f32_e32 v246, v60, v233
	v_mul_f32_e32 v247, v44, v233
	v_fma_f32 v44, v44, v232, -v246
	v_fma_f32 v60, v60, v232, v247
	v_mul_f32_e32 v44, s51, v44
	v_mul_f32_e32 v60, s51, v60
	v_mul_f32_e32 v246, v61, v235
	v_mul_f32_e32 v247, v45, v235
	v_fma_f32 v45, v45, v234, -v246
	v_fma_f32 v61, v61, v234, v247
	v_mul_f32_e32 v45, s51, v45
	v_mul_f32_e32 v61, s51, v61
	v_mul_f32_e32 v246, v62, v237
	v_mul_f32_e32 v247, v46, v237
	v_fma_f32 v46, v46, v236, -v246
	v_fma_f32 v62, v62, v236, v247
	v_mul_f32_e32 v46, s51, v46
	v_mul_f32_e32 v62, s51, v62
	v_mul_f32_e32 v246, v63, v239
	v_mul_f32_e32 v247, v47, v239
	v_fma_f32 v47, v47, v238, -v246
	v_fma_f32 v63, v63, v238, v247
	v_mul_f32_e32 v47, s51, v47
	v_mul_f32_e32 v63, s51, v63
	s_add_u32 s8, s36, 0x6000
	s_addc_u32 s9, s37, 0
	global_load_dwordx4 v[232:235], v160, s[8:9] offset:192
	global_load_dwordx4 v[236:239], v160, s[8:9] offset:208
	v_cvt_pk_bf16_f32 v244, v32, v33
	v_cvt_pk_bf16_f32 v245, v34, v35
	ds_write_b64 v178, v[244:245]
	v_cvt_pk_bf16_f32 v240, v36, v37
	v_cvt_pk_bf16_f32 v241, v38, v39
	ds_write_b64 v179, v[240:241]
	v_cvt_pk_bf16_f32 v242, v40, v41
	v_cvt_pk_bf16_f32 v243, v42, v43
	ds_write_b64 v180, v[242:243]
	v_cvt_pk_bf16_f32 v244, v44, v45
	v_cvt_pk_bf16_f32 v245, v46, v47
	ds_write_b64 v181, v[244:245]
	v_cvt_pk_bf16_f32 v240, v48, v49
	v_cvt_pk_bf16_f32 v241, v50, v51
	ds_write_b64 v188, v[240:241]
	v_cvt_pk_bf16_f32 v242, v52, v53
	v_cvt_pk_bf16_f32 v243, v54, v55
	ds_write_b64 v189, v[242:243]
	v_cvt_pk_bf16_f32 v244, v56, v57
	v_cvt_pk_bf16_f32 v245, v58, v59
	ds_write_b64 v190, v[244:245]
	v_cvt_pk_bf16_f32 v240, v60, v61
	v_cvt_pk_bf16_f32 v241, v62, v63
	ds_write_b64 v191, v[240:241]
	ds_read_b128 v[32:35], v194
	ds_read_b128 v[36:39], v194 offset:1024
	ds_read_b128 v[40:43], v194 offset:2048
	ds_read_b128 v[44:47], v194 offset:3072
	s_waitcnt lgkmcnt(12)
; DI int crow(int r, int hf) { return (r & 3) + 8 * (r >> 2) + 4 * hf; }
; DI void att_in_phase(const Params& p, int j, char* smem) {
;     ...
;         } else if (C64 < 1280) {
;           const bool isq = C64 < 1152;
;           u16* dst = isq ? SQ : SK; const int pitch = isq ? 512 : 128; const int cb = isq ? (C64 - 640) : (C64 - 1152);
;           const float sc = isq ? SWA_QSCALE : 1.f;
; #pragma unroll
;           for (int r = 0; r < 16; ++r) {
;             const int t = rb + crow(r, hf_), pos = t & (S_ - 1);
;             const float2 cs = rt64[pos * 32 + l32_];
;             const float x1 = acc[i][0][r], x2 = acc[i][1][r];
;             dst[(size_t)t * pitch + cb + l32_] = f2bf((x1 * cs.x - x2 * cs.y) * sc);
;             dst[(size_t)t * pitch + cb + 32 + l32_] = f2bf((x2 * cs.x + x1 * cs.y) * sc);
	global_store_dwordx4 v197, v[0:3], s[38:39] nt
	s_add_u32 s38, s38, 0x800
	s_addc_u32 s39, s39, 0
	global_store_dwordx4 v197, v[4:7], s[38:39] nt
	s_add_u32 s38, s38, 0x800
	s_addc_u32 s39, s39, 0
	global_store_dwordx4 v197, v[8:11], s[38:39] nt
	s_add_u32 s38, s38, 0x800
	s_addc_u32 s39, s39, 0
	global_store_dwordx4 v197, v[12:15], s[38:39] nt
	s_add_u32 s38, s38, 0x800
	s_addc_u32 s39, s39, 0
	s_waitcnt vmcnt(18)
	v_mul_f32_e32 v246, v80, v129
	v_mul_f32_e32 v247, v64, v129
	v_fma_f32 v64, v64, v128, -v246
	v_fma_f32 v80, v80, v128, v247
	v_mul_f32_e32 v64, s51, v64
	v_mul_f32_e32 v80, s51, v80
	v_mul_f32_e32 v246, v81, v131
	v_mul_f32_e32 v247, v65, v131
	v_fma_f32 v65, v65, v130, -v246
	v_fma_f32 v81, v81, v130, v247
	v_mul_f32_e32 v65, s51, v65
	v_mul_f32_e32 v81, s51, v81
	v_mul_f32_e32 v246, v82, v133
	v_mul_f32_e32 v247, v66, v133
	v_fma_f32 v66, v66, v132, -v246
	v_fma_f32 v82, v82, v132, v247
	v_mul_f32_e32 v66, s51, v66
	v_mul_f32_e32 v82, s51, v82
	v_mul_f32_e32 v246, v83, v135
	v_mul_f32_e32 v247, v67, v135
	v_fma_f32 v67, v67, v134, -v246
	v_fma_f32 v83, v83, v134, v247
	v_mul_f32_e32 v67, s51, v67
	v_mul_f32_e32 v83, s51, v83
	s_waitcnt vmcnt(16)
	v_mul_f32_e32 v246, v84, v137
	v_mul_f32_e32 v247, v68, v137
	v_fma_f32 v68, v68, v136, -v246
	v_fma_f32 v84, v84, v136, v247
	v_mul_f32_e32 v68, s51, v68
	v_mul_f32_e32 v84, s51, v84
	v_mul_f32_e32 v246, v85, v139
	v_mul_f32_e32 v247, v69, v139
	v_fma_f32 v69, v69, v138, -v246
	v_fma_f32 v85, v85, v138, v247
	v_mul_f32_e32 v69, s51, v69
	v_mul_f32_e32 v85, s51, v85
	v_mul_f32_e32 v246, v86, v141
	v_mul_f32_e32 v247, v70, v141
	v_fma_f32 v70, v70, v140, -v246
	v_fma_f32 v86, v86, v140, v247
	v_mul_f32_e32 v70, s51, v70
	v_mul_f32_e32 v86, s51, v86
	v_mul_f32_e32 v246, v87, v143
	v_mul_f32_e32 v247, v71, v143
	v_fma_f32 v71, v71, v142, -v246
	v_fma_f32 v87, v87, v142, v247
	v_mul_f32_e32 v71, s51, v71
	v_mul_f32_e32 v87, s51, v87
	s_waitcnt vmcnt(14)
	v_mul_f32_e32 v246, v88, v145
	v_mul_f32_e32 v247, v72, v145
	v_fma_f32 v72, v72, v144, -v246
	v_fma_f32 v88, v88, v144, v247
	v_mul_f32_e32 v72, s51, v72
	v_mul_f32_e32 v88, s51, v88
	v_mul_f32_e32 v246, v89, v147
	v_mul_f32_e32 v247, v73, v147
	v_fma_f32 v73, v73, v146, -v246
	v_fma_f32 v89, v89, v146, v247
	v_mul_f32_e32 v73, s51, v73
	v_mul_f32_e32 v89, s51, v89
	v_mul_f32_e32 v246, v90, v149
	v_mul_f32_e32 v247, v74, v149
	v_fma_f32 v74, v74, v148, -v246
	v_fma_f32 v90, v90, v148, v247
	v_mul_f32_e32 v74, s51, v74
	v_mul_f32_e32 v90, s51, v90
	v_mul_f32_e32 v246, v91, v151
	v_mul_f32_e32 v247, v75, v151
	v_fma_f32 v75, v75, v150, -v246
	v_fma_f32 v91, v91, v150, v247
	v_mul_f32_e32 v75, s51, v75
	v_mul_f32_e32 v91, s51, v91
	s_waitcnt vmcnt(12)
	v_mul_f32_e32 v246, v92, v153
	v_mul_f32_e32 v247, v76, v153
	v_fma_f32 v76, v76, v152, -v246
	v_fma_f32 v92, v92, v152, v247
	v_mul_f32_e32 v76, s51, v76
	v_mul_f32_e32 v92, s51, v92
	v_mul_f32_e32 v246, v93, v155
	v_mul_f32_e32 v247, v77, v155
	v_fma_f32 v77, v77, v154, -v246
	v_fma_f32 v93, v93, v154, v247
	v_mul_f32_e32 v77, s51, v77
	v_mul_f32_e32 v93, s51, v93
	v_mul_f32_e32 v246, v94, v157
	v_mul_f32_e32 v247, v78, v157
	v_fma_f32 v78, v78, v156, -v246
	v_fma_f32 v94, v94, v156, v247
	v_mul_f32_e32 v78, s51, v78
	v_mul_f32_e32 v94, s51, v94
	v_mul_f32_e32 v246, v95, v159
	v_mul_f32_e32 v247, v79, v159
	v_fma_f32 v79, v79, v158, -v246
	v_fma_f32 v95, v95, v158, v247
	v_mul_f32_e32 v79, s51, v79
	v_mul_f32_e32 v95, s51, v95
	v_cvt_pk_bf16_f32 v242, v64, v65
	v_cvt_pk_bf16_f32 v243, v66, v67
	ds_write_b64 v178, v[242:243]
	v_cvt_pk_bf16_f32 v244, v68, v69
	v_cvt_pk_bf16_f32 v245, v70, v71
	ds_write_b64 v179, v[244:245]
	v_cvt_pk_bf16_f32 v240, v72, v73
	v_cvt_pk_bf16_f32 v241, v74, v75
	ds_write_b64 v180, v[240:241]
	v_cvt_pk_bf16_f32 v242, v76, v77
	v_cvt_pk_bf16_f32 v243, v78, v79
	ds_write_b64 v181, v[242:243]
	v_cvt_pk_bf16_f32 v244, v80, v81
	v_cvt_pk_bf16_f32 v245, v82, v83
	ds_write_b64 v188, v[244:245]
	v_cvt_pk_bf16_f32 v240, v84, v85
	v_cvt_pk_bf16_f32 v241, v86, v87
	ds_write_b64 v189, v[240:241]
	v_cvt_pk_bf16_f32 v242, v88, v89
	v_cvt_pk_bf16_f32 v243, v90, v91
	ds_write_b64 v190, v[242:243]
	v_cvt_pk_bf16_f32 v244, v92, v93
	v_cvt_pk_bf16_f32 v245, v94, v95
	ds_write_b64 v191, v[244:245]
	ds_read_b128 v[64:67], v194
	ds_read_b128 v[68:71], v194 offset:1024
	ds_read_b128 v[72:75], v194 offset:2048
	ds_read_b128 v[76:79], v194 offset:3072
	s_waitcnt lgkmcnt(12)
	global_store_dwordx4 v197, v[32:35], s[38:39] nt
	s_add_u32 s38, s38, 0x800
	s_addc_u32 s39, s39, 0
	global_store_dwordx4 v197, v[36:39], s[38:39] nt
	s_add_u32 s38, s38, 0x800
	s_addc_u32 s39, s39, 0
	global_store_dwordx4 v197, v[40:43], s[38:39] nt
	s_add_u32 s38, s38, 0x800
	s_addc_u32 s39, s39, 0
	global_store_dwordx4 v197, v[44:47], s[38:39] nt
	s_add_u32 s38, s38, 0x800
	s_addc_u32 s39, s39, 0
	s_waitcnt vmcnt(14)
	v_mul_f32_e32 v246, v112, v163
	v_mul_f32_e32 v247, v96, v163
	v_fma_f32 v96, v96, v162, -v246
	v_fma_f32 v112, v112, v162, v247
	v_mul_f32_e32 v96, s51, v96
	v_mul_f32_e32 v112, s51, v112
	v_mul_f32_e32 v246, v113, v165
	v_mul_f32_e32 v247, v97, v165
	v_fma_f32 v97, v97, v164, -v246
	v_fma_f32 v113, v113, v164, v247
	v_mul_f32_e32 v97, s51, v97
	v_mul_f32_e32 v113, s51, v113
	v_mul_f32_e32 v246, v114, v167
	v_mul_f32_e32 v247, v98, v167
	v_fma_f32 v98, v98, v166, -v246
	v_fma_f32 v114, v114, v166, v247
	v_mul_f32_e32 v98, s51, v98
	v_mul_f32_e32 v114, s51, v114
	v_mul_f32_e32 v246, v115, v169
	v_mul_f32_e32 v247, v99, v169
	v_fma_f32 v99, v99, v168, -v246
	v_fma_f32 v115, v115, v168, v247
	v_mul_f32_e32 v99, s51, v99
	v_mul_f32_e32 v115, s51, v115
	s_waitcnt vmcnt(12)
; DI int crow(int r, int hf) { return (r & 3) + 8 * (r >> 2) + 4 * hf; }
; DI void att_in_phase(const Params& p, int j, char* smem) {
;     ...
;         } else if (C64 < 1280) {
;           const bool isq = C64 < 1152;
;           u16* dst = isq ? SQ : SK; const int pitch = isq ? 512 : 128; const int cb = isq ? (C64 - 640) : (C64 - 1152);
;           const float sc = isq ? SWA_QSCALE : 1.f;
; #pragma unroll
;           for (int r = 0; r < 16; ++r) {
;             const int t = rb + crow(r, hf_), pos = t & (S_ - 1);
;             const float2 cs = rt64[pos * 32 + l32_];
;             const float x1 = acc[i][0][r], x2 = acc[i][1][r];
;             dst[(size_t)t * pitch + cb + l32_] = f2bf((x1 * cs.x - x2 * cs.y) * sc);
;             dst[(size_t)t * pitch + cb + 32 + l32_] = f2bf((x2 * cs.x + x1 * cs.y) * sc);
;           }
;         } else if (C64 < 1408) {
; #pragma unroll
;           for (int jn = 0; jn < 2; ++jn)
; #pragma unroll
;             for (int r = 0; r < 16; ++r) SV[(size_t)(rb + crow(r, hf_)) * 128 + (C64 - 1280) + jn * 32 + l32_] = f2bf(acc[i][jn][r]);
	v_mul_f32_e32 v246, v116, v171
	v_mul_f32_e32 v247, v100, v171
	v_fma_f32 v100, v100, v170, -v246
	v_fma_f32 v116, v116, v170, v247
	v_mul_f32_e32 v100, s51, v100
	v_mul_f32_e32 v116, s51, v116
	v_mul_f32_e32 v246, v117, v173
	v_mul_f32_e32 v247, v101, v173
	v_fma_f32 v101, v101, v172, -v246
	v_fma_f32 v117, v117, v172, v247
	v_mul_f32_e32 v101, s51, v101
	v_mul_f32_e32 v117, s51, v117
	v_mul_f32_e32 v246, v118, v175
	v_mul_f32_e32 v247, v102, v175
	v_fma_f32 v102, v102, v174, -v246
	v_fma_f32 v118, v118, v174, v247
	v_mul_f32_e32 v102, s51, v102
	v_mul_f32_e32 v118, s51, v118
	v_mul_f32_e32 v246, v119, v177
	v_mul_f32_e32 v247, v103, v177
	v_fma_f32 v103, v103, v176, -v246
	v_fma_f32 v119, v119, v176, v247
	v_mul_f32_e32 v103, s51, v103
	v_mul_f32_e32 v119, s51, v119
	s_waitcnt vmcnt(10)
	v_mul_f32_e32 v246, v120, v225
	v_mul_f32_e32 v247, v104, v225
	v_fma_f32 v104, v104, v224, -v246
	v_fma_f32 v120, v120, v224, v247
	v_mul_f32_e32 v104, s51, v104
	v_mul_f32_e32 v120, s51, v120
	v_mul_f32_e32 v246, v121, v227
	v_mul_f32_e32 v247, v105, v227
	v_fma_f32 v105, v105, v226, -v246
	v_fma_f32 v121, v121, v226, v247
	v_mul_f32_e32 v105, s51, v105
	v_mul_f32_e32 v121, s51, v121
	v_mul_f32_e32 v246, v122, v229
	v_mul_f32_e32 v247, v106, v229
	v_fma_f32 v106, v106, v228, -v246
	v_fma_f32 v122, v122, v228, v247
	v_mul_f32_e32 v106, s51, v106
	v_mul_f32_e32 v122, s51, v122
	v_mul_f32_e32 v246, v123, v231
	v_mul_f32_e32 v247, v107, v231
	v_fma_f32 v107, v107, v230, -v246
	v_fma_f32 v123, v123, v230, v247
	v_mul_f32_e32 v107, s51, v107
	v_mul_f32_e32 v123, s51, v123
	s_waitcnt vmcnt(8)
	v_mul_f32_e32 v246, v124, v233
	v_mul_f32_e32 v247, v108, v233
	v_fma_f32 v108, v108, v232, -v246
	v_fma_f32 v124, v124, v232, v247
	v_mul_f32_e32 v108, s51, v108
	v_mul_f32_e32 v124, s51, v124
	v_mul_f32_e32 v246, v125, v235
	v_mul_f32_e32 v247, v109, v235
	v_fma_f32 v109, v109, v234, -v246
	v_fma_f32 v125, v125, v234, v247
	v_mul_f32_e32 v109, s51, v109
	v_mul_f32_e32 v125, s51, v125
	v_mul_f32_e32 v246, v126, v237
	v_mul_f32_e32 v247, v110, v237
	v_fma_f32 v110, v110, v236, -v246
	v_fma_f32 v126, v126, v236, v247
	v_mul_f32_e32 v110, s51, v110
	v_mul_f32_e32 v126, s51, v126
	v_mul_f32_e32 v246, v127, v239
	v_mul_f32_e32 v247, v111, v239
	v_fma_f32 v111, v111, v238, -v246
	v_fma_f32 v127, v127, v238, v247
	v_mul_f32_e32 v111, s51, v111
	v_mul_f32_e32 v127, s51, v127
	v_cvt_pk_bf16_f32 v240, v96, v97
	v_cvt_pk_bf16_f32 v241, v98, v99
	ds_write_b64 v178, v[240:241]
	v_cvt_pk_bf16_f32 v242, v100, v101
	v_cvt_pk_bf16_f32 v243, v102, v103
	ds_write_b64 v179, v[242:243]
	v_cvt_pk_bf16_f32 v244, v104, v105
	v_cvt_pk_bf16_f32 v245, v106, v107
	ds_write_b64 v180, v[244:245]
	v_cvt_pk_bf16_f32 v240, v108, v109
	v_cvt_pk_bf16_f32 v241, v110, v111
	ds_write_b64 v181, v[240:241]
	v_cvt_pk_bf16_f32 v242, v112, v113
	v_cvt_pk_bf16_f32 v243, v114, v115
	ds_write_b64 v188, v[242:243]
	v_cvt_pk_bf16_f32 v244, v116, v117
	v_cvt_pk_bf16_f32 v245, v118, v119
	ds_write_b64 v189, v[244:245]
	v_cvt_pk_bf16_f32 v240, v120, v121
	v_cvt_pk_bf16_f32 v241, v122, v123
	ds_write_b64 v190, v[240:241]
	v_cvt_pk_bf16_f32 v242, v124, v125
	v_cvt_pk_bf16_f32 v243, v126, v127
	ds_write_b64 v191, v[242:243]
	ds_read_b128 v[96:99], v194
	ds_read_b128 v[100:103], v194 offset:1024
	ds_read_b128 v[104:107], v194 offset:2048
	ds_read_b128 v[108:111], v194 offset:3072
	s_waitcnt lgkmcnt(12)
	global_store_dwordx4 v197, v[64:67], s[38:39] nt
	s_add_u32 s38, s38, 0x800
	s_addc_u32 s39, s39, 0
	global_store_dwordx4 v197, v[68:71], s[38:39] nt
	s_add_u32 s38, s38, 0x800
	s_addc_u32 s39, s39, 0
	global_store_dwordx4 v197, v[72:75], s[38:39] nt
	s_add_u32 s38, s38, 0x800
	s_addc_u32 s39, s39, 0
	global_store_dwordx4 v197, v[76:79], s[38:39] nt
	s_add_u32 s38, s38, 0x800
	s_addc_u32 s39, s39, 0
	s_waitcnt lgkmcnt(0)
	global_store_dwordx4 v197, v[96:99], s[38:39] nt
	s_add_u32 s38, s38, 0x800
	s_addc_u32 s39, s39, 0
	global_store_dwordx4 v197, v[100:103], s[38:39] nt
	s_add_u32 s38, s38, 0x800
	s_addc_u32 s39, s39, 0
	global_store_dwordx4 v197, v[104:107], s[38:39] nt
	s_add_u32 s38, s38, 0x800
	s_addc_u32 s39, s39, 0
	global_store_dwordx4 v197, v[108:111], s[38:39] nt
	s_branch .Lai_epi_done
.Lai_epi_sv:
	s_sub_u32 s9, s20, 20
	s_lshl_b32 s9, s9, 7
	s_mul_i32 s8, s52, 0x100
	s_add_u32 s8, s8, s9
	s_add_u32 s38, s0, s8
	s_addc_u32 s39, s1, 0
	s_add_u32 s38, s38, 0x1a424100
	s_addc_u32 s39, s39, 0
	v_cvt_pk_bf16_f32 v240, v0, v1
	v_cvt_pk_bf16_f32 v241, v2, v3
	ds_write_b64 v178, v[240:241]
	v_cvt_pk_bf16_f32 v242, v4, v5
	v_cvt_pk_bf16_f32 v243, v6, v7
	ds_write_b64 v179, v[242:243]
	v_cvt_pk_bf16_f32 v244, v8, v9
	v_cvt_pk_bf16_f32 v245, v10, v11
	ds_write_b64 v180, v[244:245]
	v_cvt_pk_bf16_f32 v246, v12, v13
	v_cvt_pk_bf16_f32 v247, v14, v15
	ds_write_b64 v181, v[246:247]
	v_cvt_pk_bf16_f32 v240, v16, v17
	v_cvt_pk_bf16_f32 v241, v18, v19
	ds_write_b64 v188, v[240:241]
	v_cvt_pk_bf16_f32 v242, v20, v21
	v_cvt_pk_bf16_f32 v243, v22, v23
	ds_write_b64 v189, v[242:243]
	v_cvt_pk_bf16_f32 v244, v24, v25
	v_cvt_pk_bf16_f32 v245, v26, v27
	ds_write_b64 v190, v[244:245]
	v_cvt_pk_bf16_f32 v246, v28, v29
	v_cvt_pk_bf16_f32 v247, v30, v31
	ds_write_b64 v191, v[246:247]
	ds_read_b128 v[0:3], v194
	ds_read_b128 v[4:7], v194 offset:1024
	ds_read_b128 v[8:11], v194 offset:2048
	ds_read_b128 v[12:15], v194 offset:3072
	v_cvt_pk_bf16_f32 v240, v32, v33
	v_cvt_pk_bf16_f32 v241, v34, v35
	ds_write_b64 v178, v[240:241]
	v_cvt_pk_bf16_f32 v242, v36, v37
	v_cvt_pk_bf16_f32 v243, v38, v39
	ds_write_b64 v179, v[242:243]
	v_cvt_pk_bf16_f32 v244, v40, v41
	v_cvt_pk_bf16_f32 v245, v42, v43
	ds_write_b64 v180, v[244:245]
	v_cvt_pk_bf16_f32 v246, v44, v45
	v_cvt_pk_bf16_f32 v247, v46, v47
	ds_write_b64 v181, v[246:247]
	v_cvt_pk_bf16_f32 v240, v48, v49
	v_cvt_pk_bf16_f32 v241, v50, v51
	ds_write_b64 v188, v[240:241]
	v_cvt_pk_bf16_f32 v242, v52, v53
	v_cvt_pk_bf16_f32 v243, v54, v55
	ds_write_b64 v189, v[242:243]
	v_cvt_pk_bf16_f32 v244, v56, v57
	v_cvt_pk_bf16_f32 v245, v58, v59
	ds_write_b64 v190, v[244:245]
	v_cvt_pk_bf16_f32 v246, v60, v61
	v_cvt_pk_bf16_f32 v247, v62, v63
	ds_write_b64 v191, v[246:247]
	ds_read_b128 v[32:35], v194
	ds_read_b128 v[36:39], v194 offset:1024
	ds_read_b128 v[40:43], v194 offset:2048
	ds_read_b128 v[44:47], v194 offset:3072
	s_waitcnt lgkmcnt(12)
; DI int crow(int r, int hf) { return (r & 3) + 8 * (r >> 2) + 4 * hf; }
; DI void att_in_phase(const Params& p, int j, char* smem) {
;     ...
;         } else if (C64 < 1408) {
; #pragma unroll
;           for (int jn = 0; jn < 2; ++jn)
; #pragma unroll
;             for (int r = 0; r < 16; ++r) SV[(size_t)(rb + crow(r, hf_)) * 128 + (C64 - 1280) + jn * 32 + l32_] = f2bf(acc[i][jn][r]);
;         } else if (C64 == 1408) {
; #pragma unroll
;           for (int r = 0; r < 16; ++r) {
;             const int t = rb + crow(r, hf_), pos = t & (S_ - 1);
;             const float x = acc[i][0][r];
;             const float xp = __shfl_xor(x, 16);
;             const float2 cs = rt32[pos * 16 + (l32_ & 15)];
;             const float o = (l32_ < 16) ? (x * cs.x - xp * cs.y) : (x * cs.x + xp * cs.y);
;             const u16 v = f2bf(o);
; #pragma unroll
;             for (int h = 0; h < 8; ++h) Kb[(size_t)t * LDKB + h * 96 + 64 + l32_] = v;
;           }
	global_store_dwordx4 v197, v[0:3], s[38:39] nt
	s_add_u32 s38, s38, 0x800
	s_addc_u32 s39, s39, 0
	global_store_dwordx4 v197, v[4:7], s[38:39] nt
	s_add_u32 s38, s38, 0x800
	s_addc_u32 s39, s39, 0
	global_store_dwordx4 v197, v[8:11], s[38:39] nt
	s_add_u32 s38, s38, 0x800
	s_addc_u32 s39, s39, 0
	global_store_dwordx4 v197, v[12:15], s[38:39] nt
	s_add_u32 s38, s38, 0x800
	s_addc_u32 s39, s39, 0
	v_cvt_pk_bf16_f32 v240, v64, v65
	v_cvt_pk_bf16_f32 v241, v66, v67
	ds_write_b64 v178, v[240:241]
	v_cvt_pk_bf16_f32 v242, v68, v69
	v_cvt_pk_bf16_f32 v243, v70, v71
	ds_write_b64 v179, v[242:243]
	v_cvt_pk_bf16_f32 v244, v72, v73
	v_cvt_pk_bf16_f32 v245, v74, v75
	ds_write_b64 v180, v[244:245]
	v_cvt_pk_bf16_f32 v246, v76, v77
	v_cvt_pk_bf16_f32 v247, v78, v79
	ds_write_b64 v181, v[246:247]
	v_cvt_pk_bf16_f32 v240, v80, v81
	v_cvt_pk_bf16_f32 v241, v82, v83
	ds_write_b64 v188, v[240:241]
	v_cvt_pk_bf16_f32 v242, v84, v85
	v_cvt_pk_bf16_f32 v243, v86, v87
	ds_write_b64 v189, v[242:243]
	v_cvt_pk_bf16_f32 v244, v88, v89
	v_cvt_pk_bf16_f32 v245, v90, v91
	ds_write_b64 v190, v[244:245]
	v_cvt_pk_bf16_f32 v246, v92, v93
	v_cvt_pk_bf16_f32 v247, v94, v95
	ds_write_b64 v191, v[246:247]
	ds_read_b128 v[64:67], v194
	ds_read_b128 v[68:71], v194 offset:1024
	ds_read_b128 v[72:75], v194 offset:2048
	ds_read_b128 v[76:79], v194 offset:3072
	s_waitcnt lgkmcnt(12)
	global_store_dwordx4 v197, v[32:35], s[38:39] nt
	s_add_u32 s38, s38, 0x800
	s_addc_u32 s39, s39, 0
	global_store_dwordx4 v197, v[36:39], s[38:39] nt
	s_add_u32 s38, s38, 0x800
	s_addc_u32 s39, s39, 0
	global_store_dwordx4 v197, v[40:43], s[38:39] nt
	s_add_u32 s38, s38, 0x800
	s_addc_u32 s39, s39, 0
	global_store_dwordx4 v197, v[44:47], s[38:39] nt
	s_add_u32 s38, s38, 0x800
	s_addc_u32 s39, s39, 0
	v_cvt_pk_bf16_f32 v240, v96, v97
	v_cvt_pk_bf16_f32 v241, v98, v99
	ds_write_b64 v178, v[240:241]
	v_cvt_pk_bf16_f32 v242, v100, v101
	v_cvt_pk_bf16_f32 v243, v102, v103
	ds_write_b64 v179, v[242:243]
	v_cvt_pk_bf16_f32 v244, v104, v105
	v_cvt_pk_bf16_f32 v245, v106, v107
	ds_write_b64 v180, v[244:245]
	v_cvt_pk_bf16_f32 v246, v108, v109
	v_cvt_pk_bf16_f32 v247, v110, v111
	ds_write_b64 v181, v[246:247]
	v_cvt_pk_bf16_f32 v240, v112, v113
	v_cvt_pk_bf16_f32 v241, v114, v115
	ds_write_b64 v188, v[240:241]
	v_cvt_pk_bf16_f32 v242, v116, v117
	v_cvt_pk_bf16_f32 v243, v118, v119
	ds_write_b64 v189, v[242:243]
	v_cvt_pk_bf16_f32 v244, v120, v121
	v_cvt_pk_bf16_f32 v245, v122, v123
	ds_write_b64 v190, v[244:245]
	v_cvt_pk_bf16_f32 v246, v124, v125
	v_cvt_pk_bf16_f32 v247, v126, v127
	ds_write_b64 v191, v[246:247]
	ds_read_b128 v[96:99], v194
	ds_read_b128 v[100:103], v194 offset:1024
	ds_read_b128 v[104:107], v194 offset:2048
	ds_read_b128 v[108:111], v194 offset:3072
	s_waitcnt lgkmcnt(12)
	global_store_dwordx4 v197, v[64:67], s[38:39] nt
	s_add_u32 s38, s38, 0x800
	s_addc_u32 s39, s39, 0
	global_store_dwordx4 v197, v[68:71], s[38:39] nt
	s_add_u32 s38, s38, 0x800
	s_addc_u32 s39, s39, 0
	global_store_dwordx4 v197, v[72:75], s[38:39] nt
	s_add_u32 s38, s38, 0x800
	s_addc_u32 s39, s39, 0
	global_store_dwordx4 v197, v[76:79], s[38:39] nt
	s_add_u32 s38, s38, 0x800
	s_addc_u32 s39, s39, 0
	s_waitcnt lgkmcnt(0)
	global_store_dwordx4 v197, v[96:99], s[38:39] nt
	s_add_u32 s38, s38, 0x800
	s_addc_u32 s39, s39, 0
	global_store_dwordx4 v197, v[100:103], s[38:39] nt
	s_add_u32 s38, s38, 0x800
	s_addc_u32 s39, s39, 0
	global_store_dwordx4 v197, v[104:107], s[38:39] nt
	s_add_u32 s38, s38, 0x800
	s_addc_u32 s39, s39, 0
	global_store_dwordx4 v197, v[108:111], s[38:39] nt
	s_branch .Lai_epi_done
.Lai_epi_kr:
	v_and_b32_e32 v245, 63, v182
	v_and_b32_e32 v244, 31, v245
	v_lshrrev_b32_e32 v243, 5, v245
	v_lshlrev_b32_e32 v246, 7, v244
	v_lshl_add_u32 v246, v243, 5, v246
	s_lshl_b32 s8, s53, 7
	s_add_u32 s54, s0, s8
	s_addc_u32 s55, s1, 0
	s_add_u32 s54, s54, 0x34100
	s_addc_u32 s55, s55, 0
	s_add_u32 s8, s54, 0x0
	s_addc_u32 s9, s55, 0
	global_load_dwordx4 v[128:131], v246, s[8:9]
	global_load_dwordx4 v[132:135], v246, s[8:9] offset:16
	global_load_dwordx4 v[136:139], v246, s[8:9] offset:64
	global_load_dwordx4 v[140:143], v246, s[8:9] offset:80
	s_add_u32 s8, s54, 0x1000
	s_addc_u32 s9, s55, 0
	global_load_dwordx4 v[144:147], v246, s[8:9]
	global_load_dwordx4 v[148:151], v246, s[8:9] offset:16
	global_load_dwordx4 v[152:155], v246, s[8:9] offset:64
	global_load_dwordx4 v[156:159], v246, s[8:9] offset:80
	s_add_u32 s8, s54, 0x2000
	s_addc_u32 s9, s55, 0
	global_load_dwordx4 v[162:165], v246, s[8:9]
	global_load_dwordx4 v[166:169], v246, s[8:9] offset:16
	global_load_dwordx4 v[170:173], v246, s[8:9] offset:64
	global_load_dwordx4 v[174:177], v246, s[8:9] offset:80
	s_add_u32 s8, s54, 0x3000
	s_addc_u32 s9, s55, 0
	global_load_dwordx4 v[224:227], v246, s[8:9]
	global_load_dwordx4 v[228:231], v246, s[8:9] offset:16
	global_load_dwordx4 v[232:235], v246, s[8:9] offset:64
	global_load_dwordx4 v[236:239], v246, s[8:9] offset:80
	v_lshrrev_b32_e32 v247, 2, v245
	v_and_b32_e32 v196, 7, v247
	v_and_b32_e32 v197, 3, v245
	v_xor_b32_e32 v196, v196, v197
	v_lshlrev_b32_e32 v196, 4, v196
	v_lshl_add_u32 v196, v247, 7, v196
	s_add_u32 s8, s14, 0x18000
	v_add_u32_e32 v196, s8, v196
	v_lshlrev_b32_e32 v197, 4, v197
	s_movk_i32 s8, 0x680
	v_mad_u32_u24 v197, v247, s8, v197
	s_mul_i32 s8, s52, 0x680
	s_add_u32 s38, s0, s8
	s_addc_u32 s39, s1, 0
	s_add_u32 s38, s38, 0x12804180
	s_addc_u32 s39, s39, 0
	s_waitcnt vmcnt(0)
; DI int crow(int r, int hf) { return (r & 3) + 8 * (r >> 2) + 4 * hf; }
; DI void att_in_phase(const Params& p, int j, char* smem) {
;     ...
;         } else if (C64 == 1408) {
; #pragma unroll
;           for (int r = 0; r < 16; ++r) {
;             const int t = rb + crow(r, hf_), pos = t & (S_ - 1);
;             const float x = acc[i][0][r];
;             const float xp = __shfl_xor(x, 16);
;             const float2 cs = rt32[pos * 16 + (l32_ & 15)];
;             const float o = (l32_ < 16) ? (x * cs.x - xp * cs.y) : (x * cs.x + xp * cs.y);
;             const u16 v = f2bf(o);
; #pragma unroll
;             for (int h = 0; h < 8; ++h) Kb[(size_t)t * LDKB + h * 96 + 64 + l32_] = v;
;           }
	v_mul_f32_e32 v246, v8, v129
	v_mul_f32_e32 v247, v0, v129
	v_fma_f32 v0, v0, v128, -v246
	v_fma_f32 v8, v8, v128, v247
	v_mul_f32_e32 v246, v9, v131
	v_mul_f32_e32 v247, v1, v131
	v_fma_f32 v1, v1, v130, -v246
	v_fma_f32 v9, v9, v130, v247
	v_mul_f32_e32 v246, v10, v133
	v_mul_f32_e32 v247, v2, v133
	v_fma_f32 v2, v2, v132, -v246
	v_fma_f32 v10, v10, v132, v247
	v_mul_f32_e32 v246, v11, v135
	v_mul_f32_e32 v247, v3, v135
	v_fma_f32 v3, v3, v134, -v246
	v_fma_f32 v11, v11, v134, v247
	v_mul_f32_e32 v246, v12, v137
	v_mul_f32_e32 v247, v4, v137
	v_fma_f32 v4, v4, v136, -v246
	v_fma_f32 v12, v12, v136, v247
	v_mul_f32_e32 v246, v13, v139
	v_mul_f32_e32 v247, v5, v139
	v_fma_f32 v5, v5, v138, -v246
	v_fma_f32 v13, v13, v138, v247
	v_mul_f32_e32 v246, v14, v141
	v_mul_f32_e32 v247, v6, v141
	v_fma_f32 v6, v6, v140, -v246
	v_fma_f32 v14, v14, v140, v247
	v_mul_f32_e32 v246, v15, v143
	v_mul_f32_e32 v247, v7, v143
	v_fma_f32 v7, v7, v142, -v246
	v_fma_f32 v15, v15, v142, v247
	v_cvt_pk_bf16_f32 v240, v0, v1
	v_cvt_pk_bf16_f32 v241, v2, v3
	ds_write_b64 v178, v[240:241]
	v_cvt_pk_bf16_f32 v242, v4, v5
	v_cvt_pk_bf16_f32 v243, v6, v7
	ds_write_b64 v179, v[242:243]
	v_cvt_pk_bf16_f32 v244, v8, v9
	v_cvt_pk_bf16_f32 v245, v10, v11
	ds_write_b64 v180, v[244:245]
	v_cvt_pk_bf16_f32 v240, v12, v13
	v_cvt_pk_bf16_f32 v241, v14, v15
	ds_write_b64 v181, v[240:241]
	ds_read_b128 v[16:19], v196
	ds_read_b128 v[20:23], v196 offset:2048
	s_waitcnt lgkmcnt(0)
	global_store_dwordx4 v197, v[16:19], s[38:39]
	global_store_dwordx4 v197, v[16:19], s[38:39] offset:192
	global_store_dwordx4 v197, v[16:19], s[38:39] offset:384
	global_store_dwordx4 v197, v[16:19], s[38:39] offset:576
	global_store_dwordx4 v197, v[16:19], s[38:39] offset:768
	global_store_dwordx4 v197, v[16:19], s[38:39] offset:960
	global_store_dwordx4 v197, v[16:19], s[38:39] offset:1152
	global_store_dwordx4 v197, v[16:19], s[38:39] offset:1344
	s_add_u32 s38, s38, 0x6800
	s_addc_u32 s39, s39, 0
	global_store_dwordx4 v197, v[20:23], s[38:39]
	global_store_dwordx4 v197, v[20:23], s[38:39] offset:192
	global_store_dwordx4 v197, v[20:23], s[38:39] offset:384
	global_store_dwordx4 v197, v[20:23], s[38:39] offset:576
	global_store_dwordx4 v197, v[20:23], s[38:39] offset:768
	global_store_dwordx4 v197, v[20:23], s[38:39] offset:960
	global_store_dwordx4 v197, v[20:23], s[38:39] offset:1152
	global_store_dwordx4 v197, v[20:23], s[38:39] offset:1344
	s_add_u32 s38, s38, 0x6800
	s_addc_u32 s39, s39, 0
	v_mul_f32_e32 v246, v40, v145
	v_mul_f32_e32 v247, v32, v145
	v_fma_f32 v32, v32, v144, -v246
	v_fma_f32 v40, v40, v144, v247
	v_mul_f32_e32 v246, v41, v147
	v_mul_f32_e32 v247, v33, v147
	v_fma_f32 v33, v33, v146, -v246
	v_fma_f32 v41, v41, v146, v247
	v_mul_f32_e32 v246, v42, v149
	v_mul_f32_e32 v247, v34, v149
	v_fma_f32 v34, v34, v148, -v246
	v_fma_f32 v42, v42, v148, v247
	v_mul_f32_e32 v246, v43, v151
	v_mul_f32_e32 v247, v35, v151
	v_fma_f32 v35, v35, v150, -v246
	v_fma_f32 v43, v43, v150, v247
	v_mul_f32_e32 v246, v44, v153
	v_mul_f32_e32 v247, v36, v153
	v_fma_f32 v36, v36, v152, -v246
	v_fma_f32 v44, v44, v152, v247
	v_mul_f32_e32 v246, v45, v155
	v_mul_f32_e32 v247, v37, v155
	v_fma_f32 v37, v37, v154, -v246
	v_fma_f32 v45, v45, v154, v247
	v_mul_f32_e32 v246, v46, v157
	v_mul_f32_e32 v247, v38, v157
	v_fma_f32 v38, v38, v156, -v246
	v_fma_f32 v46, v46, v156, v247
	v_mul_f32_e32 v246, v47, v159
	v_mul_f32_e32 v247, v39, v159
	v_fma_f32 v39, v39, v158, -v246
	v_fma_f32 v47, v47, v158, v247
	v_cvt_pk_bf16_f32 v242, v32, v33
	v_cvt_pk_bf16_f32 v243, v34, v35
	ds_write_b64 v178, v[242:243]
	v_cvt_pk_bf16_f32 v244, v36, v37
	v_cvt_pk_bf16_f32 v245, v38, v39
	ds_write_b64 v179, v[244:245]
	v_cvt_pk_bf16_f32 v240, v40, v41
	v_cvt_pk_bf16_f32 v241, v42, v43
	ds_write_b64 v180, v[240:241]
	v_cvt_pk_bf16_f32 v242, v44, v45
	v_cvt_pk_bf16_f32 v243, v46, v47
	ds_write_b64 v181, v[242:243]
	ds_read_b128 v[48:51], v196
	ds_read_b128 v[52:55], v196 offset:2048
	s_waitcnt lgkmcnt(0)
	global_store_dwordx4 v197, v[48:51], s[38:39]
	global_store_dwordx4 v197, v[48:51], s[38:39] offset:192
	global_store_dwordx4 v197, v[48:51], s[38:39] offset:384
	global_store_dwordx4 v197, v[48:51], s[38:39] offset:576
	global_store_dwordx4 v197, v[48:51], s[38:39] offset:768
	global_store_dwordx4 v197, v[48:51], s[38:39] offset:960
	global_store_dwordx4 v197, v[48:51], s[38:39] offset:1152
	global_store_dwordx4 v197, v[48:51], s[38:39] offset:1344
	s_add_u32 s38, s38, 0x6800
	s_addc_u32 s39, s39, 0
	global_store_dwordx4 v197, v[52:55], s[38:39]
	global_store_dwordx4 v197, v[52:55], s[38:39] offset:192
	global_store_dwordx4 v197, v[52:55], s[38:39] offset:384
	global_store_dwordx4 v197, v[52:55], s[38:39] offset:576
	global_store_dwordx4 v197, v[52:55], s[38:39] offset:768
	global_store_dwordx4 v197, v[52:55], s[38:39] offset:960
	global_store_dwordx4 v197, v[52:55], s[38:39] offset:1152
	global_store_dwordx4 v197, v[52:55], s[38:39] offset:1344
	s_add_u32 s38, s38, 0x6800
	s_addc_u32 s39, s39, 0
	v_mul_f32_e32 v246, v72, v163
	v_mul_f32_e32 v247, v64, v163
	v_fma_f32 v64, v64, v162, -v246
	v_fma_f32 v72, v72, v162, v247
	v_mul_f32_e32 v246, v73, v165
	v_mul_f32_e32 v247, v65, v165
	v_fma_f32 v65, v65, v164, -v246
	v_fma_f32 v73, v73, v164, v247
	v_mul_f32_e32 v246, v74, v167
	v_mul_f32_e32 v247, v66, v167
	v_fma_f32 v66, v66, v166, -v246
	v_fma_f32 v74, v74, v166, v247
	v_mul_f32_e32 v246, v75, v169
	v_mul_f32_e32 v247, v67, v169
	v_fma_f32 v67, v67, v168, -v246
	v_fma_f32 v75, v75, v168, v247
	v_mul_f32_e32 v246, v76, v171
	v_mul_f32_e32 v247, v68, v171
	v_fma_f32 v68, v68, v170, -v246
	v_fma_f32 v76, v76, v170, v247
	v_mul_f32_e32 v246, v77, v173
	v_mul_f32_e32 v247, v69, v173
	v_fma_f32 v69, v69, v172, -v246
	v_fma_f32 v77, v77, v172, v247
	v_mul_f32_e32 v246, v78, v175
	v_mul_f32_e32 v247, v70, v175
	v_fma_f32 v70, v70, v174, -v246
	v_fma_f32 v78, v78, v174, v247
	v_mul_f32_e32 v246, v79, v177
	v_mul_f32_e32 v247, v71, v177
	v_fma_f32 v71, v71, v176, -v246
	v_fma_f32 v79, v79, v176, v247
	v_cvt_pk_bf16_f32 v244, v64, v65
	v_cvt_pk_bf16_f32 v245, v66, v67
	ds_write_b64 v178, v[244:245]
	v_cvt_pk_bf16_f32 v240, v68, v69
	v_cvt_pk_bf16_f32 v241, v70, v71
	ds_write_b64 v179, v[240:241]
	v_cvt_pk_bf16_f32 v242, v72, v73
	v_cvt_pk_bf16_f32 v243, v74, v75
	ds_write_b64 v180, v[242:243]
	v_cvt_pk_bf16_f32 v244, v76, v77
	v_cvt_pk_bf16_f32 v245, v78, v79
	ds_write_b64 v181, v[244:245]
	ds_read_b128 v[80:83], v196
	ds_read_b128 v[84:87], v196 offset:2048
	s_waitcnt lgkmcnt(0)
; DI int crow(int r, int hf) { return (r & 3) + 8 * (r >> 2) + 4 * hf; }
; DI void att_in_phase(const Params& p, int j, char* smem) {
;     ...
;         } else if (C64 == 1408) {
; #pragma unroll
;           for (int r = 0; r < 16; ++r) {
;             const int t = rb + crow(r, hf_), pos = t & (S_ - 1);
;             const float x = acc[i][0][r];
;             const float xp = __shfl_xor(x, 16);
;             const float2 cs = rt32[pos * 16 + (l32_ & 15)];
;             const float o = (l32_ < 16) ? (x * cs.x - xp * cs.y) : (x * cs.x + xp * cs.y);
;             const u16 v = f2bf(o);
; #pragma unroll
;             for (int h = 0; h < 8; ++h) Kb[(size_t)t * LDKB + h * 96 + 64 + l32_] = v;
;           }
	global_store_dwordx4 v197, v[80:83], s[38:39]
	global_store_dwordx4 v197, v[80:83], s[38:39] offset:192
	global_store_dwordx4 v197, v[80:83], s[38:39] offset:384
	global_store_dwordx4 v197, v[80:83], s[38:39] offset:576
	global_store_dwordx4 v197, v[80:83], s[38:39] offset:768
	global_store_dwordx4 v197, v[80:83], s[38:39] offset:960
	global_store_dwordx4 v197, v[80:83], s[38:39] offset:1152
	global_store_dwordx4 v197, v[80:83], s[38:39] offset:1344
	s_add_u32 s38, s38, 0x6800
	s_addc_u32 s39, s39, 0
	global_store_dwordx4 v197, v[84:87], s[38:39]
	global_store_dwordx4 v197, v[84:87], s[38:39] offset:192
	global_store_dwordx4 v197, v[84:87], s[38:39] offset:384
	global_store_dwordx4 v197, v[84:87], s[38:39] offset:576
	global_store_dwordx4 v197, v[84:87], s[38:39] offset:768
	global_store_dwordx4 v197, v[84:87], s[38:39] offset:960
	global_store_dwordx4 v197, v[84:87], s[38:39] offset:1152
	global_store_dwordx4 v197, v[84:87], s[38:39] offset:1344
	s_add_u32 s38, s38, 0x6800
	s_addc_u32 s39, s39, 0
	v_mul_f32_e32 v246, v104, v225
	v_mul_f32_e32 v247, v96, v225
	v_fma_f32 v96, v96, v224, -v246
	v_fma_f32 v104, v104, v224, v247
	v_mul_f32_e32 v246, v105, v227
	v_mul_f32_e32 v247, v97, v227
	v_fma_f32 v97, v97, v226, -v246
	v_fma_f32 v105, v105, v226, v247
	v_mul_f32_e32 v246, v106, v229
	v_mul_f32_e32 v247, v98, v229
	v_fma_f32 v98, v98, v228, -v246
	v_fma_f32 v106, v106, v228, v247
	v_mul_f32_e32 v246, v107, v231
	v_mul_f32_e32 v247, v99, v231
	v_fma_f32 v99, v99, v230, -v246
	v_fma_f32 v107, v107, v230, v247
	v_mul_f32_e32 v246, v108, v233
	v_mul_f32_e32 v247, v100, v233
	v_fma_f32 v100, v100, v232, -v246
	v_fma_f32 v108, v108, v232, v247
	v_mul_f32_e32 v246, v109, v235
	v_mul_f32_e32 v247, v101, v235
	v_fma_f32 v101, v101, v234, -v246
	v_fma_f32 v109, v109, v234, v247
	v_mul_f32_e32 v246, v110, v237
	v_mul_f32_e32 v247, v102, v237
	v_fma_f32 v102, v102, v236, -v246
	v_fma_f32 v110, v110, v236, v247
	v_mul_f32_e32 v246, v111, v239
	v_mul_f32_e32 v247, v103, v239
	v_fma_f32 v103, v103, v238, -v246
	v_fma_f32 v111, v111, v238, v247
	v_cvt_pk_bf16_f32 v240, v96, v97
	v_cvt_pk_bf16_f32 v241, v98, v99
	ds_write_b64 v178, v[240:241]
	v_cvt_pk_bf16_f32 v242, v100, v101
	v_cvt_pk_bf16_f32 v243, v102, v103
	ds_write_b64 v179, v[242:243]
	v_cvt_pk_bf16_f32 v244, v104, v105
	v_cvt_pk_bf16_f32 v245, v106, v107
	ds_write_b64 v180, v[244:245]
	v_cvt_pk_bf16_f32 v240, v108, v109
	v_cvt_pk_bf16_f32 v241, v110, v111
	ds_write_b64 v181, v[240:241]
	ds_read_b128 v[112:115], v196
	ds_read_b128 v[116:119], v196 offset:2048
	s_waitcnt lgkmcnt(0)
	global_store_dwordx4 v197, v[112:115], s[38:39]
	global_store_dwordx4 v197, v[112:115], s[38:39] offset:192
	global_store_dwordx4 v197, v[112:115], s[38:39] offset:384
	global_store_dwordx4 v197, v[112:115], s[38:39] offset:576
	global_store_dwordx4 v197, v[112:115], s[38:39] offset:768
	global_store_dwordx4 v197, v[112:115], s[38:39] offset:960
	global_store_dwordx4 v197, v[112:115], s[38:39] offset:1152
	global_store_dwordx4 v197, v[112:115], s[38:39] offset:1344
	s_add_u32 s38, s38, 0x6800
	s_addc_u32 s39, s39, 0
	global_store_dwordx4 v197, v[116:119], s[38:39]
	global_store_dwordx4 v197, v[116:119], s[38:39] offset:192
	global_store_dwordx4 v197, v[116:119], s[38:39] offset:384
	global_store_dwordx4 v197, v[116:119], s[38:39] offset:576
	global_store_dwordx4 v197, v[116:119], s[38:39] offset:768
	global_store_dwordx4 v197, v[116:119], s[38:39] offset:960
	global_store_dwordx4 v197, v[116:119], s[38:39] offset:1152
	global_store_dwordx4 v197, v[116:119], s[38:39] offset:1344
	s_add_u32 s38, s38, 0x6800
	s_addc_u32 s39, s39, 0
	v_and_b32_e32 v245, 63, v182
	v_lshrrev_b32_e32 v244, 3, v245
	v_and_b32_e32 v243, 7, v245
	v_lshlrev_b32_e32 v196, 4, v243
	s_movk_i32 s10, 0x400
	v_mad_u32_u24 v196, v244, s10, v196
	v_lshlrev_b32_e32 v197, 4, v243
	s_movk_i32 s10, 0x100
	v_mad_u32_u24 v197, v244, s10, v197
.Lai_epi_done:
	s_waitcnt lgkmcnt(0)
	s_add_u32 m0, s14, 0x18000
	s_nop 0
	global_load_lds_dwordx4 v220, s[24:25]
	s_add_u32 m0, s14, 0x18400
	s_nop 0
	global_load_lds_dwordx4 v221, s[24:25]
	s_add_u32 m0, s14, 0x18800
	s_nop 0
	global_load_lds_dwordx4 v222, s[24:25]
	s_add_u32 m0, s14, 0x18c00
	s_nop 0
	global_load_lds_dwordx4 v223, s[24:25]
	s_add_u32 s22, s22, 0x80
	s_addc_u32 s23, s23, 0
	s_add_u32 s24, s24, 0x80
	s_addc_u32 s25, s25, 0
	s_add_u32 s26, s26, 1
	s_cmp_eq_u32 s26, 16
	s_cbranch_scc0 .Lai8_cadv_done
	s_mov_b32 s26, 0
	s_add_u32 s27, s27, s30
	s_cmp_lt_u32 s27, 0x60
	s_cbranch_scc1 .Lai8_cadv_new
	s_sub_u32 s22, s22, 0x800
	s_subb_u32 s23, s23, 0
	s_sub_u32 s24, s24, 0x800
	s_subb_u32 s25, s25, 0
	s_branch .Lai8_cadv_done

; DI void att_in_phase(const Params& p, int j, char* smem) {
;     ...
;   for (int lt = blockIdx.x >> 3; lt < 16 * nN; lt += gridDim.x >> 3) {
;     int mt, nt; tile_map(lt, 16, nN, 16, 2, mt, nt);
;     const int m0 = mt * 256, n0 = nt * 256;
;     gemm_tile(A + (size_t)m0 * LDH, LDH, 16, nullptr, 0, 0, Wt + (size_t)n0 * LDW1, LDW1, smem, [&](f32x16(&acc)[2][2], int moff) {
.Lai8_cadv_done:
	ds_read_b128 v[128:131], v204
	ds_read_b128 v[132:135], v204 offset:4096
	ds_read_b128 v[136:139], v204 offset:8192
	ds_read_b128 v[140:143], v204 offset:12288
	ds_read_b128 v[162:165], v212
	ds_read_b128 v[166:169], v212 offset:4096
	ds_read_b128 v[144:147], v205
	ds_read_b128 v[148:151], v205 offset:4096
	ds_read_b128 v[152:155], v205 offset:8192
	ds_read_b128 v[156:159], v205 offset:12288
	ds_read_b128 v[170:173], v213
	ds_read_b128 v[174:177], v213 offset:4096
	s_add_u32 s28, s28, s30
	s_cmp_lt_u32 s28, 0x60
	s_cbranch_scc1 .Lai_tile
	s_waitcnt vmcnt(0) lgkmcnt(0)

; DI int opqv(int x) { asm volatile("" : "+v"(x)); return x; }
; DI char* opq(char* p) { asm volatile("" : "+s"(p)); return p; }
; DI void rec_in_phase(const Params& p, int j, char* smem) {
;   const int tid = opqv(threadIdx.x), lane = tid & 63, w = tid >> 6, wm = w >> 2, wn = w & 3, l32 = lane & 31, hf = lane >> 5;
;   char* ws = opq(p.ws);
;   const u16* A = (const u16*)(ws + OFF_HY);
;   const u16* Wt = (const u16*)(ws + OFF_W_RECIN) + (size_t)j * 2560 * LDW1;
;   u16* zr = (u16*)(ws + OFF_ZR); u16* ug = (u16*)(ws + OFF_UG);
;   const float2* rt128 = (const float2*)(ws + OFF_RT128);
;   const int nN = 10;
;   for (int lt = blockIdx.x >> 3; lt < 16 * nN; lt += gridDim.x >> 3) {
;     int mt, nt; tile_map(lt, 16, nN, 16, 2, mt, nt);
;     const int m0 = mt * 256, n0 = nt * 256;
;     gemm_tile(A + (size_t)m0 * LDH, LDH, 16, nullptr, 0, 0, Wt + (size_t)n0 * LDW1, LDW1, smem, [&](f32x16(&acc)[2][2], int moff) {
.LBB0_779:
	s_and_b64 vcc, exec, s[0:1]
	s_cbranch_vccz .LBB0_846
	v_readlane_b32 s0, v252, 5
	v_readlane_b32 s1, v252, 6
	s_andn2_b64 vcc, exec, s[0:1]
	v_readlane_b32 s0, v254, 25
	v_readlane_b32 s1, v254, 26
	s_ashr_i32 s1, s0, 31
	v_readlane_b32 s4, v251, 13
	v_writelane_b32 v254, s0, 25
	v_mov_b32_e32 v0, v182
	v_readlane_b32 s5, v251, 14
	v_writelane_b32 v254, s1, 26
	s_mov_b32 s40, 0x3fb8aa3b
	s_mov_b32 s41, 0xc2ce8ed0
	s_mov_b32 s50, 0x42b17218
	s_mov_b64 s[52:53], 0x1d84180
	s_mov_b64 s[54:55], 0x1d84200
	s_cbranch_vccnz .LBB0_819
	v_readlane_b32 s28, v253, 48
	v_readlane_b32 s30, v253, 50
	s_cmp_ge_u32 s28, 0xa0
	s_cbranch_scc1 .LBB0_819
	s_add_u32 s0, s4, 0x8c04100
	s_addc_u32 s1, s5, 0
	v_readlane_b32 s6, v254, 25
	v_readlane_b32 s31, v251, 0
	s_mul_i32 s6, s6, 0x550000
	s_add_u32 s6, s4, s6
	s_addc_u32 s7, s5, 0
	s_add_u32 s6, s6, 0x1d84100
	s_addc_u32 s7, s7, 0
	s_and_b32 s31, s31, 7
	s_lshl_b32 s31, s31, 4
	s_lshr_b32 s8, s28, 1
	s_add_u32 s31, s31, s8
	s_mul_i32 s8, s31, 0x88000
	s_add_u32 s34, s0, s8
	s_addc_u32 s35, s1, 0
	v_lshrrev_b32_e32 v228, 6, v182
	v_and_b32_e32 v229, 63, v182
	v_readfirstlane_b32 s15, v228
	v_and_b32_e32 v230, 31, v229
	v_lshrrev_b32_e32 v231, 5, v229
	v_lshrrev_b32_e32 v232, 3, v229
	v_and_b32_e32 v233, 7, v229
	s_lshl_b32 s14, s15, 12
	s_add_u32 s14, s14, 32
	v_lshrrev_b32_e32 v234, 1, v232
	v_xor_b32_e32 v234, v233, v234
	v_lshlrev_b32_e32 v234, 4, v234
	s_lshl_b32 s8, s15, 2
	s_add_u32 s8, s8, 0
	s_lshl_b32 s8, s8, 3
	v_add_u32_e32 v235, s8, v232
	s_movk_i32 s9, 0x880
	v_mad_u32_u24 v220, v235, s9, v234
	v_lshrrev_b32_e32 v234, 1, v232
	v_add_u32_e32 v234, 4, v234
	v_xor_b32_e32 v234, v233, v234
	v_lshlrev_b32_e32 v234, 4, v234
	s_lshl_b32 s8, s15, 2
	s_add_u32 s8, s8, 1
	s_lshl_b32 s8, s8, 3
	v_add_u32_e32 v235, s8, v232
	s_movk_i32 s9, 0x880
	v_mad_u32_u24 v221, v235, s9, v234
	v_lshrrev_b32_e32 v234, 1, v232
	v_xor_b32_e32 v234, v233, v234
	v_lshlrev_b32_e32 v234, 4, v234
	s_lshl_b32 s8, s15, 2
	s_add_u32 s8, s8, 2
	s_lshl_b32 s8, s8, 3
	v_add_u32_e32 v235, s8, v232
	s_movk_i32 s9, 0x880
	v_mad_u32_u24 v222, v235, s9, v234
	v_lshrrev_b32_e32 v234, 1, v232
	v_add_u32_e32 v234, 4, v234
	v_xor_b32_e32 v234, v233, v234
	v_lshlrev_b32_e32 v234, 4, v234
	s_lshl_b32 s8, s15, 2
	s_add_u32 s8, s8, 3
	s_lshl_b32 s8, s8, 3
	v_add_u32_e32 v235, s8, v232
	s_movk_i32 s9, 0x880
	v_mad_u32_u24 v223, v235, s9, v234
	v_lshrrev_b32_e32 v236, 1, v230
	v_and_b32_e32 v236, 7, v236
	s_lshr_b32 s8, s15, 2
	s_and_b32 s9, s15, 3
	s_lshl_b32 s10, s8, 14
	s_add_u32 s10, s10, 32
	s_lshl_b32 s11, s9, 13
	s_add_u32 s11, s11, 0x8020
	v_lshlrev_b32_e32 v237, 7, v230
	v_add_u32_e32 v238, s11, v237
	v_add_u32_e32 v237, s10, v237
	v_add_u32_e32 v239, 0, v231
	v_xor_b32_e32 v239, v239, v236
	v_lshlrev_b32_e32 v239, 4, v239
	v_add_u32_e32 v204, v237, v239
	v_add_u32_e32 v212, v238, v239
	v_add_u32_e32 v208, 0x10000, v204
	v_add_u32_e32 v216, 0x10000, v212
	v_add_u32_e32 v239, 2, v231
	v_xor_b32_e32 v239, v239, v236
	v_lshlrev_b32_e32 v239, 4, v239
	v_add_u32_e32 v205, v237, v239
	v_add_u32_e32 v213, v238, v239
	v_add_u32_e32 v209, 0x10000, v205
	v_add_u32_e32 v217, 0x10000, v213
	v_add_u32_e32 v239, 4, v231
	v_xor_b32_e32 v239, v239, v236
	v_lshlrev_b32_e32 v239, 4, v239
	v_add_u32_e32 v206, v237, v239
	v_add_u32_e32 v214, v238, v239
	v_add_u32_e32 v210, 0x10000, v206
	v_add_u32_e32 v218, 0x10000, v214
	v_add_u32_e32 v239, 6, v231
	v_xor_b32_e32 v239, v239, v236
	v_lshlrev_b32_e32 v239, 4, v239
	v_add_u32_e32 v207, v237, v239
	v_add_u32_e32 v215, v238, v239
	v_add_u32_e32 v211, 0x10000, v207
	v_add_u32_e32 v219, 0x10000, v215
	s_add_u32 s10, s14, 0x18000
	v_lshlrev_b32_e32 v234, 7, v230
	v_lshlrev_b32_e32 v235, 3, v231
	v_add3_u32 v234, v234, v235, s10
	v_and_b32_e32 v235, 7, v230
	v_mov_b32_e32 v178, v235
	v_xor_b32_e32 v179, 1, v235
	v_xor_b32_e32 v180, 2, v235
	v_xor_b32_e32 v181, 3, v235
	v_xor_b32_e32 v188, 4, v235
	v_xor_b32_e32 v189, 5, v235
	v_xor_b32_e32 v190, 6, v235
	v_xor_b32_e32 v191, 7, v235
	v_lshl_add_u32 v178, v178, 4, v234
	v_lshl_add_u32 v179, v179, 4, v234
	v_lshl_add_u32 v180, v180, 4, v234
	v_lshl_add_u32 v181, v181, 4, v234
	v_lshl_add_u32 v188, v188, 4, v234
	v_lshl_add_u32 v189, v189, 4, v234
	v_lshl_add_u32 v190, v190, 4, v234
	v_lshl_add_u32 v191, v191, 4, v234
	v_xor_b32_e32 v194, v232, v233
	v_lshlrev_b32_e32 v194, 4, v194
	v_lshl_add_u32 v194, v232, 7, v194
	v_add_u32_e32 v194, s10, v194
	s_lshl_b32 s12, s8, 7
	s_mov_b32 s13, s9
	v_lshlrev_b32_e32 v195, 4, v233
	s_movk_i32 s10, 0x1080
	v_mad_u32_u24 v195, v232, s10, v195
	v_lshrrev_b32_e32 v234, 2, v233
	v_lshl_add_u32 v196, v234, 6, v195
	v_lshrrev_b32_e32 v234, 1, v233
	v_and_b32_e32 v235, 1, v233
	v_lshlrev_b32_e32 v235, 4, v235
	v_lshl_add_u32 v197, v234, 20, v235
	v_lshl_add_u32 v197, v232, 5, v197
	v_lshlrev_b32_e32 v160, 9, v230
	v_lshl_add_u32 v160, v231, 5, v160
	s_lshl_b32 s10, s31, 8
	s_add_u32 s10, s10, s12
	s_and_b32 s10, s10, 0x3fff
	s_lshl_b32 s10, s10, 9
	s_and_b32 s11, s13, 1
	s_lshl_b32 s11, s11, 8
	s_add_u32 s10, s10, s11
	s_add_u32 s36, s4, s10
	s_addc_u32 s37, s5, 0
	s_add_u32 s36, s36, 0x634100
	s_addc_u32 s37, s37, 0
	s_mov_b32 s27, s28
	s_mov_b32 s26, 0
	s_lshr_b32 s8, s27, 5
	s_lshl_b32 s8, s8, 1
	s_and_b32 s9, s27, 1
	s_add_u32 s8, s8, s9
	s_mul_i32 s8, s8, 0x88000
	s_add_u32 s24, s6, s8
	s_addc_u32 s25, s7, 0
	s_mov_b64 s[22:23], s[34:35]
	s_add_u32 m0, s14, 0x0
	s_nop 0
	global_load_lds_dwordx4 v220, s[22:23]
	s_add_u32 m0, s14, 0x8000
	s_nop 0
	global_load_lds_dwordx4 v220, s[24:25]
	s_add_u32 m0, s14, 0x400
	s_nop 0
	global_load_lds_dwordx4 v221, s[22:23]
	s_add_u32 m0, s14, 0x8400
	s_nop 0
	global_load_lds_dwordx4 v221, s[24:25]
	s_add_u32 m0, s14, 0x800
	s_nop 0
	global_load_lds_dwordx4 v222, s[22:23]
	s_add_u32 m0, s14, 0x8800
	s_nop 0
	global_load_lds_dwordx4 v222, s[24:25]
	s_add_u32 m0, s14, 0xc00
	s_nop 0
	global_load_lds_dwordx4 v223, s[22:23]
	s_add_u32 m0, s14, 0x8c00
	s_nop 0
	global_load_lds_dwordx4 v223, s[24:25]
	s_add_u32 s22, s22, 0x80
	s_addc_u32 s23, s23, 0
	s_add_u32 s24, s24, 0x80
	s_addc_u32 s25, s25, 0
	s_add_u32 s26, s26, 1
	s_cmp_eq_u32 s26, 16
	s_cbranch_scc0 .Lri1_cadv_done
	s_mov_b32 s26, 0
	s_add_u32 s27, s27, s30
	s_cmp_lt_u32 s27, 0xa0
	s_cbranch_scc1 .Lri1_cadv_new
	s_sub_u32 s22, s22, 0x800
	s_subb_u32 s23, s23, 0
	s_sub_u32 s24, s24, 0x800
	s_subb_u32 s25, s25, 0
	s_branch .Lri1_cadv_done

; #define RAWBAR() { asm volatile("s_waitcnt vmcnt(0) lgkmcnt(0)" ::: "memory"); __builtin_amdgcn_s_barrier(); }
;     ...
;   if (V != 1) GLDS(0, 0);
;   RAWBAR();
;   for (int kt = 0; kt < nk; kt += 2) {
;     if (V != 1) GLDS(kt + 1, 1);
.Lri1_cadv_done:
	s_add_u32 m0, s14, 0x10000
	s_nop 0
	global_load_lds_dwordx4 v220, s[22:23]
	s_add_u32 m0, s14, 0x18000
	s_nop 0
	global_load_lds_dwordx4 v220, s[24:25]
	s_add_u32 m0, s14, 0x10400
	s_nop 0
	global_load_lds_dwordx4 v221, s[22:23]
	s_add_u32 m0, s14, 0x18400
	s_nop 0
	global_load_lds_dwordx4 v221, s[24:25]
	s_add_u32 m0, s14, 0x10800
	s_nop 0
	global_load_lds_dwordx4 v222, s[22:23]
	s_add_u32 m0, s14, 0x18800
	s_nop 0
	global_load_lds_dwordx4 v222, s[24:25]
	s_add_u32 m0, s14, 0x10c00
	s_nop 0
	global_load_lds_dwordx4 v223, s[22:23]
	s_add_u32 m0, s14, 0x18c00
	s_nop 0
	global_load_lds_dwordx4 v223, s[24:25]
	s_add_u32 s22, s22, 0x80
	s_addc_u32 s23, s23, 0
	s_add_u32 s24, s24, 0x80
	s_addc_u32 s25, s25, 0
	s_add_u32 s26, s26, 1
	s_cmp_eq_u32 s26, 16
	s_cbranch_scc0 .Lri2_cadv_done
	s_mov_b32 s26, 0
	s_add_u32 s27, s27, s30
	s_cmp_lt_u32 s27, 0xa0
	s_cbranch_scc1 .Lri2_cadv_new
	s_sub_u32 s22, s22, 0x800
	s_subb_u32 s23, s23, 0
	s_sub_u32 s24, s24, 0x800
	s_subb_u32 s25, s25, 0
	s_branch .Lri2_cadv_done

; #define RAWBAR() { asm volatile("s_waitcnt vmcnt(0) lgkmcnt(0)" ::: "memory"); __builtin_amdgcn_s_barrier(); }
;     ...
;   if (V != 1) GLDS(0, 0);
;   RAWBAR();
;   for (int kt = 0; kt < nk; kt += 2) {
;     if (V != 1) GLDS(kt + 1, 1);
;     if (V != 2) COMPUTE(0);
;     RAWBAR();
;     if (V != 1) if (kt + 2 < nk) GLDS(kt + 2, 0);
;     if (V != 2) COMPUTE(1);
;     RAWBAR();
;   }
.Lri_tile:
	s_waitcnt lgkmcnt(6)
	v_mfma_f32_32x32x16_bf16 v[0:15], v[162:165], v[128:131], 0
	v_mfma_f32_32x32x16_bf16 v[16:31], v[166:169], v[128:131], 0
	ds_read_b128 v[128:131], v206
	v_mfma_f32_32x32x16_bf16 v[32:47], v[162:165], v[132:135], 0
	v_mfma_f32_32x32x16_bf16 v[48:63], v[166:169], v[132:135], 0
	ds_read_b128 v[132:135], v206 offset:4096
	v_mfma_f32_32x32x16_bf16 v[64:79], v[162:165], v[136:139], 0
	v_mfma_f32_32x32x16_bf16 v[80:95], v[166:169], v[136:139], 0
	ds_read_b128 v[136:139], v206 offset:8192
	v_mfma_f32_32x32x16_bf16 v[96:111], v[162:165], v[140:143], 0
	v_mfma_f32_32x32x16_bf16 v[112:127], v[166:169], v[140:143], 0
	ds_read_b128 v[140:143], v206 offset:12288
	ds_read_b128 v[162:165], v214
	ds_read_b128 v[166:169], v214 offset:4096
	s_waitcnt lgkmcnt(6)
	v_mfma_f32_32x32x16_bf16 v[0:15], v[170:173], v[144:147], v[0:15]
	v_mfma_f32_32x32x16_bf16 v[16:31], v[174:177], v[144:147], v[16:31]
	ds_read_b128 v[144:147], v207
	v_mfma_f32_32x32x16_bf16 v[32:47], v[170:173], v[148:151], v[32:47]
	v_mfma_f32_32x32x16_bf16 v[48:63], v[174:177], v[148:151], v[48:63]
	ds_read_b128 v[148:151], v207 offset:4096
	v_mfma_f32_32x32x16_bf16 v[64:79], v[170:173], v[152:155], v[64:79]
	v_mfma_f32_32x32x16_bf16 v[80:95], v[174:177], v[152:155], v[80:95]
	ds_read_b128 v[152:155], v207 offset:8192
	v_mfma_f32_32x32x16_bf16 v[96:111], v[170:173], v[156:159], v[96:111]
	v_mfma_f32_32x32x16_bf16 v[112:127], v[174:177], v[156:159], v[112:127]
	ds_read_b128 v[156:159], v207 offset:12288
	ds_read_b128 v[170:173], v215
	ds_read_b128 v[174:177], v215 offset:4096
	s_waitcnt vmcnt(0) lgkmcnt(0)
	s_barrier
	s_add_u32 m0, s14, 0x0
	v_mfma_f32_32x32x16_bf16 v[0:15], v[162:165], v[128:131], v[0:15]
	global_load_lds_dwordx4 v220, s[22:23]
	s_add_u32 m0, s14, 0x8000
	v_mfma_f32_32x32x16_bf16 v[16:31], v[166:169], v[128:131], v[16:31]
	global_load_lds_dwordx4 v220, s[24:25]
	ds_read_b128 v[128:131], v208
	s_add_u32 m0, s14, 0x400
	v_mfma_f32_32x32x16_bf16 v[32:47], v[162:165], v[132:135], v[32:47]
	global_load_lds_dwordx4 v221, s[22:23]
	s_add_u32 m0, s14, 0x8400
	v_mfma_f32_32x32x16_bf16 v[48:63], v[166:169], v[132:135], v[48:63]
	global_load_lds_dwordx4 v221, s[24:25]
	ds_read_b128 v[132:135], v208 offset:4096
	s_add_u32 m0, s14, 0x800
	v_mfma_f32_32x32x16_bf16 v[64:79], v[162:165], v[136:139], v[64:79]
	global_load_lds_dwordx4 v222, s[22:23]
	s_add_u32 m0, s14, 0x8800
	v_mfma_f32_32x32x16_bf16 v[80:95], v[166:169], v[136:139], v[80:95]
	global_load_lds_dwordx4 v222, s[24:25]
	ds_read_b128 v[136:139], v208 offset:8192
	s_add_u32 m0, s14, 0xc00
	v_mfma_f32_32x32x16_bf16 v[96:111], v[162:165], v[140:143], v[96:111]
	global_load_lds_dwordx4 v223, s[22:23]
	s_add_u32 m0, s14, 0x8c00
	v_mfma_f32_32x32x16_bf16 v[112:127], v[166:169], v[140:143], v[112:127]
	global_load_lds_dwordx4 v223, s[24:25]
	ds_read_b128 v[140:143], v208 offset:12288
	ds_read_b128 v[162:165], v216
	ds_read_b128 v[166:169], v216 offset:4096
	v_mfma_f32_32x32x16_bf16 v[0:15], v[170:173], v[144:147], v[0:15]
	v_mfma_f32_32x32x16_bf16 v[16:31], v[174:177], v[144:147], v[16:31]
	ds_read_b128 v[144:147], v209
	v_mfma_f32_32x32x16_bf16 v[32:47], v[170:173], v[148:151], v[32:47]
	v_mfma_f32_32x32x16_bf16 v[48:63], v[174:177], v[148:151], v[48:63]
	ds_read_b128 v[148:151], v209 offset:4096
	v_mfma_f32_32x32x16_bf16 v[64:79], v[170:173], v[152:155], v[64:79]
	v_mfma_f32_32x32x16_bf16 v[80:95], v[174:177], v[152:155], v[80:95]
	ds_read_b128 v[152:155], v209 offset:8192
	v_mfma_f32_32x32x16_bf16 v[96:111], v[170:173], v[156:159], v[96:111]
	v_mfma_f32_32x32x16_bf16 v[112:127], v[174:177], v[156:159], v[112:127]
	ds_read_b128 v[156:159], v209 offset:12288
	ds_read_b128 v[170:173], v217
	ds_read_b128 v[174:177], v217 offset:4096
	s_add_u32 s22, s22, 0x80
	s_addc_u32 s23, s23, 0
	s_add_u32 s24, s24, 0x80
	s_addc_u32 s25, s25, 0
	s_add_u32 s26, s26, 1
	s_cmp_eq_u32 s26, 16
	s_cbranch_scc0 .Lri3_cadv_done
	s_mov_b32 s26, 0
	s_add_u32 s27, s27, s30
	s_cmp_lt_u32 s27, 0xa0
	s_cbranch_scc1 .Lri3_cadv_new
	s_sub_u32 s22, s22, 0x800
	s_subb_u32 s23, s23, 0
	s_sub_u32 s24, s24, 0x800
	s_subb_u32 s25, s25, 0
	s_branch .Lri3_cadv_done

; #define RAWBAR() { asm volatile("s_waitcnt vmcnt(0) lgkmcnt(0)" ::: "memory"); __builtin_amdgcn_s_barrier(); }
;     ...
;   if (V != 1) GLDS(0, 0);
;   RAWBAR();
;   for (int kt = 0; kt < nk; kt += 2) {
;     if (V != 1) GLDS(kt + 1, 1);
;     if (V != 2) COMPUTE(0);
;     RAWBAR();
;     if (V != 1) if (kt + 2 < nk) GLDS(kt + 2, 0);
;     if (V != 2) COMPUTE(1);
;     RAWBAR();
;   }
.Lri3_cadv_done:
	s_waitcnt lgkmcnt(6)
	v_mfma_f32_32x32x16_bf16 v[0:15], v[162:165], v[128:131], v[0:15]
	v_mfma_f32_32x32x16_bf16 v[16:31], v[166:169], v[128:131], v[16:31]
	ds_read_b128 v[128:131], v210
	v_mfma_f32_32x32x16_bf16 v[32:47], v[162:165], v[132:135], v[32:47]
	v_mfma_f32_32x32x16_bf16 v[48:63], v[166:169], v[132:135], v[48:63]
	ds_read_b128 v[132:135], v210 offset:4096
	v_mfma_f32_32x32x16_bf16 v[64:79], v[162:165], v[136:139], v[64:79]
	v_mfma_f32_32x32x16_bf16 v[80:95], v[166:169], v[136:139], v[80:95]
	ds_read_b128 v[136:139], v210 offset:8192
	v_mfma_f32_32x32x16_bf16 v[96:111], v[162:165], v[140:143], v[96:111]
	v_mfma_f32_32x32x16_bf16 v[112:127], v[166:169], v[140:143], v[112:127]
	ds_read_b128 v[140:143], v210 offset:12288
	ds_read_b128 v[162:165], v218
	ds_read_b128 v[166:169], v218 offset:4096
	s_waitcnt lgkmcnt(6)
	v_mfma_f32_32x32x16_bf16 v[0:15], v[170:173], v[144:147], v[0:15]
	v_mfma_f32_32x32x16_bf16 v[16:31], v[174:177], v[144:147], v[16:31]
	ds_read_b128 v[144:147], v211
	v_mfma_f32_32x32x16_bf16 v[32:47], v[170:173], v[148:151], v[32:47]
	v_mfma_f32_32x32x16_bf16 v[48:63], v[174:177], v[148:151], v[48:63]
	ds_read_b128 v[148:151], v211 offset:4096
	v_mfma_f32_32x32x16_bf16 v[64:79], v[170:173], v[152:155], v[64:79]
	v_mfma_f32_32x32x16_bf16 v[80:95], v[174:177], v[152:155], v[80:95]
	ds_read_b128 v[152:155], v211 offset:8192
	v_mfma_f32_32x32x16_bf16 v[96:111], v[170:173], v[156:159], v[96:111]
	v_mfma_f32_32x32x16_bf16 v[112:127], v[174:177], v[156:159], v[112:127]
	ds_read_b128 v[156:159], v211 offset:12288
	ds_read_b128 v[170:173], v219
	ds_read_b128 v[174:177], v219 offset:4096
	s_waitcnt vmcnt(0) lgkmcnt(0)
	s_barrier
	s_add_u32 m0, s14, 0x10000
	v_mfma_f32_32x32x16_bf16 v[0:15], v[162:165], v[128:131], v[0:15]
	global_load_lds_dwordx4 v220, s[22:23]
	s_add_u32 m0, s14, 0x18000
	v_mfma_f32_32x32x16_bf16 v[16:31], v[166:169], v[128:131], v[16:31]
	global_load_lds_dwordx4 v220, s[24:25]
	ds_read_b128 v[128:131], v204
	s_add_u32 m0, s14, 0x10400
	v_mfma_f32_32x32x16_bf16 v[32:47], v[162:165], v[132:135], v[32:47]
	global_load_lds_dwordx4 v221, s[22:23]
	s_add_u32 m0, s14, 0x18400
	v_mfma_f32_32x32x16_bf16 v[48:63], v[166:169], v[132:135], v[48:63]
	global_load_lds_dwordx4 v221, s[24:25]
	ds_read_b128 v[132:135], v204 offset:4096
	s_add_u32 m0, s14, 0x10800
	v_mfma_f32_32x32x16_bf16 v[64:79], v[162:165], v[136:139], v[64:79]
	global_load_lds_dwordx4 v222, s[22:23]
	s_add_u32 m0, s14, 0x18800
	v_mfma_f32_32x32x16_bf16 v[80:95], v[166:169], v[136:139], v[80:95]
	global_load_lds_dwordx4 v222, s[24:25]
	ds_read_b128 v[136:139], v204 offset:8192
	s_add_u32 m0, s14, 0x10c00
	v_mfma_f32_32x32x16_bf16 v[96:111], v[162:165], v[140:143], v[96:111]
	global_load_lds_dwordx4 v223, s[22:23]
	s_add_u32 m0, s14, 0x18c00
	v_mfma_f32_32x32x16_bf16 v[112:127], v[166:169], v[140:143], v[112:127]
	global_load_lds_dwordx4 v223, s[24:25]
	ds_read_b128 v[140:143], v204 offset:12288
	ds_read_b128 v[162:165], v212
	ds_read_b128 v[166:169], v212 offset:4096
	v_mfma_f32_32x32x16_bf16 v[0:15], v[170:173], v[144:147], v[0:15]
	v_mfma_f32_32x32x16_bf16 v[16:31], v[174:177], v[144:147], v[16:31]
	ds_read_b128 v[144:147], v205
	v_mfma_f32_32x32x16_bf16 v[32:47], v[170:173], v[148:151], v[32:47]
	v_mfma_f32_32x32x16_bf16 v[48:63], v[174:177], v[148:151], v[48:63]
	ds_read_b128 v[148:151], v205 offset:4096
	v_mfma_f32_32x32x16_bf16 v[64:79], v[170:173], v[152:155], v[64:79]
	v_mfma_f32_32x32x16_bf16 v[80:95], v[174:177], v[152:155], v[80:95]
	ds_read_b128 v[152:155], v205 offset:8192
	v_mfma_f32_32x32x16_bf16 v[96:111], v[170:173], v[156:159], v[96:111]
	v_mfma_f32_32x32x16_bf16 v[112:127], v[174:177], v[156:159], v[112:127]
	ds_read_b128 v[156:159], v205 offset:12288
	ds_read_b128 v[170:173], v213
	ds_read_b128 v[174:177], v213 offset:4096
	s_add_u32 s22, s22, 0x80
	s_addc_u32 s23, s23, 0
	s_add_u32 s24, s24, 0x80
	s_addc_u32 s25, s25, 0
	s_add_u32 s26, s26, 1
	s_cmp_eq_u32 s26, 16
	s_cbranch_scc0 .Lri4_cadv_done
	s_mov_b32 s26, 0
	s_add_u32 s27, s27, s30
	s_cmp_lt_u32 s27, 0xa0
	s_cbranch_scc1 .Lri4_cadv_new
	s_sub_u32 s22, s22, 0x800
	s_subb_u32 s23, s23, 0
	s_sub_u32 s24, s24, 0x800
	s_subb_u32 s25, s25, 0
	s_branch .Lri4_cadv_done

; #define RAWBAR() { asm volatile("s_waitcnt vmcnt(0) lgkmcnt(0)" ::: "memory"); __builtin_amdgcn_s_barrier(); }
;     ...
;   if (V != 1) GLDS(0, 0);
;   RAWBAR();
;   for (int kt = 0; kt < nk; kt += 2) {
;     if (V != 1) GLDS(kt + 1, 1);
;     if (V != 2) COMPUTE(0);
;     RAWBAR();
;     if (V != 1) if (kt + 2 < nk) GLDS(kt + 2, 0);
;     if (V != 2) COMPUTE(1);
;     RAWBAR();
;   }
.Lri_pair:
	s_waitcnt lgkmcnt(6)
	v_mfma_f32_32x32x16_bf16 v[0:15], v[162:165], v[128:131], v[0:15]
	v_mfma_f32_32x32x16_bf16 v[16:31], v[166:169], v[128:131], v[16:31]
	ds_read_b128 v[128:131], v206
	v_mfma_f32_32x32x16_bf16 v[32:47], v[162:165], v[132:135], v[32:47]
	v_mfma_f32_32x32x16_bf16 v[48:63], v[166:169], v[132:135], v[48:63]
	ds_read_b128 v[132:135], v206 offset:4096
	v_mfma_f32_32x32x16_bf16 v[64:79], v[162:165], v[136:139], v[64:79]
	v_mfma_f32_32x32x16_bf16 v[80:95], v[166:169], v[136:139], v[80:95]
	ds_read_b128 v[136:139], v206 offset:8192
	v_mfma_f32_32x32x16_bf16 v[96:111], v[162:165], v[140:143], v[96:111]
	v_mfma_f32_32x32x16_bf16 v[112:127], v[166:169], v[140:143], v[112:127]
	ds_read_b128 v[140:143], v206 offset:12288
	ds_read_b128 v[162:165], v214
	ds_read_b128 v[166:169], v214 offset:4096
	s_waitcnt lgkmcnt(6)
	v_mfma_f32_32x32x16_bf16 v[0:15], v[170:173], v[144:147], v[0:15]
	v_mfma_f32_32x32x16_bf16 v[16:31], v[174:177], v[144:147], v[16:31]
	ds_read_b128 v[144:147], v207
	v_mfma_f32_32x32x16_bf16 v[32:47], v[170:173], v[148:151], v[32:47]
	v_mfma_f32_32x32x16_bf16 v[48:63], v[174:177], v[148:151], v[48:63]
	ds_read_b128 v[148:151], v207 offset:4096
	v_mfma_f32_32x32x16_bf16 v[64:79], v[170:173], v[152:155], v[64:79]
	v_mfma_f32_32x32x16_bf16 v[80:95], v[174:177], v[152:155], v[80:95]
	ds_read_b128 v[152:155], v207 offset:8192
	v_mfma_f32_32x32x16_bf16 v[96:111], v[170:173], v[156:159], v[96:111]
	v_mfma_f32_32x32x16_bf16 v[112:127], v[174:177], v[156:159], v[112:127]
	ds_read_b128 v[156:159], v207 offset:12288
	ds_read_b128 v[170:173], v215
	ds_read_b128 v[174:177], v215 offset:4096
	s_waitcnt vmcnt(0) lgkmcnt(0)
	s_barrier
	s_add_u32 m0, s14, 0x0
	v_mfma_f32_32x32x16_bf16 v[0:15], v[162:165], v[128:131], v[0:15]
	global_load_lds_dwordx4 v220, s[22:23]
	s_add_u32 m0, s14, 0x8000
	v_mfma_f32_32x32x16_bf16 v[16:31], v[166:169], v[128:131], v[16:31]
	global_load_lds_dwordx4 v220, s[24:25]
	ds_read_b128 v[128:131], v208
	s_add_u32 m0, s14, 0x400
	v_mfma_f32_32x32x16_bf16 v[32:47], v[162:165], v[132:135], v[32:47]
	global_load_lds_dwordx4 v221, s[22:23]
	s_add_u32 m0, s14, 0x8400
	v_mfma_f32_32x32x16_bf16 v[48:63], v[166:169], v[132:135], v[48:63]
	global_load_lds_dwordx4 v221, s[24:25]
	ds_read_b128 v[132:135], v208 offset:4096
	s_add_u32 m0, s14, 0x800
	v_mfma_f32_32x32x16_bf16 v[64:79], v[162:165], v[136:139], v[64:79]
	global_load_lds_dwordx4 v222, s[22:23]
	s_add_u32 m0, s14, 0x8800
	v_mfma_f32_32x32x16_bf16 v[80:95], v[166:169], v[136:139], v[80:95]
	global_load_lds_dwordx4 v222, s[24:25]
	ds_read_b128 v[136:139], v208 offset:8192
	s_add_u32 m0, s14, 0xc00
	v_mfma_f32_32x32x16_bf16 v[96:111], v[162:165], v[140:143], v[96:111]
	global_load_lds_dwordx4 v223, s[22:23]
	s_add_u32 m0, s14, 0x8c00
	v_mfma_f32_32x32x16_bf16 v[112:127], v[166:169], v[140:143], v[112:127]
	global_load_lds_dwordx4 v223, s[24:25]
	ds_read_b128 v[140:143], v208 offset:12288
	ds_read_b128 v[162:165], v216
	ds_read_b128 v[166:169], v216 offset:4096
	v_mfma_f32_32x32x16_bf16 v[0:15], v[170:173], v[144:147], v[0:15]
	v_mfma_f32_32x32x16_bf16 v[16:31], v[174:177], v[144:147], v[16:31]
	ds_read_b128 v[144:147], v209
	v_mfma_f32_32x32x16_bf16 v[32:47], v[170:173], v[148:151], v[32:47]
	v_mfma_f32_32x32x16_bf16 v[48:63], v[174:177], v[148:151], v[48:63]
	ds_read_b128 v[148:151], v209 offset:4096
	v_mfma_f32_32x32x16_bf16 v[64:79], v[170:173], v[152:155], v[64:79]
	v_mfma_f32_32x32x16_bf16 v[80:95], v[174:177], v[152:155], v[80:95]
	ds_read_b128 v[152:155], v209 offset:8192
	v_mfma_f32_32x32x16_bf16 v[96:111], v[170:173], v[156:159], v[96:111]
	v_mfma_f32_32x32x16_bf16 v[112:127], v[174:177], v[156:159], v[112:127]
	ds_read_b128 v[156:159], v209 offset:12288
	ds_read_b128 v[170:173], v217
	ds_read_b128 v[174:177], v217 offset:4096
	s_add_u32 s22, s22, 0x80
	s_addc_u32 s23, s23, 0
	s_add_u32 s24, s24, 0x80
	s_addc_u32 s25, s25, 0
	s_add_u32 s26, s26, 1
	s_cmp_eq_u32 s26, 16
	s_cbranch_scc0 .Lri5_cadv_done
	s_mov_b32 s26, 0
	s_add_u32 s27, s27, s30
	s_cmp_lt_u32 s27, 0xa0
	s_cbranch_scc1 .Lri5_cadv_new
	s_sub_u32 s22, s22, 0x800
	s_subb_u32 s23, s23, 0
	s_sub_u32 s24, s24, 0x800
	s_subb_u32 s25, s25, 0
	s_branch .Lri5_cadv_done

; DI int crow(int r, int hf) { return (r & 3) + 8 * (r >> 2) + 4 * hf; }
; #define RAWBAR() { asm volatile("s_waitcnt vmcnt(0) lgkmcnt(0)" ::: "memory"); __builtin_amdgcn_s_barrier(); }
;     ...
;   if (V != 1) GLDS(0, 0);
;   RAWBAR();
;   for (int kt = 0; kt < nk; kt += 2) {
;     if (V != 1) GLDS(kt + 1, 1);
;     if (V != 2) COMPUTE(0);
;     RAWBAR();
;     if (V != 1) if (kt + 2 < nk) GLDS(kt + 2, 0);
;     if (V != 2) COMPUTE(1);
;     RAWBAR();
;   }
; DI void rec_in_phase(const Params& p, int j, char* smem) {
;     ...
; #pragma unroll
;           for (int jn = 0; jn < 2; ++jn) {
;             const int cl = C64 - 2048 + jn * 32 + l32_, g = cl >> 4, pp = cl & 15;
; #pragma unroll
;             for (int r = 0; r < 16; ++r) ug[((size_t)g * T_ + rb + crow(r, hf_)) * 16 + pp] = f2bf(acc[i][jn][r]);
;           }
.Lri7_cadv_done:
	s_waitcnt lgkmcnt(6)
	v_mfma_f32_32x32x16_bf16 v[0:15], v[162:165], v[128:131], v[0:15]
	v_mfma_f32_32x32x16_bf16 v[16:31], v[166:169], v[128:131], v[16:31]
	ds_read_b128 v[128:131], v210
	v_mfma_f32_32x32x16_bf16 v[32:47], v[162:165], v[132:135], v[32:47]
	v_mfma_f32_32x32x16_bf16 v[48:63], v[166:169], v[132:135], v[48:63]
	ds_read_b128 v[132:135], v210 offset:4096
	v_mfma_f32_32x32x16_bf16 v[64:79], v[162:165], v[136:139], v[64:79]
	v_mfma_f32_32x32x16_bf16 v[80:95], v[166:169], v[136:139], v[80:95]
	ds_read_b128 v[136:139], v210 offset:8192
	v_mfma_f32_32x32x16_bf16 v[96:111], v[162:165], v[140:143], v[96:111]
	v_mfma_f32_32x32x16_bf16 v[112:127], v[166:169], v[140:143], v[112:127]
	ds_read_b128 v[140:143], v210 offset:12288
	ds_read_b128 v[162:165], v218
	ds_read_b128 v[166:169], v218 offset:4096
	s_waitcnt lgkmcnt(6)
	v_mfma_f32_32x32x16_bf16 v[0:15], v[170:173], v[144:147], v[0:15]
	v_mfma_f32_32x32x16_bf16 v[16:31], v[174:177], v[144:147], v[16:31]
	ds_read_b128 v[144:147], v211
	v_mfma_f32_32x32x16_bf16 v[32:47], v[170:173], v[148:151], v[32:47]
	v_mfma_f32_32x32x16_bf16 v[48:63], v[174:177], v[148:151], v[48:63]
	ds_read_b128 v[148:151], v211 offset:4096
	v_mfma_f32_32x32x16_bf16 v[64:79], v[170:173], v[152:155], v[64:79]
	v_mfma_f32_32x32x16_bf16 v[80:95], v[174:177], v[152:155], v[80:95]
	ds_read_b128 v[152:155], v211 offset:8192
	v_mfma_f32_32x32x16_bf16 v[96:111], v[170:173], v[156:159], v[96:111]
	v_mfma_f32_32x32x16_bf16 v[112:127], v[174:177], v[156:159], v[112:127]
	ds_read_b128 v[156:159], v211 offset:12288
	ds_read_b128 v[170:173], v219
	ds_read_b128 v[174:177], v219 offset:4096
	s_waitcnt vmcnt(0) lgkmcnt(0)
	s_barrier
	s_add_u32 m0, s14, 0x10000
	v_mfma_f32_32x32x16_bf16 v[0:15], v[162:165], v[128:131], v[0:15]
	global_load_lds_dwordx4 v220, s[22:23]
	s_add_u32 m0, s14, 0x10400
	v_mfma_f32_32x32x16_bf16 v[16:31], v[166:169], v[128:131], v[16:31]
	global_load_lds_dwordx4 v221, s[22:23]
	s_add_u32 m0, s14, 0x10800
	v_mfma_f32_32x32x16_bf16 v[32:47], v[162:165], v[132:135], v[32:47]
	global_load_lds_dwordx4 v222, s[22:23]
	s_add_u32 m0, s14, 0x10c00
	v_mfma_f32_32x32x16_bf16 v[48:63], v[166:169], v[132:135], v[48:63]
	global_load_lds_dwordx4 v223, s[22:23]
	v_mfma_f32_32x32x16_bf16 v[64:79], v[162:165], v[136:139], v[64:79]
	v_mfma_f32_32x32x16_bf16 v[80:95], v[166:169], v[136:139], v[80:95]
	v_mfma_f32_32x32x16_bf16 v[96:111], v[162:165], v[140:143], v[96:111]
	v_mfma_f32_32x32x16_bf16 v[112:127], v[166:169], v[140:143], v[112:127]
	v_mfma_f32_32x32x16_bf16 v[0:15], v[170:173], v[144:147], v[0:15]
	v_mfma_f32_32x32x16_bf16 v[16:31], v[174:177], v[144:147], v[16:31]
	v_mfma_f32_32x32x16_bf16 v[32:47], v[170:173], v[148:151], v[32:47]
	v_mfma_f32_32x32x16_bf16 v[48:63], v[174:177], v[148:151], v[48:63]
	v_mfma_f32_32x32x16_bf16 v[64:79], v[170:173], v[152:155], v[64:79]
	v_mfma_f32_32x32x16_bf16 v[80:95], v[174:177], v[152:155], v[80:95]
	v_mfma_f32_32x32x16_bf16 v[96:111], v[170:173], v[156:159], v[96:111]
	v_mfma_f32_32x32x16_bf16 v[112:127], v[174:177], v[156:159], v[112:127]
	s_lshr_b32 s20, s28, 5
	s_lshl_b32 s20, s20, 1
	s_and_b32 s8, s28, 1
	s_add_u32 s20, s20, s8
	s_lshl_b32 s10, s31, 8
	s_add_u32 s10, s10, s12
	s_cmp_lt_u32 s20, 4
	s_cbranch_scc1 .Lri_epi_rope
	s_cmp_lt_u32 s20, 8
	s_cbranch_scc1 .Lri_epi_plain
	s_sub_u32 s8, s20, 8
	s_lshl_b32 s8, s8, 4
	s_lshl_b32 s9, s13, 2
	s_add_u32 s8, s8, s9
	s_lshl_b32 s8, s8, 15
	s_add_u32 s8, s8, s10
	s_lshl_b32 s8, s8, 5
	s_add_u32 s38, s4, s8
	s_addc_u32 s39, s5, 0
	s_add_u32 s38, s38, 0x15404100
	s_addc_u32 s39, s39, 0
	v_cvt_pk_bf16_f32 v240, v0, v1
	v_cvt_pk_bf16_f32 v241, v2, v3
	ds_write_b64 v178, v[240:241]
	v_cvt_pk_bf16_f32 v242, v4, v5
	v_cvt_pk_bf16_f32 v243, v6, v7
	ds_write_b64 v179, v[242:243]
	v_cvt_pk_bf16_f32 v244, v8, v9
	v_cvt_pk_bf16_f32 v245, v10, v11
	ds_write_b64 v180, v[244:245]
	v_cvt_pk_bf16_f32 v246, v12, v13
	v_cvt_pk_bf16_f32 v247, v14, v15
	ds_write_b64 v181, v[246:247]
	v_cvt_pk_bf16_f32 v240, v16, v17
	v_cvt_pk_bf16_f32 v241, v18, v19
	ds_write_b64 v188, v[240:241]
	v_cvt_pk_bf16_f32 v242, v20, v21
	v_cvt_pk_bf16_f32 v243, v22, v23
	ds_write_b64 v189, v[242:243]
	v_cvt_pk_bf16_f32 v244, v24, v25
	v_cvt_pk_bf16_f32 v245, v26, v27
	ds_write_b64 v190, v[244:245]
	v_cvt_pk_bf16_f32 v246, v28, v29
	v_cvt_pk_bf16_f32 v247, v30, v31
	ds_write_b64 v191, v[246:247]
	ds_read_b128 v[0:3], v194
	ds_read_b128 v[4:7], v194 offset:1024
	ds_read_b128 v[8:11], v194 offset:2048
	ds_read_b128 v[12:15], v194 offset:3072
	v_cvt_pk_bf16_f32 v240, v32, v33
	v_cvt_pk_bf16_f32 v241, v34, v35
	ds_write_b64 v178, v[240:241]
	v_cvt_pk_bf16_f32 v242, v36, v37
	v_cvt_pk_bf16_f32 v243, v38, v39
	ds_write_b64 v179, v[242:243]
	v_cvt_pk_bf16_f32 v244, v40, v41
	v_cvt_pk_bf16_f32 v245, v42, v43
	ds_write_b64 v180, v[244:245]
	v_cvt_pk_bf16_f32 v246, v44, v45
	v_cvt_pk_bf16_f32 v247, v46, v47
	ds_write_b64 v181, v[246:247]
	v_cvt_pk_bf16_f32 v240, v48, v49
	v_cvt_pk_bf16_f32 v241, v50, v51
	ds_write_b64 v188, v[240:241]
	v_cvt_pk_bf16_f32 v242, v52, v53
	v_cvt_pk_bf16_f32 v243, v54, v55
	ds_write_b64 v189, v[242:243]
	v_cvt_pk_bf16_f32 v244, v56, v57
	v_cvt_pk_bf16_f32 v245, v58, v59
	ds_write_b64 v190, v[244:245]
	v_cvt_pk_bf16_f32 v246, v60, v61
	v_cvt_pk_bf16_f32 v247, v62, v63
	ds_write_b64 v191, v[246:247]
	ds_read_b128 v[32:35], v194
	ds_read_b128 v[36:39], v194 offset:1024
	ds_read_b128 v[40:43], v194 offset:2048
	ds_read_b128 v[44:47], v194 offset:3072
	s_waitcnt lgkmcnt(12)
; DI int crow(int r, int hf) { return (r & 3) + 8 * (r >> 2) + 4 * hf; }
; DI void rec_in_phase(const Params& p, int j, char* smem) {
;     ...
;         } else if (C64 < 2048) {
; #pragma unroll
;           for (int jn = 0; jn < 2; ++jn)
; #pragma unroll
;             for (int r = 0; r < 16; ++r) zr[(size_t)(rb + crow(r, hf_)) * LDZR + C64 + jn * 32 + l32_] = f2bf(acc[i][jn][r]);
;         } else {
; #pragma unroll
;           for (int jn = 0; jn < 2; ++jn) {
;             const int cl = C64 - 2048 + jn * 32 + l32_, g = cl >> 4, pp = cl & 15;
; #pragma unroll
;             for (int r = 0; r < 16; ++r) ug[((size_t)g * T_ + rb + crow(r, hf_)) * 16 + pp] = f2bf(acc[i][jn][r]);
;           }
	global_store_dwordx4 v197, v[0:3], s[38:39] nt
	s_add_u32 s38, s38, 0x100
	s_addc_u32 s39, s39, 0
	global_store_dwordx4 v197, v[4:7], s[38:39] nt
	s_add_u32 s38, s38, 0x100
	s_addc_u32 s39, s39, 0
	global_store_dwordx4 v197, v[8:11], s[38:39] nt
	s_add_u32 s38, s38, 0x100
	s_addc_u32 s39, s39, 0
	global_store_dwordx4 v197, v[12:15], s[38:39] nt
	s_add_u32 s38, s38, 0x100
	s_addc_u32 s39, s39, 0
	v_cvt_pk_bf16_f32 v240, v64, v65
	v_cvt_pk_bf16_f32 v241, v66, v67
	ds_write_b64 v178, v[240:241]
	v_cvt_pk_bf16_f32 v242, v68, v69
	v_cvt_pk_bf16_f32 v243, v70, v71
	ds_write_b64 v179, v[242:243]
	v_cvt_pk_bf16_f32 v244, v72, v73
	v_cvt_pk_bf16_f32 v245, v74, v75
	ds_write_b64 v180, v[244:245]
	v_cvt_pk_bf16_f32 v246, v76, v77
	v_cvt_pk_bf16_f32 v247, v78, v79
	ds_write_b64 v181, v[246:247]
	v_cvt_pk_bf16_f32 v240, v80, v81
	v_cvt_pk_bf16_f32 v241, v82, v83
	ds_write_b64 v188, v[240:241]
	v_cvt_pk_bf16_f32 v242, v84, v85
	v_cvt_pk_bf16_f32 v243, v86, v87
	ds_write_b64 v189, v[242:243]
	v_cvt_pk_bf16_f32 v244, v88, v89
	v_cvt_pk_bf16_f32 v245, v90, v91
	ds_write_b64 v190, v[244:245]
	v_cvt_pk_bf16_f32 v246, v92, v93
	v_cvt_pk_bf16_f32 v247, v94, v95
	ds_write_b64 v191, v[246:247]
	ds_read_b128 v[64:67], v194
	ds_read_b128 v[68:71], v194 offset:1024
	ds_read_b128 v[72:75], v194 offset:2048
	ds_read_b128 v[76:79], v194 offset:3072
	s_waitcnt lgkmcnt(12)
	global_store_dwordx4 v197, v[32:35], s[38:39] nt
	s_add_u32 s38, s38, 0x100
	s_addc_u32 s39, s39, 0
	global_store_dwordx4 v197, v[36:39], s[38:39] nt
	s_add_u32 s38, s38, 0x100
	s_addc_u32 s39, s39, 0
	global_store_dwordx4 v197, v[40:43], s[38:39] nt
	s_add_u32 s38, s38, 0x100
	s_addc_u32 s39, s39, 0
	global_store_dwordx4 v197, v[44:47], s[38:39] nt
	s_add_u32 s38, s38, 0x100
	s_addc_u32 s39, s39, 0
	v_cvt_pk_bf16_f32 v240, v96, v97
	v_cvt_pk_bf16_f32 v241, v98, v99
	ds_write_b64 v178, v[240:241]
	v_cvt_pk_bf16_f32 v242, v100, v101
	v_cvt_pk_bf16_f32 v243, v102, v103
	ds_write_b64 v179, v[242:243]
	v_cvt_pk_bf16_f32 v244, v104, v105
	v_cvt_pk_bf16_f32 v245, v106, v107
	ds_write_b64 v180, v[244:245]
	v_cvt_pk_bf16_f32 v246, v108, v109
	v_cvt_pk_bf16_f32 v247, v110, v111
	ds_write_b64 v181, v[246:247]
	v_cvt_pk_bf16_f32 v240, v112, v113
	v_cvt_pk_bf16_f32 v241, v114, v115
	ds_write_b64 v188, v[240:241]
	v_cvt_pk_bf16_f32 v242, v116, v117
	v_cvt_pk_bf16_f32 v243, v118, v119
	ds_write_b64 v189, v[242:243]
	v_cvt_pk_bf16_f32 v244, v120, v121
	v_cvt_pk_bf16_f32 v245, v122, v123
	ds_write_b64 v190, v[244:245]
	v_cvt_pk_bf16_f32 v246, v124, v125
	v_cvt_pk_bf16_f32 v247, v126, v127
	ds_write_b64 v191, v[246:247]
	ds_read_b128 v[96:99], v194
	ds_read_b128 v[100:103], v194 offset:1024
	ds_read_b128 v[104:107], v194 offset:2048
	ds_read_b128 v[108:111], v194 offset:3072
	s_waitcnt lgkmcnt(12)
	global_store_dwordx4 v197, v[64:67], s[38:39] nt
	s_add_u32 s38, s38, 0x100
	s_addc_u32 s39, s39, 0
	global_store_dwordx4 v197, v[68:71], s[38:39] nt
	s_add_u32 s38, s38, 0x100
	s_addc_u32 s39, s39, 0
	global_store_dwordx4 v197, v[72:75], s[38:39] nt
	s_add_u32 s38, s38, 0x100
	s_addc_u32 s39, s39, 0
	global_store_dwordx4 v197, v[76:79], s[38:39] nt
	s_add_u32 s38, s38, 0x100
	s_addc_u32 s39, s39, 0
	s_waitcnt lgkmcnt(0)
	global_store_dwordx4 v197, v[96:99], s[38:39] nt
	s_add_u32 s38, s38, 0x100
	s_addc_u32 s39, s39, 0
	global_store_dwordx4 v197, v[100:103], s[38:39] nt
	s_add_u32 s38, s38, 0x100
	s_addc_u32 s39, s39, 0
	global_store_dwordx4 v197, v[104:107], s[38:39] nt
	s_add_u32 s38, s38, 0x100
	s_addc_u32 s39, s39, 0
	global_store_dwordx4 v197, v[108:111], s[38:39] nt
	s_branch .Lri_epi_done
.Lri_epi_plain:
	s_mul_i32 s8, s10, 0x1080
	s_lshl_b32 s9, s20, 9
	s_lshl_b32 s11, s13, 7
	s_add_u32 s9, s9, s11
	s_add_u32 s8, s8, s9
	s_add_u32 s38, s4, s8
	s_addc_u32 s39, s5, 0
	s_add_u32 s38, s38, 0xd004100
	s_addc_u32 s39, s39, 0
	v_cvt_pk_bf16_f32 v240, v0, v1
	v_cvt_pk_bf16_f32 v241, v2, v3
	ds_write_b64 v178, v[240:241]
	v_cvt_pk_bf16_f32 v242, v4, v5
	v_cvt_pk_bf16_f32 v243, v6, v7
	ds_write_b64 v179, v[242:243]
	v_cvt_pk_bf16_f32 v244, v8, v9
	v_cvt_pk_bf16_f32 v245, v10, v11
	ds_write_b64 v180, v[244:245]
	v_cvt_pk_bf16_f32 v246, v12, v13
	v_cvt_pk_bf16_f32 v247, v14, v15
	ds_write_b64 v181, v[246:247]
	v_cvt_pk_bf16_f32 v240, v16, v17
	v_cvt_pk_bf16_f32 v241, v18, v19
	ds_write_b64 v188, v[240:241]
	v_cvt_pk_bf16_f32 v242, v20, v21
	v_cvt_pk_bf16_f32 v243, v22, v23
	ds_write_b64 v189, v[242:243]
	v_cvt_pk_bf16_f32 v244, v24, v25
	v_cvt_pk_bf16_f32 v245, v26, v27
	ds_write_b64 v190, v[244:245]
	v_cvt_pk_bf16_f32 v246, v28, v29
	v_cvt_pk_bf16_f32 v247, v30, v31
	ds_write_b64 v191, v[246:247]
	ds_read_b128 v[0:3], v194
	ds_read_b128 v[4:7], v194 offset:1024
	ds_read_b128 v[8:11], v194 offset:2048
	ds_read_b128 v[12:15], v194 offset:3072
	v_cvt_pk_bf16_f32 v240, v32, v33
	v_cvt_pk_bf16_f32 v241, v34, v35
	ds_write_b64 v178, v[240:241]
	v_cvt_pk_bf16_f32 v242, v36, v37
	v_cvt_pk_bf16_f32 v243, v38, v39
	ds_write_b64 v179, v[242:243]
	v_cvt_pk_bf16_f32 v244, v40, v41
	v_cvt_pk_bf16_f32 v245, v42, v43
	ds_write_b64 v180, v[244:245]
	v_cvt_pk_bf16_f32 v246, v44, v45
	v_cvt_pk_bf16_f32 v247, v46, v47
	ds_write_b64 v181, v[246:247]
	v_cvt_pk_bf16_f32 v240, v48, v49
	v_cvt_pk_bf16_f32 v241, v50, v51
	ds_write_b64 v188, v[240:241]
	v_cvt_pk_bf16_f32 v242, v52, v53
	v_cvt_pk_bf16_f32 v243, v54, v55
	ds_write_b64 v189, v[242:243]
	v_cvt_pk_bf16_f32 v244, v56, v57
	v_cvt_pk_bf16_f32 v245, v58, v59
	ds_write_b64 v190, v[244:245]
	v_cvt_pk_bf16_f32 v246, v60, v61
	v_cvt_pk_bf16_f32 v247, v62, v63
	ds_write_b64 v191, v[246:247]
	ds_read_b128 v[32:35], v194
	ds_read_b128 v[36:39], v194 offset:1024
	ds_read_b128 v[40:43], v194 offset:2048
	ds_read_b128 v[44:47], v194 offset:3072
	s_waitcnt lgkmcnt(12)
; DI int crow(int r, int hf) { return (r & 3) + 8 * (r >> 2) + 4 * hf; }
; DI void rec_in_phase(const Params& p, int j, char* smem) {
;     ...
;         if (C64 < 1024) {
;           const int fi = ((C64 & 127) >> 1) + l32_, cbase = C64 & ~127;
;           const float sc = (C64 >= 512) ? RET_KSCALE : 1.f;
; #pragma unroll
;           for (int r = 0; r < 16; ++r) {
;             const int t = rb + crow(r, hf_), pos = t & (S_ - 1);
;             const float2 cs = rt128[pos * 64 + fi];
;             const float x1 = acc[i][0][r], x2 = acc[i][1][r];
;             zr[(size_t)t * LDZR + cbase + fi] = f2bf((x1 * cs.x - x2 * cs.y) * sc);
;             zr[(size_t)t * LDZR + cbase + 64 + fi] = f2bf((x2 * cs.x + x1 * cs.y) * sc);
;           }
;         } else if (C64 < 2048) {
; #pragma unroll
;           for (int jn = 0; jn < 2; ++jn)
; #pragma unroll
;             for (int r = 0; r < 16; ++r) zr[(size_t)(rb + crow(r, hf_)) * LDZR + C64 + jn * 32 + l32_] = f2bf(acc[i][jn][r]);
	global_store_dwordx4 v195, v[0:3], s[38:39] nt
	s_add_u32 s38, s38, 0x8400
	s_addc_u32 s39, s39, 0
	global_store_dwordx4 v195, v[4:7], s[38:39] nt
	s_add_u32 s38, s38, 0x8400
	s_addc_u32 s39, s39, 0
	global_store_dwordx4 v195, v[8:11], s[38:39] nt
	s_add_u32 s38, s38, 0x8400
	s_addc_u32 s39, s39, 0
	global_store_dwordx4 v195, v[12:15], s[38:39] nt
	s_add_u32 s38, s38, 0x8400
	s_addc_u32 s39, s39, 0
	v_cvt_pk_bf16_f32 v240, v64, v65
	v_cvt_pk_bf16_f32 v241, v66, v67
	ds_write_b64 v178, v[240:241]
	v_cvt_pk_bf16_f32 v242, v68, v69
	v_cvt_pk_bf16_f32 v243, v70, v71
	ds_write_b64 v179, v[242:243]
	v_cvt_pk_bf16_f32 v244, v72, v73
	v_cvt_pk_bf16_f32 v245, v74, v75
	ds_write_b64 v180, v[244:245]
	v_cvt_pk_bf16_f32 v246, v76, v77
	v_cvt_pk_bf16_f32 v247, v78, v79
	ds_write_b64 v181, v[246:247]
	v_cvt_pk_bf16_f32 v240, v80, v81
	v_cvt_pk_bf16_f32 v241, v82, v83
	ds_write_b64 v188, v[240:241]
	v_cvt_pk_bf16_f32 v242, v84, v85
	v_cvt_pk_bf16_f32 v243, v86, v87
	ds_write_b64 v189, v[242:243]
	v_cvt_pk_bf16_f32 v244, v88, v89
	v_cvt_pk_bf16_f32 v245, v90, v91
	ds_write_b64 v190, v[244:245]
	v_cvt_pk_bf16_f32 v246, v92, v93
	v_cvt_pk_bf16_f32 v247, v94, v95
	ds_write_b64 v191, v[246:247]
	ds_read_b128 v[64:67], v194
	ds_read_b128 v[68:71], v194 offset:1024
	ds_read_b128 v[72:75], v194 offset:2048
	ds_read_b128 v[76:79], v194 offset:3072
	s_waitcnt lgkmcnt(12)
	global_store_dwordx4 v195, v[32:35], s[38:39] nt
	s_add_u32 s38, s38, 0x8400
	s_addc_u32 s39, s39, 0
	global_store_dwordx4 v195, v[36:39], s[38:39] nt
	s_add_u32 s38, s38, 0x8400
	s_addc_u32 s39, s39, 0
	global_store_dwordx4 v195, v[40:43], s[38:39] nt
	s_add_u32 s38, s38, 0x8400
	s_addc_u32 s39, s39, 0
	global_store_dwordx4 v195, v[44:47], s[38:39] nt
	s_add_u32 s38, s38, 0x8400
	s_addc_u32 s39, s39, 0
	v_cvt_pk_bf16_f32 v240, v96, v97
	v_cvt_pk_bf16_f32 v241, v98, v99
	ds_write_b64 v178, v[240:241]
	v_cvt_pk_bf16_f32 v242, v100, v101
	v_cvt_pk_bf16_f32 v243, v102, v103
	ds_write_b64 v179, v[242:243]
	v_cvt_pk_bf16_f32 v244, v104, v105
	v_cvt_pk_bf16_f32 v245, v106, v107
	ds_write_b64 v180, v[244:245]
	v_cvt_pk_bf16_f32 v246, v108, v109
	v_cvt_pk_bf16_f32 v247, v110, v111
	ds_write_b64 v181, v[246:247]
	v_cvt_pk_bf16_f32 v240, v112, v113
	v_cvt_pk_bf16_f32 v241, v114, v115
	ds_write_b64 v188, v[240:241]
	v_cvt_pk_bf16_f32 v242, v116, v117
	v_cvt_pk_bf16_f32 v243, v118, v119
	ds_write_b64 v189, v[242:243]
	v_cvt_pk_bf16_f32 v244, v120, v121
	v_cvt_pk_bf16_f32 v245, v122, v123
	ds_write_b64 v190, v[244:245]
	v_cvt_pk_bf16_f32 v246, v124, v125
	v_cvt_pk_bf16_f32 v247, v126, v127
	ds_write_b64 v191, v[246:247]
	ds_read_b128 v[96:99], v194
	ds_read_b128 v[100:103], v194 offset:1024
	ds_read_b128 v[104:107], v194 offset:2048
	ds_read_b128 v[108:111], v194 offset:3072
	s_waitcnt lgkmcnt(12)
	global_store_dwordx4 v195, v[64:67], s[38:39] nt
	s_add_u32 s38, s38, 0x8400
	s_addc_u32 s39, s39, 0
	global_store_dwordx4 v195, v[68:71], s[38:39] nt
	s_add_u32 s38, s38, 0x8400
	s_addc_u32 s39, s39, 0
	global_store_dwordx4 v195, v[72:75], s[38:39] nt
	s_add_u32 s38, s38, 0x8400
	s_addc_u32 s39, s39, 0
	global_store_dwordx4 v195, v[76:79], s[38:39] nt
	s_add_u32 s38, s38, 0x8400
	s_addc_u32 s39, s39, 0
	s_waitcnt lgkmcnt(0)
	global_store_dwordx4 v195, v[96:99], s[38:39] nt
	s_add_u32 s38, s38, 0x8400
	s_addc_u32 s39, s39, 0
	global_store_dwordx4 v195, v[100:103], s[38:39] nt
	s_add_u32 s38, s38, 0x8400
	s_addc_u32 s39, s39, 0
	global_store_dwordx4 v195, v[104:107], s[38:39] nt
	s_add_u32 s38, s38, 0x8400
	s_addc_u32 s39, s39, 0
	global_store_dwordx4 v195, v[108:111], s[38:39] nt
	s_branch .Lri_epi_done
.Lri_epi_rope:
	s_mul_i32 s8, s10, 0x1080
	s_lshl_b32 s9, s20, 9
	s_lshr_b32 s11, s13, 1
	s_lshl_b32 s11, s11, 8
	s_add_u32 s9, s9, s11
	s_and_b32 s11, s13, 1
	s_lshl_b32 s11, s11, 6
	s_add_u32 s9, s9, s11
	s_add_u32 s8, s8, s9
	s_add_u32 s38, s4, s8
	s_addc_u32 s39, s5, 0
	s_add_u32 s38, s38, 0xd004100
	s_addc_u32 s39, s39, 0
	s_cmp_lt_u32 s20, 2
	s_cselect_b32 s20, 1.0, 0x3db504f3
	s_mov_b64 s[100:101], s[36:37]
	s_add_u32 s8, s36, 0x0
	s_addc_u32 s9, s37, 0
	global_load_dwordx4 v[128:131], v160, s[8:9]
	global_load_dwordx4 v[132:135], v160, s[8:9] offset:16
	s_add_u32 s8, s36, 0x0
	s_addc_u32 s9, s37, 0
	global_load_dwordx4 v[136:139], v160, s[8:9] offset:64
	global_load_dwordx4 v[140:143], v160, s[8:9] offset:80
	s_add_u32 s8, s36, 0x0
	s_addc_u32 s9, s37, 0
	global_load_dwordx4 v[144:147], v160, s[8:9] offset:128
	global_load_dwordx4 v[148:151], v160, s[8:9] offset:144
	s_add_u32 s8, s36, 0x0
	s_addc_u32 s9, s37, 0
	global_load_dwordx4 v[152:155], v160, s[8:9] offset:192
	global_load_dwordx4 v[156:159], v160, s[8:9] offset:208
	s_add_u32 s8, s36, 0x4000
	s_addc_u32 s9, s37, 0
	global_load_dwordx4 v[162:165], v160, s[8:9]
	global_load_dwordx4 v[166:169], v160, s[8:9] offset:16
	s_add_u32 s8, s36, 0x4000
	s_addc_u32 s9, s37, 0
	global_load_dwordx4 v[170:173], v160, s[8:9] offset:64
	global_load_dwordx4 v[174:177], v160, s[8:9] offset:80
	s_add_u32 s8, s36, 0x4000
	s_addc_u32 s9, s37, 0
	global_load_dwordx4 v[224:227], v160, s[8:9] offset:128
	global_load_dwordx4 v[228:231], v160, s[8:9] offset:144
	s_add_u32 s8, s36, 0x4000
	s_addc_u32 s9, s37, 0
	global_load_dwordx4 v[232:235], v160, s[8:9] offset:192
	global_load_dwordx4 v[236:239], v160, s[8:9] offset:208
	s_waitcnt vmcnt(14)
; DI int crow(int r, int hf) { return (r & 3) + 8 * (r >> 2) + 4 * hf; }
; DI void rec_in_phase(const Params& p, int j, char* smem) {
;     ...
;         if (C64 < 1024) {
;           const int fi = ((C64 & 127) >> 1) + l32_, cbase = C64 & ~127;
;           const float sc = (C64 >= 512) ? RET_KSCALE : 1.f;
; #pragma unroll
;           for (int r = 0; r < 16; ++r) {
;             const int t = rb + crow(r, hf_), pos = t & (S_ - 1);
;             const float2 cs = rt128[pos * 64 + fi];
;             const float x1 = acc[i][0][r], x2 = acc[i][1][r];
;             zr[(size_t)t * LDZR + cbase + fi] = f2bf((x1 * cs.x - x2 * cs.y) * sc);
;             zr[(size_t)t * LDZR + cbase + 64 + fi] = f2bf((x2 * cs.x + x1 * cs.y) * sc);
;           }
	v_mul_f32_e32 v246, v16, v129
	v_mul_f32_e32 v247, v0, v129
	v_fma_f32 v0, v0, v128, -v246
	v_fma_f32 v16, v16, v128, v247
	v_mul_f32_e32 v0, s20, v0
	v_mul_f32_e32 v16, s20, v16
	v_mul_f32_e32 v246, v17, v131
	v_mul_f32_e32 v247, v1, v131
	v_fma_f32 v1, v1, v130, -v246
	v_fma_f32 v17, v17, v130, v247
	v_mul_f32_e32 v1, s20, v1
	v_mul_f32_e32 v17, s20, v17
	v_mul_f32_e32 v246, v18, v133
	v_mul_f32_e32 v247, v2, v133
	v_fma_f32 v2, v2, v132, -v246
	v_fma_f32 v18, v18, v132, v247
	v_mul_f32_e32 v2, s20, v2
	v_mul_f32_e32 v18, s20, v18
	v_mul_f32_e32 v246, v19, v135
	v_mul_f32_e32 v247, v3, v135
	v_fma_f32 v3, v3, v134, -v246
	v_fma_f32 v19, v19, v134, v247
	v_mul_f32_e32 v3, s20, v3
	v_mul_f32_e32 v19, s20, v19
	s_add_u32 s8, s36, 0x8000
	s_addc_u32 s9, s37, 0
	global_load_dwordx4 v[128:131], v160, s[8:9]
	global_load_dwordx4 v[132:135], v160, s[8:9] offset:16
	s_waitcnt vmcnt(14)
	v_mul_f32_e32 v246, v20, v137
	v_mul_f32_e32 v247, v4, v137
	v_fma_f32 v4, v4, v136, -v246
	v_fma_f32 v20, v20, v136, v247
	v_mul_f32_e32 v4, s20, v4
	v_mul_f32_e32 v20, s20, v20
	v_mul_f32_e32 v246, v21, v139
	v_mul_f32_e32 v247, v5, v139
	v_fma_f32 v5, v5, v138, -v246
	v_fma_f32 v21, v21, v138, v247
	v_mul_f32_e32 v5, s20, v5
	v_mul_f32_e32 v21, s20, v21
	v_mul_f32_e32 v246, v22, v141
	v_mul_f32_e32 v247, v6, v141
	v_fma_f32 v6, v6, v140, -v246
	v_fma_f32 v22, v22, v140, v247
	v_mul_f32_e32 v6, s20, v6
	v_mul_f32_e32 v22, s20, v22
	v_mul_f32_e32 v246, v23, v143
	v_mul_f32_e32 v247, v7, v143
	v_fma_f32 v7, v7, v142, -v246
	v_fma_f32 v23, v23, v142, v247
	v_mul_f32_e32 v7, s20, v7
	v_mul_f32_e32 v23, s20, v23
	s_add_u32 s8, s36, 0x8000
	s_addc_u32 s9, s37, 0
	global_load_dwordx4 v[136:139], v160, s[8:9] offset:64
	global_load_dwordx4 v[140:143], v160, s[8:9] offset:80
	s_waitcnt vmcnt(14)
	v_mul_f32_e32 v246, v24, v145
	v_mul_f32_e32 v247, v8, v145
	v_fma_f32 v8, v8, v144, -v246
	v_fma_f32 v24, v24, v144, v247
	v_mul_f32_e32 v8, s20, v8
	v_mul_f32_e32 v24, s20, v24
	v_mul_f32_e32 v246, v25, v147
	v_mul_f32_e32 v247, v9, v147
	v_fma_f32 v9, v9, v146, -v246
	v_fma_f32 v25, v25, v146, v247
	v_mul_f32_e32 v9, s20, v9
	v_mul_f32_e32 v25, s20, v25
	v_mul_f32_e32 v246, v26, v149
	v_mul_f32_e32 v247, v10, v149
	v_fma_f32 v10, v10, v148, -v246
	v_fma_f32 v26, v26, v148, v247
	v_mul_f32_e32 v10, s20, v10
	v_mul_f32_e32 v26, s20, v26
	v_mul_f32_e32 v246, v27, v151
	v_mul_f32_e32 v247, v11, v151
	v_fma_f32 v11, v11, v150, -v246
	v_fma_f32 v27, v27, v150, v247
	v_mul_f32_e32 v11, s20, v11
	v_mul_f32_e32 v27, s20, v27
	s_add_u32 s8, s36, 0x8000
	s_addc_u32 s9, s37, 0
	global_load_dwordx4 v[144:147], v160, s[8:9] offset:128
	global_load_dwordx4 v[148:151], v160, s[8:9] offset:144
	s_waitcnt vmcnt(14)
	v_mul_f32_e32 v246, v28, v153
	v_mul_f32_e32 v247, v12, v153
	v_fma_f32 v12, v12, v152, -v246
	v_fma_f32 v28, v28, v152, v247
	v_mul_f32_e32 v12, s20, v12
	v_mul_f32_e32 v28, s20, v28
	v_mul_f32_e32 v246, v29, v155
	v_mul_f32_e32 v247, v13, v155
	v_fma_f32 v13, v13, v154, -v246
	v_fma_f32 v29, v29, v154, v247
	v_mul_f32_e32 v13, s20, v13
	v_mul_f32_e32 v29, s20, v29
	v_mul_f32_e32 v246, v30, v157
	v_mul_f32_e32 v247, v14, v157
	v_fma_f32 v14, v14, v156, -v246
	v_fma_f32 v30, v30, v156, v247
	v_mul_f32_e32 v14, s20, v14
	v_mul_f32_e32 v30, s20, v30
	v_mul_f32_e32 v246, v31, v159
	v_mul_f32_e32 v247, v15, v159
	v_fma_f32 v15, v15, v158, -v246
	v_fma_f32 v31, v31, v158, v247
	v_mul_f32_e32 v15, s20, v15
	v_mul_f32_e32 v31, s20, v31
	s_add_u32 s8, s36, 0x8000
	s_addc_u32 s9, s37, 0
	global_load_dwordx4 v[152:155], v160, s[8:9] offset:192
	global_load_dwordx4 v[156:159], v160, s[8:9] offset:208
	v_cvt_pk_bf16_f32 v240, v0, v1
	v_cvt_pk_bf16_f32 v241, v2, v3
	ds_write_b64 v178, v[240:241]
	v_cvt_pk_bf16_f32 v242, v4, v5
	v_cvt_pk_bf16_f32 v243, v6, v7
	ds_write_b64 v179, v[242:243]
	v_cvt_pk_bf16_f32 v244, v8, v9
	v_cvt_pk_bf16_f32 v245, v10, v11
	ds_write_b64 v180, v[244:245]
	v_cvt_pk_bf16_f32 v240, v12, v13
	v_cvt_pk_bf16_f32 v241, v14, v15
	ds_write_b64 v181, v[240:241]
	v_cvt_pk_bf16_f32 v242, v16, v17
	v_cvt_pk_bf16_f32 v243, v18, v19
	ds_write_b64 v188, v[242:243]
	v_cvt_pk_bf16_f32 v244, v20, v21
	v_cvt_pk_bf16_f32 v245, v22, v23
	ds_write_b64 v189, v[244:245]
	v_cvt_pk_bf16_f32 v240, v24, v25
	v_cvt_pk_bf16_f32 v241, v26, v27
	ds_write_b64 v190, v[240:241]
	v_cvt_pk_bf16_f32 v242, v28, v29
	v_cvt_pk_bf16_f32 v243, v30, v31
	ds_write_b64 v191, v[242:243]
	ds_read_b128 v[0:3], v194
	ds_read_b128 v[4:7], v194 offset:1024
	ds_read_b128 v[8:11], v194 offset:2048
	ds_read_b128 v[12:15], v194 offset:3072
	s_waitcnt vmcnt(14)
	v_mul_f32_e32 v246, v48, v163
	v_mul_f32_e32 v247, v32, v163
	v_fma_f32 v32, v32, v162, -v246
	v_fma_f32 v48, v48, v162, v247
	v_mul_f32_e32 v32, s20, v32
	v_mul_f32_e32 v48, s20, v48
	v_mul_f32_e32 v246, v49, v165
	v_mul_f32_e32 v247, v33, v165
	v_fma_f32 v33, v33, v164, -v246
	v_fma_f32 v49, v49, v164, v247
	v_mul_f32_e32 v33, s20, v33
	v_mul_f32_e32 v49, s20, v49
	v_mul_f32_e32 v246, v50, v167
	v_mul_f32_e32 v247, v34, v167
	v_fma_f32 v34, v34, v166, -v246
	v_fma_f32 v50, v50, v166, v247
	v_mul_f32_e32 v34, s20, v34
	v_mul_f32_e32 v50, s20, v50
	v_mul_f32_e32 v246, v51, v169
	v_mul_f32_e32 v247, v35, v169
	v_fma_f32 v35, v35, v168, -v246
	v_fma_f32 v51, v51, v168, v247
	v_mul_f32_e32 v35, s20, v35
	v_mul_f32_e32 v51, s20, v51
	s_add_u32 s8, s36, 0xc000
	s_addc_u32 s9, s37, 0
	global_load_dwordx4 v[162:165], v160, s[8:9]
	global_load_dwordx4 v[166:169], v160, s[8:9] offset:16
	s_waitcnt vmcnt(14)
; DI int crow(int r, int hf) { return (r & 3) + 8 * (r >> 2) + 4 * hf; }
; DI void rec_in_phase(const Params& p, int j, char* smem) {
;     ...
;         if (C64 < 1024) {
;           const int fi = ((C64 & 127) >> 1) + l32_, cbase = C64 & ~127;
;           const float sc = (C64 >= 512) ? RET_KSCALE : 1.f;
; #pragma unroll
;           for (int r = 0; r < 16; ++r) {
;             const int t = rb + crow(r, hf_), pos = t & (S_ - 1);
;             const float2 cs = rt128[pos * 64 + fi];
;             const float x1 = acc[i][0][r], x2 = acc[i][1][r];
;             zr[(size_t)t * LDZR + cbase + fi] = f2bf((x1 * cs.x - x2 * cs.y) * sc);
;             zr[(size_t)t * LDZR + cbase + 64 + fi] = f2bf((x2 * cs.x + x1 * cs.y) * sc);
;           }
	v_mul_f32_e32 v246, v52, v171
	v_mul_f32_e32 v247, v36, v171
	v_fma_f32 v36, v36, v170, -v246
	v_fma_f32 v52, v52, v170, v247
	v_mul_f32_e32 v36, s20, v36
	v_mul_f32_e32 v52, s20, v52
	v_mul_f32_e32 v246, v53, v173
	v_mul_f32_e32 v247, v37, v173
	v_fma_f32 v37, v37, v172, -v246
	v_fma_f32 v53, v53, v172, v247
	v_mul_f32_e32 v37, s20, v37
	v_mul_f32_e32 v53, s20, v53
	v_mul_f32_e32 v246, v54, v175
	v_mul_f32_e32 v247, v38, v175
	v_fma_f32 v38, v38, v174, -v246
	v_fma_f32 v54, v54, v174, v247
	v_mul_f32_e32 v38, s20, v38
	v_mul_f32_e32 v54, s20, v54
	v_mul_f32_e32 v246, v55, v177
	v_mul_f32_e32 v247, v39, v177
	v_fma_f32 v39, v39, v176, -v246
	v_fma_f32 v55, v55, v176, v247
	v_mul_f32_e32 v39, s20, v39
	v_mul_f32_e32 v55, s20, v55
	s_add_u32 s8, s36, 0xc000
	s_addc_u32 s9, s37, 0
	global_load_dwordx4 v[170:173], v160, s[8:9] offset:64
	global_load_dwordx4 v[174:177], v160, s[8:9] offset:80
	s_waitcnt vmcnt(14)
	v_mul_f32_e32 v246, v56, v225
	v_mul_f32_e32 v247, v40, v225
	v_fma_f32 v40, v40, v224, -v246
	v_fma_f32 v56, v56, v224, v247
	v_mul_f32_e32 v40, s20, v40
	v_mul_f32_e32 v56, s20, v56
	v_mul_f32_e32 v246, v57, v227
	v_mul_f32_e32 v247, v41, v227
	v_fma_f32 v41, v41, v226, -v246
	v_fma_f32 v57, v57, v226, v247
	v_mul_f32_e32 v41, s20, v41
	v_mul_f32_e32 v57, s20, v57
	v_mul_f32_e32 v246, v58, v229
	v_mul_f32_e32 v247, v42, v229
	v_fma_f32 v42, v42, v228, -v246
	v_fma_f32 v58, v58, v228, v247
	v_mul_f32_e32 v42, s20, v42
	v_mul_f32_e32 v58, s20, v58
	v_mul_f32_e32 v246, v59, v231
	v_mul_f32_e32 v247, v43, v231
	v_fma_f32 v43, v43, v230, -v246
	v_fma_f32 v59, v59, v230, v247
	v_mul_f32_e32 v43, s20, v43
	v_mul_f32_e32 v59, s20, v59
	s_add_u32 s8, s36, 0xc000
	s_addc_u32 s9, s37, 0
	global_load_dwordx4 v[224:227], v160, s[8:9] offset:128
	global_load_dwordx4 v[228:231], v160, s[8:9] offset:144
	s_waitcnt vmcnt(14)
	v_mul_f32_e32 v246, v60, v233
	v_mul_f32_e32 v247, v44, v233
	v_fma_f32 v44, v44, v232, -v246
	v_fma_f32 v60, v60, v232, v247
	v_mul_f32_e32 v44, s20, v44
	v_mul_f32_e32 v60, s20, v60
	v_mul_f32_e32 v246, v61, v235
	v_mul_f32_e32 v247, v45, v235
	v_fma_f32 v45, v45, v234, -v246
	v_fma_f32 v61, v61, v234, v247
	v_mul_f32_e32 v45, s20, v45
	v_mul_f32_e32 v61, s20, v61
	v_mul_f32_e32 v246, v62, v237
	v_mul_f32_e32 v247, v46, v237
	v_fma_f32 v46, v46, v236, -v246
	v_fma_f32 v62, v62, v236, v247
	v_mul_f32_e32 v46, s20, v46
	v_mul_f32_e32 v62, s20, v62
	v_mul_f32_e32 v246, v63, v239
	v_mul_f32_e32 v247, v47, v239
	v_fma_f32 v47, v47, v238, -v246
	v_fma_f32 v63, v63, v238, v247
	v_mul_f32_e32 v47, s20, v47
	v_mul_f32_e32 v63, s20, v63
	s_add_u32 s8, s36, 0xc000
	s_addc_u32 s9, s37, 0
	global_load_dwordx4 v[232:235], v160, s[8:9] offset:192
	global_load_dwordx4 v[236:239], v160, s[8:9] offset:208
	v_cvt_pk_bf16_f32 v244, v32, v33
	v_cvt_pk_bf16_f32 v245, v34, v35
	ds_write_b64 v178, v[244:245]
	v_cvt_pk_bf16_f32 v240, v36, v37
	v_cvt_pk_bf16_f32 v241, v38, v39
	ds_write_b64 v179, v[240:241]
	v_cvt_pk_bf16_f32 v242, v40, v41
	v_cvt_pk_bf16_f32 v243, v42, v43
	ds_write_b64 v180, v[242:243]
	v_cvt_pk_bf16_f32 v244, v44, v45
	v_cvt_pk_bf16_f32 v245, v46, v47
	ds_write_b64 v181, v[244:245]
	v_cvt_pk_bf16_f32 v240, v48, v49
	v_cvt_pk_bf16_f32 v241, v50, v51
	ds_write_b64 v188, v[240:241]
	v_cvt_pk_bf16_f32 v242, v52, v53
	v_cvt_pk_bf16_f32 v243, v54, v55
	ds_write_b64 v189, v[242:243]
	v_cvt_pk_bf16_f32 v244, v56, v57
	v_cvt_pk_bf16_f32 v245, v58, v59
	ds_write_b64 v190, v[244:245]
	v_cvt_pk_bf16_f32 v240, v60, v61
	v_cvt_pk_bf16_f32 v241, v62, v63
	ds_write_b64 v191, v[240:241]
	ds_read_b128 v[32:35], v194
	ds_read_b128 v[36:39], v194 offset:1024
	ds_read_b128 v[40:43], v194 offset:2048
	ds_read_b128 v[44:47], v194 offset:3072
	s_waitcnt lgkmcnt(12)
	global_store_dwordx4 v196, v[0:3], s[38:39] nt
	s_add_u32 s38, s38, 0x8400
	s_addc_u32 s39, s39, 0
	global_store_dwordx4 v196, v[4:7], s[38:39] nt
	s_add_u32 s38, s38, 0x8400
	s_addc_u32 s39, s39, 0
	global_store_dwordx4 v196, v[8:11], s[38:39] nt
	s_add_u32 s38, s38, 0x8400
	s_addc_u32 s39, s39, 0
	global_store_dwordx4 v196, v[12:15], s[38:39] nt
	s_add_u32 s38, s38, 0x8400
	s_addc_u32 s39, s39, 0
	s_waitcnt vmcnt(18)
	v_mul_f32_e32 v246, v80, v129
	v_mul_f32_e32 v247, v64, v129
	v_fma_f32 v64, v64, v128, -v246
	v_fma_f32 v80, v80, v128, v247
	v_mul_f32_e32 v64, s20, v64
	v_mul_f32_e32 v80, s20, v80
	v_mul_f32_e32 v246, v81, v131
	v_mul_f32_e32 v247, v65, v131
	v_fma_f32 v65, v65, v130, -v246
	v_fma_f32 v81, v81, v130, v247
	v_mul_f32_e32 v65, s20, v65
	v_mul_f32_e32 v81, s20, v81
	v_mul_f32_e32 v246, v82, v133
	v_mul_f32_e32 v247, v66, v133
	v_fma_f32 v66, v66, v132, -v246
	v_fma_f32 v82, v82, v132, v247
	v_mul_f32_e32 v66, s20, v66
	v_mul_f32_e32 v82, s20, v82
	v_mul_f32_e32 v246, v83, v135
	v_mul_f32_e32 v247, v67, v135
	v_fma_f32 v67, v67, v134, -v246
	v_fma_f32 v83, v83, v134, v247
	v_mul_f32_e32 v67, s20, v67
	v_mul_f32_e32 v83, s20, v83
	s_waitcnt vmcnt(16)
	v_mul_f32_e32 v246, v84, v137
	v_mul_f32_e32 v247, v68, v137
	v_fma_f32 v68, v68, v136, -v246
	v_fma_f32 v84, v84, v136, v247
	v_mul_f32_e32 v68, s20, v68
	v_mul_f32_e32 v84, s20, v84
	v_mul_f32_e32 v246, v85, v139
	v_mul_f32_e32 v247, v69, v139
	v_fma_f32 v69, v69, v138, -v246
	v_fma_f32 v85, v85, v138, v247
	v_mul_f32_e32 v69, s20, v69
	v_mul_f32_e32 v85, s20, v85
	v_mul_f32_e32 v246, v86, v141
	v_mul_f32_e32 v247, v70, v141
	v_fma_f32 v70, v70, v140, -v246
	v_fma_f32 v86, v86, v140, v247
	v_mul_f32_e32 v70, s20, v70
	v_mul_f32_e32 v86, s20, v86
	v_mul_f32_e32 v246, v87, v143
	v_mul_f32_e32 v247, v71, v143
	v_fma_f32 v71, v71, v142, -v246
	v_fma_f32 v87, v87, v142, v247
	v_mul_f32_e32 v71, s20, v71
	v_mul_f32_e32 v87, s20, v87
	s_waitcnt vmcnt(14)
; DI int crow(int r, int hf) { return (r & 3) + 8 * (r >> 2) + 4 * hf; }
; DI void rec_in_phase(const Params& p, int j, char* smem) {
;     ...
;         if (C64 < 1024) {
;           const int fi = ((C64 & 127) >> 1) + l32_, cbase = C64 & ~127;
;           const float sc = (C64 >= 512) ? RET_KSCALE : 1.f;
; #pragma unroll
;           for (int r = 0; r < 16; ++r) {
;             const int t = rb + crow(r, hf_), pos = t & (S_ - 1);
;             const float2 cs = rt128[pos * 64 + fi];
;             const float x1 = acc[i][0][r], x2 = acc[i][1][r];
;             zr[(size_t)t * LDZR + cbase + fi] = f2bf((x1 * cs.x - x2 * cs.y) * sc);
;             zr[(size_t)t * LDZR + cbase + 64 + fi] = f2bf((x2 * cs.x + x1 * cs.y) * sc);
;           }
	v_mul_f32_e32 v246, v88, v145
	v_mul_f32_e32 v247, v72, v145
	v_fma_f32 v72, v72, v144, -v246
	v_fma_f32 v88, v88, v144, v247
	v_mul_f32_e32 v72, s20, v72
	v_mul_f32_e32 v88, s20, v88
	v_mul_f32_e32 v246, v89, v147
	v_mul_f32_e32 v247, v73, v147
	v_fma_f32 v73, v73, v146, -v246
	v_fma_f32 v89, v89, v146, v247
	v_mul_f32_e32 v73, s20, v73
	v_mul_f32_e32 v89, s20, v89
	v_mul_f32_e32 v246, v90, v149
	v_mul_f32_e32 v247, v74, v149
	v_fma_f32 v74, v74, v148, -v246
	v_fma_f32 v90, v90, v148, v247
	v_mul_f32_e32 v74, s20, v74
	v_mul_f32_e32 v90, s20, v90
	v_mul_f32_e32 v246, v91, v151
	v_mul_f32_e32 v247, v75, v151
	v_fma_f32 v75, v75, v150, -v246
	v_fma_f32 v91, v91, v150, v247
	v_mul_f32_e32 v75, s20, v75
	v_mul_f32_e32 v91, s20, v91
	s_waitcnt vmcnt(12)
	v_mul_f32_e32 v246, v92, v153
	v_mul_f32_e32 v247, v76, v153
	v_fma_f32 v76, v76, v152, -v246
	v_fma_f32 v92, v92, v152, v247
	v_mul_f32_e32 v76, s20, v76
	v_mul_f32_e32 v92, s20, v92
	v_mul_f32_e32 v246, v93, v155
	v_mul_f32_e32 v247, v77, v155
	v_fma_f32 v77, v77, v154, -v246
	v_fma_f32 v93, v93, v154, v247
	v_mul_f32_e32 v77, s20, v77
	v_mul_f32_e32 v93, s20, v93
	v_mul_f32_e32 v246, v94, v157
	v_mul_f32_e32 v247, v78, v157
	v_fma_f32 v78, v78, v156, -v246
	v_fma_f32 v94, v94, v156, v247
	v_mul_f32_e32 v78, s20, v78
	v_mul_f32_e32 v94, s20, v94
	v_mul_f32_e32 v246, v95, v159
	v_mul_f32_e32 v247, v79, v159
	v_fma_f32 v79, v79, v158, -v246
	v_fma_f32 v95, v95, v158, v247
	v_mul_f32_e32 v79, s20, v79
	v_mul_f32_e32 v95, s20, v95
	v_cvt_pk_bf16_f32 v242, v64, v65
	v_cvt_pk_bf16_f32 v243, v66, v67
	ds_write_b64 v178, v[242:243]
	v_cvt_pk_bf16_f32 v244, v68, v69
	v_cvt_pk_bf16_f32 v245, v70, v71
	ds_write_b64 v179, v[244:245]
	v_cvt_pk_bf16_f32 v240, v72, v73
	v_cvt_pk_bf16_f32 v241, v74, v75
	ds_write_b64 v180, v[240:241]
	v_cvt_pk_bf16_f32 v242, v76, v77
	v_cvt_pk_bf16_f32 v243, v78, v79
	ds_write_b64 v181, v[242:243]
	v_cvt_pk_bf16_f32 v244, v80, v81
	v_cvt_pk_bf16_f32 v245, v82, v83
	ds_write_b64 v188, v[244:245]
	v_cvt_pk_bf16_f32 v240, v84, v85
	v_cvt_pk_bf16_f32 v241, v86, v87
	ds_write_b64 v189, v[240:241]
	v_cvt_pk_bf16_f32 v242, v88, v89
	v_cvt_pk_bf16_f32 v243, v90, v91
	ds_write_b64 v190, v[242:243]
	v_cvt_pk_bf16_f32 v244, v92, v93
	v_cvt_pk_bf16_f32 v245, v94, v95
	ds_write_b64 v191, v[244:245]
	ds_read_b128 v[64:67], v194
	ds_read_b128 v[68:71], v194 offset:1024
	ds_read_b128 v[72:75], v194 offset:2048
	ds_read_b128 v[76:79], v194 offset:3072
	s_waitcnt lgkmcnt(12)
	global_store_dwordx4 v196, v[32:35], s[38:39] nt
	s_add_u32 s38, s38, 0x8400
	s_addc_u32 s39, s39, 0
	global_store_dwordx4 v196, v[36:39], s[38:39] nt
	s_add_u32 s38, s38, 0x8400
	s_addc_u32 s39, s39, 0
	global_store_dwordx4 v196, v[40:43], s[38:39] nt
	s_add_u32 s38, s38, 0x8400
	s_addc_u32 s39, s39, 0
	global_store_dwordx4 v196, v[44:47], s[38:39] nt
	s_add_u32 s38, s38, 0x8400
	s_addc_u32 s39, s39, 0
	s_waitcnt vmcnt(14)
	v_mul_f32_e32 v246, v112, v163
	v_mul_f32_e32 v247, v96, v163
	v_fma_f32 v96, v96, v162, -v246
	v_fma_f32 v112, v112, v162, v247
	v_mul_f32_e32 v96, s20, v96
	v_mul_f32_e32 v112, s20, v112
	v_mul_f32_e32 v246, v113, v165
	v_mul_f32_e32 v247, v97, v165
	v_fma_f32 v97, v97, v164, -v246
	v_fma_f32 v113, v113, v164, v247
	v_mul_f32_e32 v97, s20, v97
	v_mul_f32_e32 v113, s20, v113
	v_mul_f32_e32 v246, v114, v167
	v_mul_f32_e32 v247, v98, v167
	v_fma_f32 v98, v98, v166, -v246
	v_fma_f32 v114, v114, v166, v247
	v_mul_f32_e32 v98, s20, v98
	v_mul_f32_e32 v114, s20, v114
	v_mul_f32_e32 v246, v115, v169
	v_mul_f32_e32 v247, v99, v169
	v_fma_f32 v99, v99, v168, -v246
	v_fma_f32 v115, v115, v168, v247
	v_mul_f32_e32 v99, s20, v99
	v_mul_f32_e32 v115, s20, v115
	s_waitcnt vmcnt(12)
	v_mul_f32_e32 v246, v116, v171
	v_mul_f32_e32 v247, v100, v171
	v_fma_f32 v100, v100, v170, -v246
	v_fma_f32 v116, v116, v170, v247
	v_mul_f32_e32 v100, s20, v100
	v_mul_f32_e32 v116, s20, v116
	v_mul_f32_e32 v246, v117, v173
	v_mul_f32_e32 v247, v101, v173
	v_fma_f32 v101, v101, v172, -v246
	v_fma_f32 v117, v117, v172, v247
	v_mul_f32_e32 v101, s20, v101
	v_mul_f32_e32 v117, s20, v117
	v_mul_f32_e32 v246, v118, v175
	v_mul_f32_e32 v247, v102, v175
	v_fma_f32 v102, v102, v174, -v246
	v_fma_f32 v118, v118, v174, v247
	v_mul_f32_e32 v102, s20, v102
	v_mul_f32_e32 v118, s20, v118
	v_mul_f32_e32 v246, v119, v177
	v_mul_f32_e32 v247, v103, v177
	v_fma_f32 v103, v103, v176, -v246
	v_fma_f32 v119, v119, v176, v247
	v_mul_f32_e32 v103, s20, v103
	v_mul_f32_e32 v119, s20, v119
	s_waitcnt vmcnt(10)
; DI int crow(int r, int hf) { return (r & 3) + 8 * (r >> 2) + 4 * hf; }
; DI void rec_in_phase(const Params& p, int j, char* smem) {
;     ...
;         if (C64 < 1024) {
;           const int fi = ((C64 & 127) >> 1) + l32_, cbase = C64 & ~127;
;           const float sc = (C64 >= 512) ? RET_KSCALE : 1.f;
; #pragma unroll
;           for (int r = 0; r < 16; ++r) {
;             const int t = rb + crow(r, hf_), pos = t & (S_ - 1);
;             const float2 cs = rt128[pos * 64 + fi];
;             const float x1 = acc[i][0][r], x2 = acc[i][1][r];
;             zr[(size_t)t * LDZR + cbase + fi] = f2bf((x1 * cs.x - x2 * cs.y) * sc);
;             zr[(size_t)t * LDZR + cbase + 64 + fi] = f2bf((x2 * cs.x + x1 * cs.y) * sc);
;           }
	v_mul_f32_e32 v246, v120, v225
	v_mul_f32_e32 v247, v104, v225
	v_fma_f32 v104, v104, v224, -v246
	v_fma_f32 v120, v120, v224, v247
	v_mul_f32_e32 v104, s20, v104
	v_mul_f32_e32 v120, s20, v120
	v_mul_f32_e32 v246, v121, v227
	v_mul_f32_e32 v247, v105, v227
	v_fma_f32 v105, v105, v226, -v246
	v_fma_f32 v121, v121, v226, v247
	v_mul_f32_e32 v105, s20, v105
	v_mul_f32_e32 v121, s20, v121
	v_mul_f32_e32 v246, v122, v229
	v_mul_f32_e32 v247, v106, v229
	v_fma_f32 v106, v106, v228, -v246
	v_fma_f32 v122, v122, v228, v247
	v_mul_f32_e32 v106, s20, v106
	v_mul_f32_e32 v122, s20, v122
	v_mul_f32_e32 v246, v123, v231
	v_mul_f32_e32 v247, v107, v231
	v_fma_f32 v107, v107, v230, -v246
	v_fma_f32 v123, v123, v230, v247
	v_mul_f32_e32 v107, s20, v107
	v_mul_f32_e32 v123, s20, v123
	s_waitcnt vmcnt(8)
	v_mul_f32_e32 v246, v124, v233
	v_mul_f32_e32 v247, v108, v233
	v_fma_f32 v108, v108, v232, -v246
	v_fma_f32 v124, v124, v232, v247
	v_mul_f32_e32 v108, s20, v108
	v_mul_f32_e32 v124, s20, v124
	v_mul_f32_e32 v246, v125, v235
	v_mul_f32_e32 v247, v109, v235
	v_fma_f32 v109, v109, v234, -v246
	v_fma_f32 v125, v125, v234, v247
	v_mul_f32_e32 v109, s20, v109
	v_mul_f32_e32 v125, s20, v125
	v_mul_f32_e32 v246, v126, v237
	v_mul_f32_e32 v247, v110, v237
	v_fma_f32 v110, v110, v236, -v246
	v_fma_f32 v126, v126, v236, v247
	v_mul_f32_e32 v110, s20, v110
	v_mul_f32_e32 v126, s20, v126
	v_mul_f32_e32 v246, v127, v239
	v_mul_f32_e32 v247, v111, v239
	v_fma_f32 v111, v111, v238, -v246
	v_fma_f32 v127, v127, v238, v247
	v_mul_f32_e32 v111, s20, v111
	v_mul_f32_e32 v127, s20, v127
	v_cvt_pk_bf16_f32 v240, v96, v97
	v_cvt_pk_bf16_f32 v241, v98, v99
	ds_write_b64 v178, v[240:241]
	v_cvt_pk_bf16_f32 v242, v100, v101
	v_cvt_pk_bf16_f32 v243, v102, v103
	ds_write_b64 v179, v[242:243]
	v_cvt_pk_bf16_f32 v244, v104, v105
	v_cvt_pk_bf16_f32 v245, v106, v107
	ds_write_b64 v180, v[244:245]
	v_cvt_pk_bf16_f32 v240, v108, v109
	v_cvt_pk_bf16_f32 v241, v110, v111
	ds_write_b64 v181, v[240:241]
	v_cvt_pk_bf16_f32 v242, v112, v113
	v_cvt_pk_bf16_f32 v243, v114, v115
	ds_write_b64 v188, v[242:243]
	v_cvt_pk_bf16_f32 v244, v116, v117
	v_cvt_pk_bf16_f32 v245, v118, v119
	ds_write_b64 v189, v[244:245]
	v_cvt_pk_bf16_f32 v240, v120, v121
	v_cvt_pk_bf16_f32 v241, v122, v123
	ds_write_b64 v190, v[240:241]
	v_cvt_pk_bf16_f32 v242, v124, v125
	v_cvt_pk_bf16_f32 v243, v126, v127
	ds_write_b64 v191, v[242:243]
	ds_read_b128 v[96:99], v194
	ds_read_b128 v[100:103], v194 offset:1024
	ds_read_b128 v[104:107], v194 offset:2048
	ds_read_b128 v[108:111], v194 offset:3072
	s_waitcnt lgkmcnt(12)
	global_store_dwordx4 v196, v[64:67], s[38:39] nt
	s_add_u32 s38, s38, 0x8400
	s_addc_u32 s39, s39, 0
	global_store_dwordx4 v196, v[68:71], s[38:39] nt
	s_add_u32 s38, s38, 0x8400
	s_addc_u32 s39, s39, 0
	global_store_dwordx4 v196, v[72:75], s[38:39] nt
	s_add_u32 s38, s38, 0x8400
	s_addc_u32 s39, s39, 0
	global_store_dwordx4 v196, v[76:79], s[38:39] nt
	s_add_u32 s38, s38, 0x8400
	s_addc_u32 s39, s39, 0
	s_waitcnt lgkmcnt(0)
	global_store_dwordx4 v196, v[96:99], s[38:39] nt
	s_add_u32 s38, s38, 0x8400
	s_addc_u32 s39, s39, 0
	global_store_dwordx4 v196, v[100:103], s[38:39] nt
	s_add_u32 s38, s38, 0x8400
	s_addc_u32 s39, s39, 0
	global_store_dwordx4 v196, v[104:107], s[38:39] nt
	s_add_u32 s38, s38, 0x8400
	s_addc_u32 s39, s39, 0
	global_store_dwordx4 v196, v[108:111], s[38:39] nt
.Lri_epi_done:
	s_waitcnt lgkmcnt(0)
	s_add_u32 m0, s14, 0x18000
	s_nop 0
	global_load_lds_dwordx4 v220, s[24:25]
	s_add_u32 m0, s14, 0x18400
	s_nop 0
	global_load_lds_dwordx4 v221, s[24:25]
	s_add_u32 m0, s14, 0x18800
	s_nop 0
	global_load_lds_dwordx4 v222, s[24:25]
	s_add_u32 m0, s14, 0x18c00
	s_nop 0
	global_load_lds_dwordx4 v223, s[24:25]
	s_add_u32 s22, s22, 0x80
	s_addc_u32 s23, s23, 0
	s_add_u32 s24, s24, 0x80
	s_addc_u32 s25, s25, 0
	s_add_u32 s26, s26, 1
	s_cmp_eq_u32 s26, 16
	s_cbranch_scc0 .Lri8_cadv_done
	s_mov_b32 s26, 0
	s_add_u32 s27, s27, s30
	s_cmp_lt_u32 s27, 0xa0
	s_cbranch_scc1 .Lri8_cadv_new
	s_sub_u32 s22, s22, 0x800
	s_subb_u32 s23, s23, 0
	s_sub_u32 s24, s24, 0x800
	s_subb_u32 s25, s25, 0
	s_branch .Lri8_cadv_done

; DI void rec_in_phase(const Params& p, int j, char* smem) {
;     ...
;   for (int lt = blockIdx.x >> 3; lt < 16 * nN; lt += gridDim.x >> 3) {
;     int mt, nt; tile_map(lt, 16, nN, 16, 2, mt, nt);
;     const int m0 = mt * 256, n0 = nt * 256;
;     gemm_tile(A + (size_t)m0 * LDH, LDH, 16, nullptr, 0, 0, Wt + (size_t)n0 * LDW1, LDW1, smem, [&](f32x16(&acc)[2][2], int moff) {
.Lri8_cadv_done:
	ds_read_b128 v[128:131], v204
	ds_read_b128 v[132:135], v204 offset:4096
	ds_read_b128 v[136:139], v204 offset:8192
	ds_read_b128 v[140:143], v204 offset:12288
	ds_read_b128 v[162:165], v212
	ds_read_b128 v[166:169], v212 offset:4096
	ds_read_b128 v[144:147], v205
	ds_read_b128 v[148:151], v205 offset:4096
	ds_read_b128 v[152:155], v205 offset:8192
	ds_read_b128 v[156:159], v205 offset:12288
	ds_read_b128 v[170:173], v213
	ds_read_b128 v[174:177], v213 offset:4096
	s_add_u32 s28, s28, s30
	s_cmp_lt_u32 s28, 0xa0
	s_cbranch_scc1 .Lri_tile
	s_waitcnt vmcnt(0) lgkmcnt(0)
